# strategy 7 (fewer loader instructions): on top of v36, six m0 wait-state s_nops replaced by reordering an independent SALU instruction between the m0 write and the DMA
# baseline (speedup 1.0000x reference)
; #define PG8_STAGE(bufoff, gbase) do { _Pragma("unroll") for (int _i = 0; _i < 2; ++_i) \
;         __builtin_amdgcn_global_load_lds((const unsigned*)((const char*)(gbase) + voff[_i]), (LAS unsigned*)(lds + (bufoff) + ldsw + _i * 8192), 16, 0, 0); } while (0)
; #define PG8_LDA(dst, b, h) do { _Pragma("unroll") for (int m = 0; m < 4; ++m) _Pragma("unroll") for (int k = 0; k < 2; ++k) dst[m][k] = *(const LAS bf16x8*)(lds + PG8_SA(b, h) + aoff + m * 2048 + k * 1024); } while (0)
; #define PG8_LDB(dst, b, h) do { _Pragma("unroll") for (int n = 0; n < 2; ++n) _Pragma("unroll") for (int k = 0; k < 2; ++k) dst[n][k] = *(const LAS bf16x8*)(lds + PG8_SB(b, h) + boff + n * 2048 + k * 1024); } while (0)
; #define PG8_MMA(ai, bj, At, Bt) do { __builtin_amdgcn_s_setprio(1); _Pragma("unroll") for (int m = 0; m < 4; ++m) _Pragma("unroll") for (int n = 0; n < 2; ++n) _Pragma("unroll") for (int k = 0; k < 2; ++k) \
;         acc[ai][bj][m][n] = __builtin_amdgcn_mfma_f32_16x16x32_bf16(Bt[n][k], At[m][k], acc[ai][bj][m][n], 0, 0, 0); __builtin_amdgcn_s_setprio(0); } while (0)
; #define PG8_WAIT_V(n) asm volatile("s_waitcnt vmcnt(" #n ")" ::: "memory")
; #define PG8_WAIT_L(n) asm volatile("s_waitcnt lgkmcnt(" #n ")" ::: "memory")
; #define PG8_BAR __builtin_amdgcn_s_barrier()
; #define PG8_SCHED __builtin_amdgcn_sched_barrier(0)
; template <class Epi>
; DI void gemm_phase(LAS unsigned char* lds, const Gemm g, const StaticOrder& S, const Epi& E) {
;     ...
;             PG8_LDB(B0, 0, 0); PG8_SCHED; PG8_LDA(At, 0, 0); PG8_STAGE(PG8_SA(1, 1), a1 + hstep);
;             PG8_WAIT_L(8); PG8_BAR; PG8_WAIT_L(0); PG8_MMA(0, 0, At, B0); PG8_BAR; PG8_SCHED;
;             PG8_LDB(B1, 0, 1); PG8_STAGE(PG8_SB(0, 0), b2);
;             PG8_BAR; PG8_WAIT_L(0); PG8_MMA(0, 1, At, B1); PG8_BAR;
;             PG8_LDA(At, 0, 1); PG8_STAGE(PG8_SA(0, 0), a2);
;             PG8_BAR; PG8_WAIT_L(0); PG8_MMA(1, 0, At, B0); PG8_BAR; PG8_SCHED;
;             PG8_STAGE(PG8_SB(0, 1), b2 + hstep);
;             PG8_WAIT_V(6); PG8_BAR; PG8_MMA(1, 1, At, B1); PG8_BAR;
.LBB0_37:
	ds_read_b128 v[138:141], v135
	ds_read_b128 v[142:145], v135 offset:1024
	ds_read_b128 v[146:149], v135 offset:2048
	ds_read_b128 v[150:153], v135 offset:3072
	ds_read_b128 v[186:189], v137
	ds_read_b128 v[190:193], v137 offset:1024
	ds_read_b128 v[194:197], v137 offset:2048
	ds_read_b128 v[198:201], v137 offset:3072
	ds_read_b128 v[202:205], v137 offset:4096
	ds_read_b128 v[206:209], v137 offset:5120
	ds_read_b128 v[210:213], v137 offset:6144
	ds_read_b128 v[214:217], v137 offset:7168
	s_add_u32 s20, s18, 0xfff80080
	s_addc_u32 s21, s19, -1
	s_add_i32 s39, 0, 0x10000
	s_cmp_eq_u32 s38, 28
	s_cselect_b32 s23, s4, s21
	s_cselect_b32 s22, s5, s20
	s_cselect_b32 s21, s9, s37
	s_cselect_b32 s20, s11, s33
	s_add_i32 m0, s28, 0xc000
	s_nop 0
	global_load_lds_dwordx4 v130, s[18:19]
	s_add_i32 m0, s28, 0xe000
	s_nop 0
	global_load_lds_dwordx4 v132, s[18:19]
	s_waitcnt lgkmcnt(8)
	s_setprio 1
	s_barrier
	s_waitcnt lgkmcnt(0)
	v_mfma_f32_16x16x32_bf16 v[124:127], v[138:141], v[186:189], v[124:127]
	v_mfma_f32_16x16x32_bf16 v[120:123], v[146:149], v[186:189], v[120:123]
	v_mfma_f32_16x16x32_bf16 v[108:111], v[138:141], v[194:197], v[108:111]
	v_mfma_f32_16x16x32_bf16 v[104:107], v[146:149], v[194:197], v[104:107]
	v_mfma_f32_16x16x32_bf16 v[92:95], v[138:141], v[202:205], v[92:95]
	v_mfma_f32_16x16x32_bf16 v[88:91], v[146:149], v[202:205], v[88:91]
	v_mfma_f32_16x16x32_bf16 v[76:79], v[138:141], v[210:213], v[76:79]
	v_mfma_f32_16x16x32_bf16 v[72:75], v[146:149], v[210:213], v[72:75]
	v_mfma_f32_16x16x32_bf16 v[124:127], v[142:145], v[190:193], v[124:127]
	v_mfma_f32_16x16x32_bf16 v[120:123], v[150:153], v[190:193], v[120:123]
	v_mfma_f32_16x16x32_bf16 v[108:111], v[142:145], v[198:201], v[108:111]
	v_mfma_f32_16x16x32_bf16 v[104:107], v[150:153], v[198:201], v[104:107]
	v_mfma_f32_16x16x32_bf16 v[92:95], v[142:145], v[206:209], v[92:95]
	v_mfma_f32_16x16x32_bf16 v[88:91], v[150:153], v[206:209], v[88:91]
	v_mfma_f32_16x16x32_bf16 v[76:79], v[142:145], v[214:217], v[76:79]
	s_setprio 0
	v_mfma_f32_16x16x32_bf16 v[72:75], v[150:153], v[214:217], v[72:75]
	s_barrier
	ds_read_b128 v[226:229], v135 offset:16384
	ds_read_b128 v[230:233], v135 offset:17408
	ds_read_b128 v[234:237], v135 offset:18432
	ds_read_b128 v[238:241], v135 offset:19456
	s_add_i32 s42, 0, 0x14000
	s_add_i32 s39, s39, s27
	s_mov_b32 m0, s39
	s_nop 0
	global_load_lds_dwordx4 v158, s[20:21]
	s_add_i32 m0, s39, 0x2000
	s_nop 0
	global_load_lds_dwordx4 v128, s[20:21]
	s_waitcnt lgkmcnt(0)
	s_setprio 1
	s_barrier
	v_mfma_f32_16x16x32_bf16 v[116:119], v[226:229], v[186:189], v[116:119]
	v_mfma_f32_16x16x32_bf16 v[112:115], v[234:237], v[186:189], v[112:115]
	v_mfma_f32_16x16x32_bf16 v[100:103], v[226:229], v[194:197], v[100:103]
	v_mfma_f32_16x16x32_bf16 v[96:99], v[234:237], v[194:197], v[96:99]
	v_mfma_f32_16x16x32_bf16 v[84:87], v[226:229], v[202:205], v[84:87]
	v_mfma_f32_16x16x32_bf16 v[80:83], v[234:237], v[202:205], v[80:83]
	v_mfma_f32_16x16x32_bf16 v[68:71], v[226:229], v[210:213], v[68:71]
	v_mfma_f32_16x16x32_bf16 v[64:67], v[234:237], v[210:213], v[64:67]
	v_mfma_f32_16x16x32_bf16 v[116:119], v[230:233], v[190:193], v[116:119]
	v_mfma_f32_16x16x32_bf16 v[112:115], v[238:241], v[190:193], v[112:115]
	v_mfma_f32_16x16x32_bf16 v[100:103], v[230:233], v[198:201], v[100:103]
	v_mfma_f32_16x16x32_bf16 v[96:99], v[238:241], v[198:201], v[96:99]
	v_mfma_f32_16x16x32_bf16 v[84:87], v[230:233], v[206:209], v[84:87]
	v_mfma_f32_16x16x32_bf16 v[80:83], v[238:241], v[206:209], v[80:83]
	v_mfma_f32_16x16x32_bf16 v[68:71], v[230:233], v[214:217], v[68:71]
	s_setprio 0
	v_mfma_f32_16x16x32_bf16 v[64:67], v[238:241], v[214:217], v[64:67]
	s_barrier
	ds_read_b128 v[186:189], v137 offset:16384
	ds_read_b128 v[190:193], v137 offset:17408
	ds_read_b128 v[194:197], v137 offset:18432
	ds_read_b128 v[198:201], v137 offset:19456
	ds_read_b128 v[202:205], v137 offset:20480
	ds_read_b128 v[206:209], v137 offset:21504
	ds_read_b128 v[210:213], v137 offset:22528
	ds_read_b128 v[214:217], v137 offset:23552
	s_mov_b32 m0, s28
	s_nop 0
	global_load_lds_dwordx4 v158, s[22:23]
	s_mov_b32 m0, s29
	s_mov_b64 s[100:101], s[22:23]
	global_load_lds_dwordx4 v128, s[22:23]
	s_waitcnt lgkmcnt(0)
	s_setprio 1
	s_barrier
	v_mfma_f32_16x16x32_bf16 v[60:63], v[138:141], v[186:189], v[60:63]
	v_mfma_f32_16x16x32_bf16 v[56:59], v[146:149], v[186:189], v[56:59]
	v_mfma_f32_16x16x32_bf16 v[44:47], v[138:141], v[194:197], v[44:47]
	v_mfma_f32_16x16x32_bf16 v[40:43], v[146:149], v[194:197], v[40:43]
	v_mfma_f32_16x16x32_bf16 v[28:31], v[138:141], v[202:205], v[28:31]
	v_mfma_f32_16x16x32_bf16 v[24:27], v[146:149], v[202:205], v[24:27]
	v_mfma_f32_16x16x32_bf16 v[12:15], v[138:141], v[210:213], v[12:15]
	v_mfma_f32_16x16x32_bf16 v[8:11], v[146:149], v[210:213], v[8:11]
	v_mfma_f32_16x16x32_bf16 v[60:63], v[142:145], v[190:193], v[60:63]
	v_mfma_f32_16x16x32_bf16 v[56:59], v[150:153], v[190:193], v[56:59]
	v_mfma_f32_16x16x32_bf16 v[44:47], v[142:145], v[198:201], v[44:47]
	v_mfma_f32_16x16x32_bf16 v[40:43], v[150:153], v[198:201], v[40:43]
	v_mfma_f32_16x16x32_bf16 v[28:31], v[142:145], v[206:209], v[28:31]
	v_mfma_f32_16x16x32_bf16 v[24:27], v[150:153], v[206:209], v[24:27]
	v_mfma_f32_16x16x32_bf16 v[12:15], v[142:145], v[214:217], v[12:15]
	s_setprio 0
	v_mfma_f32_16x16x32_bf16 v[8:11], v[150:153], v[214:217], v[8:11]
	s_barrier
	s_add_u32 s40, s20, 0x80000
	s_addc_u32 s41, s21, 0
	s_add_i32 s39, s42, s27
	s_mov_b32 m0, s39
	s_nop 0
	global_load_lds_dwordx4 v158, s[40:41]
	s_add_i32 m0, s39, 0x2000
	s_nop 0
	global_load_lds_dwordx4 v128, s[40:41]
	s_waitcnt vmcnt(6)
	s_setprio 1
	s_barrier
; #define PG8_STAGE(bufoff, gbase) do { _Pragma("unroll") for (int _i = 0; _i < 2; ++_i) \
;         __builtin_amdgcn_global_load_lds((const unsigned*)((const char*)(gbase) + voff[_i]), (LAS unsigned*)(lds + (bufoff) + ldsw + _i * 8192), 16, 0, 0); } while (0)
; #define PG8_LDA(dst, b, h) do { _Pragma("unroll") for (int m = 0; m < 4; ++m) _Pragma("unroll") for (int k = 0; k < 2; ++k) dst[m][k] = *(const LAS bf16x8*)(lds + PG8_SA(b, h) + aoff + m * 2048 + k * 1024); } while (0)
; #define PG8_LDB(dst, b, h) do { _Pragma("unroll") for (int n = 0; n < 2; ++n) _Pragma("unroll") for (int k = 0; k < 2; ++k) dst[n][k] = *(const LAS bf16x8*)(lds + PG8_SB(b, h) + boff + n * 2048 + k * 1024); } while (0)
; #define PG8_MMA(ai, bj, At, Bt) do { __builtin_amdgcn_s_setprio(1); _Pragma("unroll") for (int m = 0; m < 4; ++m) _Pragma("unroll") for (int n = 0; n < 2; ++n) _Pragma("unroll") for (int k = 0; k < 2; ++k) \
;         acc[ai][bj][m][n] = __builtin_amdgcn_mfma_f32_16x16x32_bf16(Bt[n][k], At[m][k], acc[ai][bj][m][n], 0, 0, 0); __builtin_amdgcn_s_setprio(0); } while (0)
; #define PG8_WAIT_V(n) asm volatile("s_waitcnt vmcnt(" #n ")" ::: "memory")
; #define PG8_WAIT_L(n) asm volatile("s_waitcnt lgkmcnt(" #n ")" ::: "memory")
; #define PG8_BAR __builtin_amdgcn_s_barrier()
; #define PG8_SCHED __builtin_amdgcn_sched_barrier(0)
; template <class Epi>
; DI void gemm_phase(LAS unsigned char* lds, const Gemm g, const StaticOrder& S, const Epi& E) {
;     ...
;             PG8_WAIT_V(6); PG8_BAR; PG8_MMA(1, 1, At, B1); PG8_BAR;
;             PG8_LDB(B0, 1, 0); PG8_SCHED; PG8_LDA(At, 1, 0); PG8_STAGE(PG8_SA(0, 1), a2 + hstep);
;             PG8_WAIT_L(8); PG8_BAR; PG8_WAIT_L(0); PG8_MMA(0, 0, At, B0); PG8_BAR; PG8_SCHED;
;             PG8_LDB(B1, 1, 1); PG8_STAGE(PG8_SB(1, 0), b3);
;             PG8_BAR; PG8_WAIT_L(0); PG8_MMA(0, 1, At, B1); PG8_BAR;
;             PG8_LDA(At, 1, 1); PG8_STAGE(PG8_SA(1, 0), a3);
;             PG8_BAR; PG8_WAIT_L(0); PG8_MMA(1, 0, At, B0); PG8_BAR; PG8_SCHED;
	v_mfma_f32_16x16x32_bf16 v[52:55], v[226:229], v[186:189], v[52:55]
	v_mfma_f32_16x16x32_bf16 v[48:51], v[234:237], v[186:189], v[48:51]
	v_mfma_f32_16x16x32_bf16 v[36:39], v[226:229], v[194:197], v[36:39]
	v_mfma_f32_16x16x32_bf16 v[32:35], v[234:237], v[194:197], v[32:35]
	v_mfma_f32_16x16x32_bf16 v[20:23], v[226:229], v[202:205], v[20:23]
	v_mfma_f32_16x16x32_bf16 v[16:19], v[234:237], v[202:205], v[16:19]
	v_mfma_f32_16x16x32_bf16 v[4:7], v[226:229], v[210:213], v[4:7]
	v_mfma_f32_16x16x32_bf16 v[0:3], v[234:237], v[210:213], v[0:3]
	v_mfma_f32_16x16x32_bf16 v[52:55], v[230:233], v[190:193], v[52:55]
	v_mfma_f32_16x16x32_bf16 v[48:51], v[238:241], v[190:193], v[48:51]
	v_mfma_f32_16x16x32_bf16 v[36:39], v[230:233], v[198:201], v[36:39]
	v_mfma_f32_16x16x32_bf16 v[32:35], v[238:241], v[198:201], v[32:35]
	v_mfma_f32_16x16x32_bf16 v[20:23], v[230:233], v[206:209], v[20:23]
	v_mfma_f32_16x16x32_bf16 v[16:19], v[238:241], v[206:209], v[16:19]
	v_mfma_f32_16x16x32_bf16 v[4:7], v[230:233], v[214:217], v[4:7]
	s_setprio 0
	v_mfma_f32_16x16x32_bf16 v[0:3], v[238:241], v[214:217], v[0:3]
	s_barrier
	ds_read_b128 v[138:141], v135 offset:32768
	ds_read_b128 v[142:145], v135 offset:33792
	ds_read_b128 v[146:149], v135 offset:34816
	ds_read_b128 v[150:153], v135 offset:35840
	ds_read_b128 v[186:189], v137 offset:32768
	ds_read_b128 v[190:193], v137 offset:33792
	ds_read_b128 v[194:197], v137 offset:34816
	ds_read_b128 v[198:201], v137 offset:35840
	ds_read_b128 v[202:205], v137 offset:36864
	ds_read_b128 v[206:209], v137 offset:37888
	ds_read_b128 v[210:213], v137 offset:38912
	ds_read_b128 v[214:217], v137 offset:39936
	s_add_i32 s39, 0, 0x18000
	s_add_u32 s22, s22, 0x80000
	s_addc_u32 s23, s23, 0
	s_mov_b32 m0, s30
	s_nop 0
	global_load_lds_dwordx4 v158, s[22:23]
	s_mov_b32 m0, s31
	s_nop 0
	global_load_lds_dwordx4 v128, s[22:23]
	s_waitcnt lgkmcnt(8)
	s_setprio 1
	s_barrier
	s_waitcnt lgkmcnt(0)
	v_mfma_f32_16x16x32_bf16 v[124:127], v[138:141], v[186:189], v[124:127]
	v_mfma_f32_16x16x32_bf16 v[120:123], v[146:149], v[186:189], v[120:123]
	v_mfma_f32_16x16x32_bf16 v[108:111], v[138:141], v[194:197], v[108:111]
	v_mfma_f32_16x16x32_bf16 v[104:107], v[146:149], v[194:197], v[104:107]
	v_mfma_f32_16x16x32_bf16 v[92:95], v[138:141], v[202:205], v[92:95]
	v_mfma_f32_16x16x32_bf16 v[88:91], v[146:149], v[202:205], v[88:91]
	v_mfma_f32_16x16x32_bf16 v[76:79], v[138:141], v[210:213], v[76:79]
	v_mfma_f32_16x16x32_bf16 v[72:75], v[146:149], v[210:213], v[72:75]
	v_mfma_f32_16x16x32_bf16 v[124:127], v[142:145], v[190:193], v[124:127]
	v_mfma_f32_16x16x32_bf16 v[120:123], v[150:153], v[190:193], v[120:123]
	v_mfma_f32_16x16x32_bf16 v[108:111], v[142:145], v[198:201], v[108:111]
	v_mfma_f32_16x16x32_bf16 v[104:107], v[150:153], v[198:201], v[104:107]
	v_mfma_f32_16x16x32_bf16 v[92:95], v[142:145], v[206:209], v[92:95]
	v_mfma_f32_16x16x32_bf16 v[88:91], v[150:153], v[206:209], v[88:91]
	v_mfma_f32_16x16x32_bf16 v[76:79], v[142:145], v[214:217], v[76:79]
	s_setprio 0
	v_mfma_f32_16x16x32_bf16 v[72:75], v[150:153], v[214:217], v[72:75]
	s_barrier
	ds_read_b128 v[226:229], v135 offset:49152
	ds_read_b128 v[230:233], v135 offset:50176
	ds_read_b128 v[234:237], v135 offset:51200
	ds_read_b128 v[238:241], v135 offset:52224
	s_add_i32 s22, 0, 0x1c000
	s_add_i32 s23, s39, s27
	s_add_i32 m0, s23, 0xffffff80
	s_nop 0
	global_load_lds_dwordx4 v158, s[20:21] offset:128
	s_add_i32 m0, s23, 0x1f80
	s_nop 0
	global_load_lds_dwordx4 v128, s[20:21] offset:128
	s_waitcnt lgkmcnt(0)
	s_setprio 1
	s_barrier
	v_mfma_f32_16x16x32_bf16 v[116:119], v[226:229], v[186:189], v[116:119]
	v_mfma_f32_16x16x32_bf16 v[112:115], v[234:237], v[186:189], v[112:115]
	v_mfma_f32_16x16x32_bf16 v[100:103], v[226:229], v[194:197], v[100:103]
	v_mfma_f32_16x16x32_bf16 v[96:99], v[234:237], v[194:197], v[96:99]
	v_mfma_f32_16x16x32_bf16 v[84:87], v[226:229], v[202:205], v[84:87]
	v_mfma_f32_16x16x32_bf16 v[80:83], v[234:237], v[202:205], v[80:83]
	v_mfma_f32_16x16x32_bf16 v[68:71], v[226:229], v[210:213], v[68:71]
	v_mfma_f32_16x16x32_bf16 v[64:67], v[234:237], v[210:213], v[64:67]
	v_mfma_f32_16x16x32_bf16 v[116:119], v[230:233], v[190:193], v[116:119]
	v_mfma_f32_16x16x32_bf16 v[112:115], v[238:241], v[190:193], v[112:115]
	v_mfma_f32_16x16x32_bf16 v[100:103], v[230:233], v[198:201], v[100:103]
	v_mfma_f32_16x16x32_bf16 v[96:99], v[238:241], v[198:201], v[96:99]
	v_mfma_f32_16x16x32_bf16 v[84:87], v[230:233], v[206:209], v[84:87]
	v_mfma_f32_16x16x32_bf16 v[80:83], v[238:241], v[206:209], v[80:83]
	v_mfma_f32_16x16x32_bf16 v[68:71], v[230:233], v[214:217], v[68:71]
	s_setprio 0
	v_mfma_f32_16x16x32_bf16 v[64:67], v[238:241], v[214:217], v[64:67]
	s_barrier
	ds_read_b128 v[186:189], v137 offset:49152
	ds_read_b128 v[190:193], v137 offset:50176
	ds_read_b128 v[194:197], v137 offset:51200
	ds_read_b128 v[198:201], v137 offset:52224
	ds_read_b128 v[202:205], v137 offset:53248
	ds_read_b128 v[206:209], v137 offset:54272
	ds_read_b128 v[210:213], v137 offset:55296
	ds_read_b128 v[214:217], v137 offset:56320
	s_add_i32 m0, s34, 0xffffff80
	s_nop 0
	global_load_lds_dwordx4 v158, s[100:101] offset:128
	s_add_i32 m0, s35, 0xffffff80
	s_nop 0
	global_load_lds_dwordx4 v128, s[100:101] offset:128
	s_waitcnt lgkmcnt(0)
	s_setprio 1
	s_barrier
; #define PG8_STAGE(bufoff, gbase) do { _Pragma("unroll") for (int _i = 0; _i < 2; ++_i) \
;         __builtin_amdgcn_global_load_lds((const unsigned*)((const char*)(gbase) + voff[_i]), (LAS unsigned*)(lds + (bufoff) + ldsw + _i * 8192), 16, 0, 0); } while (0)
; #define PG8_MMA(ai, bj, At, Bt) do { __builtin_amdgcn_s_setprio(1); _Pragma("unroll") for (int m = 0; m < 4; ++m) _Pragma("unroll") for (int n = 0; n < 2; ++n) _Pragma("unroll") for (int k = 0; k < 2; ++k) \
;         acc[ai][bj][m][n] = __builtin_amdgcn_mfma_f32_16x16x32_bf16(Bt[n][k], At[m][k], acc[ai][bj][m][n], 0, 0, 0); __builtin_amdgcn_s_setprio(0); } while (0)
; #define PG8_WAIT_V(n) asm volatile("s_waitcnt vmcnt(" #n ")" ::: "memory")
; #define PG8_WAIT_L(n) asm volatile("s_waitcnt lgkmcnt(" #n ")" ::: "memory")
; #define PG8_BAR __builtin_amdgcn_s_barrier()
; #define PG8_SCHED __builtin_amdgcn_sched_barrier(0)
; template <class Epi>
; DI void gemm_phase(LAS unsigned char* lds, const Gemm g, const StaticOrder& S, const Epi& E) {
;     ...
;             PG8_BAR; PG8_WAIT_L(0); PG8_MMA(1, 0, At, B0); PG8_BAR; PG8_SCHED;
;             PG8_STAGE(PG8_SB(1, 1), b3 + hstep);
;             PG8_WAIT_V(6); PG8_BAR; PG8_MMA(1, 1, At, B1); PG8_BAR;
;     DI void operator()(const f32x4 (&acc)[2][2][4][2], const Unit& u, int wr, int wc, int fr, int fq) const {
;         const int row0 = u.pm * BM + wr * 64 + fr, col0 = u.pn * HALF + wc * 32 + 8 * fq;
; #pragma unroll
;         for (int ai = 0; ai < 2; ++ai)
; #pragma unroll
;             for (int m = 0; m < 4; ++m) { float hv[8];
; #pragma unroll
;                 for (int n = 0; n < 2; ++n)
; #pragma unroll
;                     for (int e = 0; e < 4; ++e) { const float gt = acc[ai][0][m][n][e], up = acc[ai][1][m][n][e];
;                         hv[n * 4 + e] = gt * __builtin_amdgcn_rcpf(1.f + __builtin_amdgcn_exp2f(-1.4426950408889634f * gt)) * up; }
;                 *(u32x4*)(H + (size_t)(row0 + ai * HALF + m * 16) * DFF + col0) = (u32x4){pk(hv[0], hv[1]), pk(hv[2], hv[3]), pk(hv[4], hv[5]), pk(hv[6], hv[7])}; }
	v_mfma_f32_16x16x32_bf16 v[60:63], v[138:141], v[186:189], v[60:63]
	v_mfma_f32_16x16x32_bf16 v[56:59], v[146:149], v[186:189], v[56:59]
	v_mfma_f32_16x16x32_bf16 v[44:47], v[138:141], v[194:197], v[44:47]
	v_mfma_f32_16x16x32_bf16 v[40:43], v[146:149], v[194:197], v[40:43]
	v_mfma_f32_16x16x32_bf16 v[28:31], v[138:141], v[202:205], v[28:31]
	v_mfma_f32_16x16x32_bf16 v[24:27], v[146:149], v[202:205], v[24:27]
	v_mfma_f32_16x16x32_bf16 v[12:15], v[138:141], v[210:213], v[12:15]
	v_mfma_f32_16x16x32_bf16 v[8:11], v[146:149], v[210:213], v[8:11]
	v_mfma_f32_16x16x32_bf16 v[60:63], v[142:145], v[190:193], v[60:63]
	v_mfma_f32_16x16x32_bf16 v[56:59], v[150:153], v[190:193], v[56:59]
	v_mfma_f32_16x16x32_bf16 v[44:47], v[142:145], v[198:201], v[44:47]
	v_mfma_f32_16x16x32_bf16 v[40:43], v[150:153], v[198:201], v[40:43]
	v_mfma_f32_16x16x32_bf16 v[28:31], v[142:145], v[206:209], v[28:31]
	v_mfma_f32_16x16x32_bf16 v[24:27], v[150:153], v[206:209], v[24:27]
	v_mfma_f32_16x16x32_bf16 v[12:15], v[142:145], v[214:217], v[12:15]
	s_setprio 0
	v_mfma_f32_16x16x32_bf16 v[8:11], v[150:153], v[214:217], v[8:11]
	s_barrier
	s_add_u32 s20, s20, 0x80080
	s_addc_u32 s21, s21, 0
	s_add_i32 s22, s22, s27
	s_mov_b32 m0, s22
	s_nop 0
	global_load_lds_dwordx4 v158, s[20:21]
	s_add_i32 m0, s22, 0x2000
	s_nop 0
	global_load_lds_dwordx4 v128, s[20:21]
	s_waitcnt vmcnt(6)
	s_setprio 1
	s_barrier
	v_mfma_f32_16x16x32_bf16 v[52:55], v[226:229], v[186:189], v[52:55]
	v_mfma_f32_16x16x32_bf16 v[48:51], v[234:237], v[186:189], v[48:51]
	v_mfma_f32_16x16x32_bf16 v[36:39], v[226:229], v[194:197], v[36:39]
	v_mfma_f32_16x16x32_bf16 v[32:35], v[234:237], v[194:197], v[32:35]
	v_mfma_f32_16x16x32_bf16 v[20:23], v[226:229], v[202:205], v[20:23]
	v_mfma_f32_16x16x32_bf16 v[16:19], v[234:237], v[202:205], v[16:19]
	v_mfma_f32_16x16x32_bf16 v[4:7], v[226:229], v[210:213], v[4:7]
	v_mfma_f32_16x16x32_bf16 v[0:3], v[234:237], v[210:213], v[0:3]
	v_mfma_f32_16x16x32_bf16 v[52:55], v[230:233], v[190:193], v[52:55]
	s_add_i32 s38, s38, 2
	v_mfma_f32_16x16x32_bf16 v[48:51], v[238:241], v[190:193], v[48:51]
	s_add_u32 s18, s18, 0x100
	v_mfma_f32_16x16x32_bf16 v[36:39], v[230:233], v[198:201], v[36:39]
	s_addc_u32 s19, s19, 0
	v_mfma_f32_16x16x32_bf16 v[32:35], v[238:241], v[198:201], v[32:35]
	s_add_u32 s33, s33, 0x100
	v_mfma_f32_16x16x32_bf16 v[20:23], v[230:233], v[206:209], v[20:23]
	s_addc_u32 s37, s37, 0
	v_mfma_f32_16x16x32_bf16 v[16:19], v[238:241], v[206:209], v[16:19]
	s_cmp_gt_u32 s38, 29
	v_mfma_f32_16x16x32_bf16 v[4:7], v[230:233], v[214:217], v[4:7]
	s_setprio 0
	v_mfma_f32_16x16x32_bf16 v[0:3], v[238:241], v[214:217], v[0:3]
	s_barrier
	s_cbranch_scc0 .LBB0_37
	v_mul_f32_e32 v139, 0xbfb8aa3b, v124
	v_exp_f32_e32 v139, v139
	v_lshl_or_b32 v140, s2, 7, v136
	v_lshl_add_u32 v138, s3, 8, v134
	v_ashrrev_i32_e32 v141, 31, v140
	v_add_f32_e32 v139, 1.0, v139
	v_rcp_f32_e32 v142, v139
	v_mul_f32_e32 v139, 0xbfb8aa3b, v125
	v_exp_f32_e32 v139, v139
	s_movk_i32 s4, 0x2c00
	s_and_b64 vcc, exec, s[6:7]
	s_mov_b64 s[20:21], s[16:17]
	v_add_f32_e32 v139, 1.0, v139
	v_rcp_f32_e32 v143, v139
	v_mul_f32_e32 v139, 0xbfb8aa3b, v126
	v_exp_f32_e32 v139, v139
	s_mov_b64 s[18:19], s[14:15]
	v_pk_mul_f32 v[124:125], v[124:125], v[142:143]
	v_add_f32_e32 v139, 1.0, v139
	v_rcp_f32_e32 v144, v139
	v_mul_f32_e32 v139, 0xbfb8aa3b, v127
	v_exp_f32_e32 v139, v139
	v_pk_mul_f32 v[116:117], v[124:125], v[116:117]
	v_add_f32_e32 v139, 1.0, v139
	v_rcp_f32_e32 v145, v139
	v_mul_f32_e32 v139, 0xbfb8aa3b, v120
	v_exp_f32_e32 v139, v139
	v_cvt_pk_bf16_f32 v116, v116, v117
	v_pk_mul_f32 v[124:125], v[126:127], v[144:145]
	v_add_f32_e32 v139, 1.0, v139
	v_rcp_f32_e32 v146, v139
	v_mul_f32_e32 v139, 0xbfb8aa3b, v121
	v_exp_f32_e32 v139, v139
	v_pk_mul_f32 v[118:119], v[124:125], v[118:119]
	v_add_f32_e32 v139, 1.0, v139
	v_rcp_f32_e32 v147, v139
	v_mul_f32_e32 v139, 0xbfb8aa3b, v122
	v_exp_f32_e32 v139, v139
	v_cvt_pk_bf16_f32 v117, v118, v119
	v_pk_mul_f32 v[118:119], v[120:121], v[146:147]
	v_add_f32_e32 v139, 1.0, v139
	v_rcp_f32_e32 v148, v139
	v_mul_f32_e32 v139, 0xbfb8aa3b, v123
	v_exp_f32_e32 v139, v139
	v_pk_mul_f32 v[112:113], v[118:119], v[112:113]
	v_add_f32_e32 v139, 1.0, v139
	v_rcp_f32_e32 v149, v139
	v_cvt_pk_bf16_f32 v118, v112, v113
	v_pk_mul_f32 v[112:113], v[122:123], v[148:149]
	s_nop 0
	v_pk_mul_f32 v[112:113], v[112:113], v[114:115]
	v_lshlrev_b64 v[114:115], 1, v[140:141]
	v_cvt_pk_bf16_f32 v119, v112, v113
	v_mov_b64_e32 v[112:113], s[54:55]
	v_mad_i64_i32 v[120:121], s[2:3], v138, s4, v[112:113]
	v_lshl_add_u64 v[120:121], v[120:121], 0, v[114:115]
	global_store_dwordx4 v[120:121], v[116:119], off
	v_mul_f32_e32 v120, 0xbfb8aa3b, v104
	v_mul_f32_e32 v121, 0xbfb8aa3b, v105
	v_mul_f32_e32 v116, 0xbfb8aa3b, v108
	v_mul_f32_e32 v117, 0xbfb8aa3b, v109
	v_exp_f32_e32 v116, v116
	v_exp_f32_e32 v117, v117
	v_mul_f32_e32 v118, 0xbfb8aa3b, v110
	v_mul_f32_e32 v119, 0xbfb8aa3b, v111
	v_exp_f32_e32 v118, v118
	v_exp_f32_e32 v119, v119
	v_exp_f32_e32 v120, v120
	v_exp_f32_e32 v121, v121
	v_add_f32_e32 v116, 1.0, v116
	v_add_f32_e32 v117, 1.0, v117
	v_mul_f32_e32 v122, 0xbfb8aa3b, v106
	v_mul_f32_e32 v123, 0xbfb8aa3b, v107
	v_rcp_f32_e32 v116, v116
	v_rcp_f32_e32 v117, v117
	v_add_f32_e32 v118, 1.0, v118
	v_add_f32_e32 v119, 1.0, v119
	v_exp_f32_e32 v122, v122
	v_exp_f32_e32 v123, v123
	v_rcp_f32_e32 v118, v118
	v_rcp_f32_e32 v119, v119
	v_add_f32_e32 v120, 1.0, v120
	v_add_f32_e32 v121, 1.0, v121
	v_rcp_f32_e32 v120, v120
	v_rcp_f32_e32 v121, v121
	v_add_f32_e32 v122, 1.0, v122
	v_add_f32_e32 v123, 1.0, v123
	v_pk_mul_f32 v[108:109], v[108:109], v[116:117]
	v_rcp_f32_e32 v122, v122
;     DI void operator()(const f32x4 (&acc)[2][2][4][2], const Unit& u, int wr, int wc, int fr, int fq) const {
;         const int row0 = u.pm * BM + wr * 64 + fr, col0 = u.pn * HALF + wc * 32 + 8 * fq;
; #pragma unroll
;         for (int ai = 0; ai < 2; ++ai)
; #pragma unroll
;             for (int m = 0; m < 4; ++m) { float hv[8];
; #pragma unroll
;                 for (int n = 0; n < 2; ++n)
; #pragma unroll
;                     for (int e = 0; e < 4; ++e) { const float gt = acc[ai][0][m][n][e], up = acc[ai][1][m][n][e];
;                         hv[n * 4 + e] = gt * __builtin_amdgcn_rcpf(1.f + __builtin_amdgcn_exp2f(-1.4426950408889634f * gt)) * up; }
;                 *(u32x4*)(H + (size_t)(row0 + ai * HALF + m * 16) * DFF + col0) = (u32x4){pk(hv[0], hv[1]), pk(hv[2], hv[3]), pk(hv[4], hv[5]), pk(hv[6], hv[7])}; }
	v_rcp_f32_e32 v123, v123
	v_pk_mul_f32 v[100:101], v[108:109], v[100:101]
	v_pk_mul_f32 v[108:109], v[110:111], v[118:119]
	v_cvt_pk_bf16_f32 v100, v100, v101
	v_pk_mul_f32 v[102:103], v[108:109], v[102:103]
	s_nop 0
	v_cvt_pk_bf16_f32 v101, v102, v103
	v_pk_mul_f32 v[102:103], v[104:105], v[120:121]
	s_nop 0
	v_pk_mul_f32 v[96:97], v[102:103], v[96:97]
	s_nop 0
	v_cvt_pk_bf16_f32 v102, v96, v97
	v_pk_mul_f32 v[96:97], v[106:107], v[122:123]
	s_nop 0
	v_pk_mul_f32 v[96:97], v[96:97], v[98:99]
	v_mul_f32_e32 v98, 0xbfb8aa3b, v94
	v_cvt_pk_bf16_f32 v103, v96, v97
	v_or_b32_e32 v96, 16, v138
	v_mad_i64_i32 v[96:97], s[2:3], v96, s4, v[112:113]
	v_lshl_add_u64 v[96:97], v[96:97], 0, v[114:115]
	global_store_dwordx4 v[96:97], v[100:103], off
	v_mul_f32_e32 v96, 0xbfb8aa3b, v92
	v_mul_f32_e32 v97, 0xbfb8aa3b, v93
	v_exp_f32_e32 v96, v96
	v_exp_f32_e32 v97, v97
	v_mul_f32_e32 v99, 0xbfb8aa3b, v95
	v_exp_f32_e32 v98, v98
	v_exp_f32_e32 v99, v99
	v_mul_f32_e32 v100, 0xbfb8aa3b, v88
	v_mul_f32_e32 v101, 0xbfb8aa3b, v89
	v_exp_f32_e32 v100, v100
	v_exp_f32_e32 v101, v101
	v_add_f32_e32 v96, 1.0, v96
	v_add_f32_e32 v97, 1.0, v97
	v_mul_f32_e32 v102, 0xbfb8aa3b, v90
	v_mul_f32_e32 v103, 0xbfb8aa3b, v91
	v_rcp_f32_e32 v96, v96
	v_rcp_f32_e32 v97, v97
	v_add_f32_e32 v98, 1.0, v98
	v_add_f32_e32 v99, 1.0, v99
	v_exp_f32_e32 v102, v102
	v_exp_f32_e32 v103, v103
	v_rcp_f32_e32 v98, v98
	v_rcp_f32_e32 v99, v99
	v_add_f32_e32 v100, 1.0, v100
	v_add_f32_e32 v101, 1.0, v101
	v_rcp_f32_e32 v100, v100
	v_rcp_f32_e32 v101, v101
	v_add_f32_e32 v102, 1.0, v102
	v_add_f32_e32 v103, 1.0, v103
	v_pk_mul_f32 v[92:93], v[92:93], v[96:97]
	v_rcp_f32_e32 v102, v102
	v_rcp_f32_e32 v103, v103
	v_pk_mul_f32 v[84:85], v[92:93], v[84:85]
	v_pk_mul_f32 v[92:93], v[94:95], v[98:99]
	v_cvt_pk_bf16_f32 v84, v84, v85
	v_pk_mul_f32 v[86:87], v[92:93], v[86:87]
	s_nop 0
	v_cvt_pk_bf16_f32 v85, v86, v87
	v_pk_mul_f32 v[86:87], v[88:89], v[100:101]
	s_nop 0
	v_pk_mul_f32 v[80:81], v[86:87], v[80:81]
	s_nop 0
	v_cvt_pk_bf16_f32 v86, v80, v81
	v_pk_mul_f32 v[80:81], v[90:91], v[102:103]
	s_nop 0
	v_pk_mul_f32 v[80:81], v[80:81], v[82:83]
	v_mul_f32_e32 v82, 0xbfb8aa3b, v78
	v_cvt_pk_bf16_f32 v87, v80, v81
	v_or_b32_e32 v80, 32, v138
	v_mad_i64_i32 v[80:81], s[2:3], v80, s4, v[112:113]
	v_lshl_add_u64 v[80:81], v[80:81], 0, v[114:115]
	global_store_dwordx4 v[80:81], v[84:87], off
	v_mul_f32_e32 v80, 0xbfb8aa3b, v76
	v_mul_f32_e32 v81, 0xbfb8aa3b, v77
	v_exp_f32_e32 v80, v80
	v_exp_f32_e32 v81, v81
	v_mul_f32_e32 v83, 0xbfb8aa3b, v79
	v_exp_f32_e32 v82, v82
	v_exp_f32_e32 v83, v83
	v_mul_f32_e32 v84, 0xbfb8aa3b, v72
	v_mul_f32_e32 v85, 0xbfb8aa3b, v73
	v_exp_f32_e32 v84, v84
	v_exp_f32_e32 v85, v85
	v_add_f32_e32 v80, 1.0, v80
	v_add_f32_e32 v81, 1.0, v81
	v_mul_f32_e32 v86, 0xbfb8aa3b, v74
	v_mul_f32_e32 v87, 0xbfb8aa3b, v75
	v_rcp_f32_e32 v80, v80
	v_rcp_f32_e32 v81, v81
	v_add_f32_e32 v82, 1.0, v82
	v_add_f32_e32 v83, 1.0, v83
	v_exp_f32_e32 v86, v86
	v_exp_f32_e32 v87, v87
	v_rcp_f32_e32 v82, v82
	v_rcp_f32_e32 v83, v83
	v_add_f32_e32 v84, 1.0, v84
	v_add_f32_e32 v85, 1.0, v85
	v_rcp_f32_e32 v84, v84
	v_rcp_f32_e32 v85, v85
	v_add_f32_e32 v86, 1.0, v86
	v_add_f32_e32 v87, 1.0, v87
	v_pk_mul_f32 v[76:77], v[76:77], v[80:81]
	v_rcp_f32_e32 v86, v86
	v_rcp_f32_e32 v87, v87
	v_pk_mul_f32 v[68:69], v[76:77], v[68:69]
	v_pk_mul_f32 v[76:77], v[78:79], v[82:83]
	v_cvt_pk_bf16_f32 v68, v68, v69
	v_pk_mul_f32 v[70:71], v[76:77], v[70:71]
	s_nop 0
	v_cvt_pk_bf16_f32 v69, v70, v71
	v_pk_mul_f32 v[70:71], v[72:73], v[84:85]
	v_add_u32_e32 v72, 0x80, v138
	v_pk_mul_f32 v[64:65], v[70:71], v[64:65]
	s_nop 0
	v_cvt_pk_bf16_f32 v70, v64, v65
	v_pk_mul_f32 v[64:65], v[74:75], v[86:87]
	s_nop 0
	v_pk_mul_f32 v[64:65], v[64:65], v[66:67]
	v_mul_f32_e32 v66, 0xbfb8aa3b, v62
	v_cvt_pk_bf16_f32 v71, v64, v65
	v_or_b32_e32 v64, 48, v138
	v_mad_i64_i32 v[64:65], s[2:3], v64, s4, v[112:113]
	v_lshl_add_u64 v[64:65], v[64:65], 0, v[114:115]
	global_store_dwordx4 v[64:65], v[68:71], off
	v_mul_f32_e32 v64, 0xbfb8aa3b, v60
	v_mul_f32_e32 v65, 0xbfb8aa3b, v61
	v_exp_f32_e32 v64, v64
	v_exp_f32_e32 v65, v65
	v_mul_f32_e32 v67, 0xbfb8aa3b, v63
	v_exp_f32_e32 v66, v66
	v_exp_f32_e32 v67, v67
	v_mul_f32_e32 v68, 0xbfb8aa3b, v56
	v_mul_f32_e32 v69, 0xbfb8aa3b, v57
	v_exp_f32_e32 v68, v68
	v_exp_f32_e32 v69, v69
	v_add_f32_e32 v64, 1.0, v64
	v_add_f32_e32 v65, 1.0, v65
	v_mul_f32_e32 v70, 0xbfb8aa3b, v58
	v_mul_f32_e32 v71, 0xbfb8aa3b, v59
	v_rcp_f32_e32 v64, v64
	v_rcp_f32_e32 v65, v65
	v_add_f32_e32 v66, 1.0, v66
	v_add_f32_e32 v67, 1.0, v67
	v_exp_f32_e32 v70, v70
	v_exp_f32_e32 v71, v71
	v_rcp_f32_e32 v66, v66
	v_rcp_f32_e32 v67, v67
	v_add_f32_e32 v68, 1.0, v68
	v_add_f32_e32 v69, 1.0, v69
	v_rcp_f32_e32 v68, v68
	v_rcp_f32_e32 v69, v69
	v_add_f32_e32 v70, 1.0, v70
	v_add_f32_e32 v71, 1.0, v71
	v_pk_mul_f32 v[60:61], v[60:61], v[64:65]
	v_rcp_f32_e32 v70, v70
	v_rcp_f32_e32 v71, v71
	v_pk_mul_f32 v[52:53], v[60:61], v[52:53]
	v_pk_mul_f32 v[60:61], v[62:63], v[66:67]
	v_cvt_pk_bf16_f32 v52, v52, v53
	v_pk_mul_f32 v[54:55], v[60:61], v[54:55]
	s_nop 0
	v_cvt_pk_bf16_f32 v53, v54, v55
	v_pk_mul_f32 v[54:55], v[56:57], v[68:69]
	s_nop 0
	v_pk_mul_f32 v[48:49], v[54:55], v[48:49]
; #define PG8_WAIT_V(n) asm volatile("s_waitcnt vmcnt(" #n ")" ::: "memory")
; #define PG8_BAR __builtin_amdgcn_s_barrier()
; template <class Epi>
; DI void gemm_phase(LAS unsigned char* lds, const Gemm g, const StaticOrder& S, const Epi& E) {
;     ...
;         E(acc, cur, wr, wc, fr, fq);
;         if (!has_next) break;
; #pragma unroll
;         for (int a = 0; a < 2; ++a)
; #pragma unroll
;             for (int b = 0; b < 2; ++b)
; #pragma unroll
;                 for (int m = 0; m < 4; ++m)
; #pragma unroll
;                     for (int n = 0; n < 2; ++n) acc[a][b][m][n] = (f32x4){0.f, 0.f, 0.f, 0.f};
;         cur = nxt; cA = nA; cB = nB; ++ui;
;     }
;     PG8_WAIT_V(0);
;     if (wr == 0) PG8_BAR;
;     DI void operator()(const f32x4 (&acc)[2][2][4][2], const Unit& u, int wr, int wc, int fr, int fq) const {
;         const int row0 = u.pm * BM + wr * 64 + fr, col0 = u.pn * HALF + wc * 32 + 8 * fq;
; #pragma unroll
;         for (int ai = 0; ai < 2; ++ai)
; #pragma unroll
;             for (int m = 0; m < 4; ++m) { float hv[8];
; #pragma unroll
;                 for (int n = 0; n < 2; ++n)
; #pragma unroll
;                     for (int e = 0; e < 4; ++e) { const float gt = acc[ai][0][m][n][e], up = acc[ai][1][m][n][e];
;                         hv[n * 4 + e] = gt * __builtin_amdgcn_rcpf(1.f + __builtin_amdgcn_exp2f(-1.4426950408889634f * gt)) * up; }
;                 *(u32x4*)(H + (size_t)(row0 + ai * HALF + m * 16) * DFF + col0) = (u32x4){pk(hv[0], hv[1]), pk(hv[2], hv[3]), pk(hv[4], hv[5]), pk(hv[6], hv[7])}; }
	s_nop 0
	v_cvt_pk_bf16_f32 v54, v48, v49
	v_pk_mul_f32 v[48:49], v[58:59], v[70:71]
	s_nop 0
	v_pk_mul_f32 v[48:49], v[48:49], v[50:51]
	v_mul_f32_e32 v50, 0xbfb8aa3b, v46
	v_cvt_pk_bf16_f32 v55, v48, v49
	v_mad_i64_i32 v[48:49], s[2:3], v72, s4, v[112:113]
	v_lshl_add_u64 v[48:49], v[48:49], 0, v[114:115]
	global_store_dwordx4 v[48:49], v[52:55], off
	v_mul_f32_e32 v48, 0xbfb8aa3b, v44
	v_mul_f32_e32 v49, 0xbfb8aa3b, v45
	v_exp_f32_e32 v48, v48
	v_exp_f32_e32 v49, v49
	v_mul_f32_e32 v51, 0xbfb8aa3b, v47
	v_exp_f32_e32 v50, v50
	v_exp_f32_e32 v51, v51
	v_mul_f32_e32 v52, 0xbfb8aa3b, v40
	v_mul_f32_e32 v53, 0xbfb8aa3b, v41
	v_exp_f32_e32 v52, v52
	v_exp_f32_e32 v53, v53
	v_add_f32_e32 v48, 1.0, v48
	v_add_f32_e32 v49, 1.0, v49
	v_mul_f32_e32 v54, 0xbfb8aa3b, v42
	v_mul_f32_e32 v55, 0xbfb8aa3b, v43
	v_rcp_f32_e32 v48, v48
	v_rcp_f32_e32 v49, v49
	v_add_f32_e32 v50, 1.0, v50
	v_add_f32_e32 v51, 1.0, v51
	v_exp_f32_e32 v54, v54
	v_exp_f32_e32 v55, v55
	v_rcp_f32_e32 v50, v50
	v_rcp_f32_e32 v51, v51
	v_add_f32_e32 v52, 1.0, v52
	v_add_f32_e32 v53, 1.0, v53
	v_rcp_f32_e32 v52, v52
	v_rcp_f32_e32 v53, v53
	v_add_f32_e32 v54, 1.0, v54
	v_add_f32_e32 v55, 1.0, v55
	v_pk_mul_f32 v[44:45], v[44:45], v[48:49]
	v_rcp_f32_e32 v54, v54
	v_rcp_f32_e32 v55, v55
	v_pk_mul_f32 v[36:37], v[44:45], v[36:37]
	v_pk_mul_f32 v[44:45], v[46:47], v[50:51]
	v_cvt_pk_bf16_f32 v36, v36, v37
	v_pk_mul_f32 v[38:39], v[44:45], v[38:39]
	s_nop 0
	v_cvt_pk_bf16_f32 v37, v38, v39
	v_pk_mul_f32 v[38:39], v[40:41], v[52:53]
	s_nop 0
	v_pk_mul_f32 v[32:33], v[38:39], v[32:33]
	s_nop 0
	v_cvt_pk_bf16_f32 v38, v32, v33
	v_pk_mul_f32 v[32:33], v[42:43], v[54:55]
	s_nop 0
	v_pk_mul_f32 v[32:33], v[32:33], v[34:35]
	v_mul_f32_e32 v34, 0xbfb8aa3b, v30
	v_cvt_pk_bf16_f32 v39, v32, v33
	v_add_u32_e32 v32, 0x90, v138
	v_mad_i64_i32 v[32:33], s[2:3], v32, s4, v[112:113]
	v_lshl_add_u64 v[32:33], v[32:33], 0, v[114:115]
	global_store_dwordx4 v[32:33], v[36:39], off
	v_mul_f32_e32 v32, 0xbfb8aa3b, v28
	v_mul_f32_e32 v33, 0xbfb8aa3b, v29
	v_exp_f32_e32 v32, v32
	v_exp_f32_e32 v33, v33
	v_mul_f32_e32 v35, 0xbfb8aa3b, v31
	v_exp_f32_e32 v34, v34
	v_exp_f32_e32 v35, v35
	v_mul_f32_e32 v36, 0xbfb8aa3b, v24
	v_mul_f32_e32 v37, 0xbfb8aa3b, v25
	v_exp_f32_e32 v36, v36
	v_exp_f32_e32 v37, v37
	v_add_f32_e32 v32, 1.0, v32
	v_add_f32_e32 v33, 1.0, v33
	v_mul_f32_e32 v38, 0xbfb8aa3b, v26
	v_mul_f32_e32 v39, 0xbfb8aa3b, v27
	v_rcp_f32_e32 v32, v32
	v_rcp_f32_e32 v33, v33
	v_add_f32_e32 v34, 1.0, v34
	v_add_f32_e32 v35, 1.0, v35
	v_exp_f32_e32 v38, v38
	v_exp_f32_e32 v39, v39
	v_rcp_f32_e32 v34, v34
	v_rcp_f32_e32 v35, v35
	v_add_f32_e32 v36, 1.0, v36
	v_add_f32_e32 v37, 1.0, v37
	v_rcp_f32_e32 v36, v36
	v_rcp_f32_e32 v37, v37
	v_add_f32_e32 v38, 1.0, v38
	v_add_f32_e32 v39, 1.0, v39
	v_pk_mul_f32 v[28:29], v[28:29], v[32:33]
	v_rcp_f32_e32 v38, v38
	v_rcp_f32_e32 v39, v39
	v_pk_mul_f32 v[20:21], v[28:29], v[20:21]
	v_pk_mul_f32 v[28:29], v[30:31], v[34:35]
	v_cvt_pk_bf16_f32 v20, v20, v21
	v_pk_mul_f32 v[22:23], v[28:29], v[22:23]
	s_nop 0
	v_cvt_pk_bf16_f32 v21, v22, v23
	v_pk_mul_f32 v[22:23], v[24:25], v[36:37]
	s_nop 0
	v_pk_mul_f32 v[16:17], v[22:23], v[16:17]
	s_nop 0
	v_cvt_pk_bf16_f32 v22, v16, v17
	v_pk_mul_f32 v[16:17], v[26:27], v[38:39]
	s_nop 0
	v_pk_mul_f32 v[16:17], v[16:17], v[18:19]
	v_mul_f32_e32 v18, 0xbfb8aa3b, v14
	v_cvt_pk_bf16_f32 v23, v16, v17
	v_add_u32_e32 v16, 0xa0, v138
	v_mad_i64_i32 v[16:17], s[2:3], v16, s4, v[112:113]
	v_lshl_add_u64 v[16:17], v[16:17], 0, v[114:115]
	global_store_dwordx4 v[16:17], v[20:23], off
	v_mul_f32_e32 v16, 0xbfb8aa3b, v12
	v_mul_f32_e32 v17, 0xbfb8aa3b, v13
	v_exp_f32_e32 v16, v16
	v_exp_f32_e32 v17, v17
	v_mul_f32_e32 v19, 0xbfb8aa3b, v15
	v_exp_f32_e32 v18, v18
	v_exp_f32_e32 v19, v19
	v_mul_f32_e32 v20, 0xbfb8aa3b, v8
	v_mul_f32_e32 v21, 0xbfb8aa3b, v9
	v_exp_f32_e32 v20, v20
	v_exp_f32_e32 v21, v21
	v_add_f32_e32 v16, 1.0, v16
	v_add_f32_e32 v17, 1.0, v17
	v_mul_f32_e32 v22, 0xbfb8aa3b, v10
	v_mul_f32_e32 v23, 0xbfb8aa3b, v11
	v_rcp_f32_e32 v16, v16
	v_rcp_f32_e32 v17, v17
	v_add_f32_e32 v18, 1.0, v18
	v_add_f32_e32 v19, 1.0, v19
	v_exp_f32_e32 v22, v22
	v_exp_f32_e32 v23, v23
	v_rcp_f32_e32 v18, v18
	v_rcp_f32_e32 v19, v19
	v_add_f32_e32 v20, 1.0, v20
	v_add_f32_e32 v21, 1.0, v21
	v_rcp_f32_e32 v20, v20
	v_rcp_f32_e32 v21, v21
	v_add_f32_e32 v22, 1.0, v22
	v_add_f32_e32 v23, 1.0, v23
	v_pk_mul_f32 v[12:13], v[12:13], v[16:17]
	v_rcp_f32_e32 v22, v22
	v_rcp_f32_e32 v23, v23
	v_pk_mul_f32 v[4:5], v[12:13], v[4:5]
	v_pk_mul_f32 v[12:13], v[14:15], v[18:19]
	v_cvt_pk_bf16_f32 v4, v4, v5
	v_pk_mul_f32 v[6:7], v[12:13], v[6:7]
	s_nop 0
	v_cvt_pk_bf16_f32 v5, v6, v7
	v_pk_mul_f32 v[6:7], v[8:9], v[20:21]
	s_nop 0
	v_pk_mul_f32 v[0:1], v[6:7], v[0:1]
	s_nop 0
	v_cvt_pk_bf16_f32 v6, v0, v1
	v_pk_mul_f32 v[0:1], v[10:11], v[22:23]
	s_nop 0
	v_pk_mul_f32 v[0:1], v[0:1], v[2:3]
	s_nop 0
	v_cvt_pk_bf16_f32 v7, v0, v1
	v_add_u32_e32 v0, 0xb0, v138
	v_mad_i64_i32 v[0:1], s[2:3], v0, s4, v[112:113]
	v_lshl_add_u64 v[0:1], v[0:1], 0, v[114:115]
	s_mov_b32 s2, s8
	s_mov_b32 s3, s10
	global_store_dwordx4 v[0:1], v[4:7], off
	s_cbranch_vccz .LBB0_34
	s_waitcnt vmcnt(0)
	s_cmpk_gt_u32 s24, 0xff
	s_cbranch_scc1 .LBB0_41
	s_barrier

; #define PG8_STAGE(bufoff, gbase) do { _Pragma("unroll") for (int _i = 0; _i < 2; ++_i) \
;         __builtin_amdgcn_global_load_lds((const unsigned*)((const char*)(gbase) + voff[_i]), (LAS unsigned*)(lds + (bufoff) + ldsw + _i * 8192), 16, 0, 0); } while (0)
; #define PG8_LDA(dst, b, h) do { _Pragma("unroll") for (int m = 0; m < 4; ++m) _Pragma("unroll") for (int k = 0; k < 2; ++k) dst[m][k] = *(const LAS bf16x8*)(lds + PG8_SA(b, h) + aoff + m * 2048 + k * 1024); } while (0)
; #define PG8_LDB(dst, b, h) do { _Pragma("unroll") for (int n = 0; n < 2; ++n) _Pragma("unroll") for (int k = 0; k < 2; ++k) dst[n][k] = *(const LAS bf16x8*)(lds + PG8_SB(b, h) + boff + n * 2048 + k * 1024); } while (0)
; #define PG8_MMA(ai, bj, At, Bt) do { __builtin_amdgcn_s_setprio(1); _Pragma("unroll") for (int m = 0; m < 4; ++m) _Pragma("unroll") for (int n = 0; n < 2; ++n) _Pragma("unroll") for (int k = 0; k < 2; ++k) \
;         acc[ai][bj][m][n] = __builtin_amdgcn_mfma_f32_16x16x32_bf16(Bt[n][k], At[m][k], acc[ai][bj][m][n], 0, 0, 0); __builtin_amdgcn_s_setprio(0); } while (0)
; #define PG8_WAIT_V(n) asm volatile("s_waitcnt vmcnt(" #n ")" ::: "memory")
; #define PG8_WAIT_L(n) asm volatile("s_waitcnt lgkmcnt(" #n ")" ::: "memory")
; #define PG8_BAR __builtin_amdgcn_s_barrier()
; #define PG8_SCHED __builtin_amdgcn_sched_barrier(0)
; template <class Epi>
; DI void gemm_phase(LAS unsigned char* lds, const Gemm g, const StaticOrder& S, const Epi& E) {
;     ...
;             PG8_LDB(B0, 0, 0); PG8_SCHED; PG8_LDA(At, 0, 0); PG8_STAGE(PG8_SA(1, 1), a1 + hstep);
;             PG8_WAIT_L(8); PG8_BAR; PG8_WAIT_L(0); PG8_MMA(0, 0, At, B0); PG8_BAR; PG8_SCHED;
;             PG8_LDB(B1, 0, 1); PG8_STAGE(PG8_SB(0, 0), b2);
;             PG8_BAR; PG8_WAIT_L(0); PG8_MMA(0, 1, At, B1); PG8_BAR;
;             PG8_LDA(At, 0, 1); PG8_STAGE(PG8_SA(0, 0), a2);
;             PG8_BAR; PG8_WAIT_L(0); PG8_MMA(1, 0, At, B0); PG8_BAR; PG8_SCHED;
;             PG8_STAGE(PG8_SB(0, 1), b2 + hstep);
;             PG8_WAIT_V(6); PG8_BAR; PG8_MMA(1, 1, At, B1); PG8_BAR;
.LBB0_77:
	ds_read_b128 v[128:131], v226
	ds_read_b128 v[132:135], v226 offset:1024
	ds_read_b128 v[136:139], v226 offset:2048
	ds_read_b128 v[140:143], v226 offset:3072
	ds_read_b128 v[144:147], v228
	ds_read_b128 v[148:151], v228 offset:1024
	ds_read_b128 v[152:155], v228 offset:2048
	ds_read_b128 v[194:197], v228 offset:3072
	ds_read_b128 v[198:201], v228 offset:4096
	ds_read_b128 v[202:205], v228 offset:5120
	ds_read_b128 v[206:209], v228 offset:6144
	ds_read_b128 v[210:213], v228 offset:7168
	s_add_u32 s22, s20, 0x100
	s_addc_u32 s23, s21, 0
	s_add_i32 s43, 0, 0x10000
	s_cmp_eq_u32 s33, 32
	s_cselect_b32 s27, s9, s23
	s_cselect_b32 s26, s8, s22
	s_cselect_b32 s25, s11, s5
	s_cselect_b32 s24, s10, s4
	s_add_i32 m0, s34, 0xc000
	s_nop 0
	global_load_lds_dwordx4 v190, s[20:21]
	s_add_i32 m0, s34, 0xe000
	s_nop 0
	global_load_lds_dwordx4 v192, s[20:21]
	s_waitcnt lgkmcnt(8)
	s_setprio 1
	s_barrier
	s_waitcnt lgkmcnt(0)
	v_mfma_f32_16x16x32_bf16 v[124:127], v[128:131], v[144:147], v[124:127]
	v_mfma_f32_16x16x32_bf16 v[120:123], v[136:139], v[144:147], v[120:123]
	v_mfma_f32_16x16x32_bf16 v[116:119], v[128:131], v[152:155], v[116:119]
	v_mfma_f32_16x16x32_bf16 v[112:115], v[136:139], v[152:155], v[112:115]
	v_mfma_f32_16x16x32_bf16 v[108:111], v[128:131], v[198:201], v[108:111]
	v_mfma_f32_16x16x32_bf16 v[104:107], v[136:139], v[198:201], v[104:107]
	v_mfma_f32_16x16x32_bf16 v[100:103], v[128:131], v[206:209], v[100:103]
	v_mfma_f32_16x16x32_bf16 v[96:99], v[136:139], v[206:209], v[96:99]
	v_mfma_f32_16x16x32_bf16 v[124:127], v[132:135], v[148:151], v[124:127]
	v_mfma_f32_16x16x32_bf16 v[120:123], v[140:143], v[148:151], v[120:123]
	v_mfma_f32_16x16x32_bf16 v[116:119], v[132:135], v[194:197], v[116:119]
	v_mfma_f32_16x16x32_bf16 v[112:115], v[140:143], v[194:197], v[112:115]
	v_mfma_f32_16x16x32_bf16 v[108:111], v[132:135], v[202:205], v[108:111]
	v_mfma_f32_16x16x32_bf16 v[104:107], v[140:143], v[202:205], v[104:107]
	v_mfma_f32_16x16x32_bf16 v[100:103], v[132:135], v[210:213], v[100:103]
	s_setprio 0
	v_mfma_f32_16x16x32_bf16 v[96:99], v[140:143], v[210:213], v[96:99]
	s_barrier
	ds_read_b128 v[214:217], v226 offset:16384
	ds_read_b128 v[230:233], v226 offset:17408
	ds_read_b128 v[234:237], v226 offset:18432
	ds_read_b128 v[238:241], v226 offset:19456
	s_add_i32 s44, 0, 0x14000
	s_add_i32 s20, s43, s31
	s_mov_b32 m0, s20
	s_nop 0
	global_load_lds_dwordx4 v188, s[24:25]
	s_add_i32 m0, s20, 0x2000
	s_nop 0
	global_load_lds_dwordx4 v186, s[24:25]
	s_waitcnt lgkmcnt(0)
	s_setprio 1
	s_barrier
	v_mfma_f32_16x16x32_bf16 v[60:63], v[214:217], v[144:147], v[60:63]
	v_mfma_f32_16x16x32_bf16 v[56:59], v[234:237], v[144:147], v[56:59]
	v_mfma_f32_16x16x32_bf16 v[52:55], v[214:217], v[152:155], v[52:55]
	v_mfma_f32_16x16x32_bf16 v[48:51], v[234:237], v[152:155], v[48:51]
	v_mfma_f32_16x16x32_bf16 v[44:47], v[214:217], v[198:201], v[44:47]
	v_mfma_f32_16x16x32_bf16 v[40:43], v[234:237], v[198:201], v[40:43]
	v_mfma_f32_16x16x32_bf16 v[36:39], v[214:217], v[206:209], v[36:39]
	v_mfma_f32_16x16x32_bf16 v[32:35], v[234:237], v[206:209], v[32:35]
	v_mfma_f32_16x16x32_bf16 v[60:63], v[230:233], v[148:151], v[60:63]
	v_mfma_f32_16x16x32_bf16 v[56:59], v[238:241], v[148:151], v[56:59]
	v_mfma_f32_16x16x32_bf16 v[52:55], v[230:233], v[194:197], v[52:55]
	v_mfma_f32_16x16x32_bf16 v[48:51], v[238:241], v[194:197], v[48:51]
	v_mfma_f32_16x16x32_bf16 v[44:47], v[230:233], v[202:205], v[44:47]
	v_mfma_f32_16x16x32_bf16 v[40:43], v[238:241], v[202:205], v[40:43]
	v_mfma_f32_16x16x32_bf16 v[36:39], v[230:233], v[210:213], v[36:39]
	s_setprio 0
	v_mfma_f32_16x16x32_bf16 v[32:35], v[238:241], v[210:213], v[32:35]
	s_barrier
	ds_read_b128 v[144:147], v228 offset:16384
	ds_read_b128 v[148:151], v228 offset:17408
	ds_read_b128 v[152:155], v228 offset:18432
	ds_read_b128 v[194:197], v228 offset:19456
	ds_read_b128 v[198:201], v228 offset:20480
	ds_read_b128 v[202:205], v228 offset:21504
	ds_read_b128 v[206:209], v228 offset:22528
	ds_read_b128 v[210:213], v228 offset:23552
	s_mov_b32 m0, s34
	s_nop 0
	global_load_lds_dwordx4 v188, s[26:27]
	s_mov_b32 m0, s35
	s_mov_b64 s[100:101], s[26:27]
	global_load_lds_dwordx4 v186, s[26:27]
	s_waitcnt lgkmcnt(0)
	s_setprio 1
	s_barrier
	v_mfma_f32_16x16x32_bf16 v[92:95], v[128:131], v[144:147], v[92:95]
	v_mfma_f32_16x16x32_bf16 v[88:91], v[136:139], v[144:147], v[88:91]
	v_mfma_f32_16x16x32_bf16 v[84:87], v[128:131], v[152:155], v[84:87]
	v_mfma_f32_16x16x32_bf16 v[80:83], v[136:139], v[152:155], v[80:83]
	v_mfma_f32_16x16x32_bf16 v[76:79], v[128:131], v[198:201], v[76:79]
	v_mfma_f32_16x16x32_bf16 v[72:75], v[136:139], v[198:201], v[72:75]
	v_mfma_f32_16x16x32_bf16 v[68:71], v[128:131], v[206:209], v[68:71]
	v_mfma_f32_16x16x32_bf16 v[64:67], v[136:139], v[206:209], v[64:67]
	v_mfma_f32_16x16x32_bf16 v[92:95], v[132:135], v[148:151], v[92:95]
	v_mfma_f32_16x16x32_bf16 v[88:91], v[140:143], v[148:151], v[88:91]
	v_mfma_f32_16x16x32_bf16 v[84:87], v[132:135], v[194:197], v[84:87]
	v_mfma_f32_16x16x32_bf16 v[80:83], v[140:143], v[194:197], v[80:83]
	v_mfma_f32_16x16x32_bf16 v[76:79], v[132:135], v[202:205], v[76:79]
	v_mfma_f32_16x16x32_bf16 v[72:75], v[140:143], v[202:205], v[72:75]
	v_mfma_f32_16x16x32_bf16 v[68:71], v[132:135], v[210:213], v[68:71]
	s_setprio 0
	v_mfma_f32_16x16x32_bf16 v[64:67], v[140:143], v[210:213], v[64:67]
	s_barrier
	s_add_u32 s20, s24, 0x90000
	s_addc_u32 s21, s25, 0
	s_add_i32 s43, s44, s31
	s_mov_b32 m0, s43
	s_nop 0
	global_load_lds_dwordx4 v188, s[20:21]
	s_add_i32 m0, s43, 0x2000
	s_nop 0
	global_load_lds_dwordx4 v186, s[20:21]
	s_waitcnt vmcnt(6)
	s_setprio 1
	s_barrier
; #define PG8_STAGE(bufoff, gbase) do { _Pragma("unroll") for (int _i = 0; _i < 2; ++_i) \
;         __builtin_amdgcn_global_load_lds((const unsigned*)((const char*)(gbase) + voff[_i]), (LAS unsigned*)(lds + (bufoff) + ldsw + _i * 8192), 16, 0, 0); } while (0)
; #define PG8_LDA(dst, b, h) do { _Pragma("unroll") for (int m = 0; m < 4; ++m) _Pragma("unroll") for (int k = 0; k < 2; ++k) dst[m][k] = *(const LAS bf16x8*)(lds + PG8_SA(b, h) + aoff + m * 2048 + k * 1024); } while (0)
; #define PG8_LDB(dst, b, h) do { _Pragma("unroll") for (int n = 0; n < 2; ++n) _Pragma("unroll") for (int k = 0; k < 2; ++k) dst[n][k] = *(const LAS bf16x8*)(lds + PG8_SB(b, h) + boff + n * 2048 + k * 1024); } while (0)
; #define PG8_MMA(ai, bj, At, Bt) do { __builtin_amdgcn_s_setprio(1); _Pragma("unroll") for (int m = 0; m < 4; ++m) _Pragma("unroll") for (int n = 0; n < 2; ++n) _Pragma("unroll") for (int k = 0; k < 2; ++k) \
;         acc[ai][bj][m][n] = __builtin_amdgcn_mfma_f32_16x16x32_bf16(Bt[n][k], At[m][k], acc[ai][bj][m][n], 0, 0, 0); __builtin_amdgcn_s_setprio(0); } while (0)
; #define PG8_WAIT_V(n) asm volatile("s_waitcnt vmcnt(" #n ")" ::: "memory")
; #define PG8_WAIT_L(n) asm volatile("s_waitcnt lgkmcnt(" #n ")" ::: "memory")
; #define PG8_BAR __builtin_amdgcn_s_barrier()
; #define PG8_SCHED __builtin_amdgcn_sched_barrier(0)
; template <class Epi>
; DI void gemm_phase(LAS unsigned char* lds, const Gemm g, const StaticOrder& S, const Epi& E) {
;     ...
;             PG8_WAIT_V(6); PG8_BAR; PG8_MMA(1, 1, At, B1); PG8_BAR;
;             PG8_LDB(B0, 1, 0); PG8_SCHED; PG8_LDA(At, 1, 0); PG8_STAGE(PG8_SA(0, 1), a2 + hstep);
;             PG8_WAIT_L(8); PG8_BAR; PG8_WAIT_L(0); PG8_MMA(0, 0, At, B0); PG8_BAR; PG8_SCHED;
;             PG8_LDB(B1, 1, 1); PG8_STAGE(PG8_SB(1, 0), b3);
;             PG8_BAR; PG8_WAIT_L(0); PG8_MMA(0, 1, At, B1); PG8_BAR;
;             PG8_LDA(At, 1, 1); PG8_STAGE(PG8_SA(1, 0), a3);
;             PG8_BAR; PG8_WAIT_L(0); PG8_MMA(1, 0, At, B0); PG8_BAR; PG8_SCHED;
	v_mfma_f32_16x16x32_bf16 v[28:31], v[214:217], v[144:147], v[28:31]
	v_mfma_f32_16x16x32_bf16 v[24:27], v[234:237], v[144:147], v[24:27]
	v_mfma_f32_16x16x32_bf16 v[20:23], v[214:217], v[152:155], v[20:23]
	v_mfma_f32_16x16x32_bf16 v[16:19], v[234:237], v[152:155], v[16:19]
	v_mfma_f32_16x16x32_bf16 v[12:15], v[214:217], v[198:201], v[12:15]
	v_mfma_f32_16x16x32_bf16 v[8:11], v[234:237], v[198:201], v[8:11]
	v_mfma_f32_16x16x32_bf16 v[4:7], v[214:217], v[206:209], v[4:7]
	v_mfma_f32_16x16x32_bf16 v[0:3], v[234:237], v[206:209], v[0:3]
	v_mfma_f32_16x16x32_bf16 v[28:31], v[230:233], v[148:151], v[28:31]
	v_mfma_f32_16x16x32_bf16 v[24:27], v[238:241], v[148:151], v[24:27]
	v_mfma_f32_16x16x32_bf16 v[20:23], v[230:233], v[194:197], v[20:23]
	v_mfma_f32_16x16x32_bf16 v[16:19], v[238:241], v[194:197], v[16:19]
	v_mfma_f32_16x16x32_bf16 v[12:15], v[230:233], v[202:205], v[12:15]
	v_mfma_f32_16x16x32_bf16 v[8:11], v[238:241], v[202:205], v[8:11]
	v_mfma_f32_16x16x32_bf16 v[4:7], v[230:233], v[210:213], v[4:7]
	s_setprio 0
	v_mfma_f32_16x16x32_bf16 v[0:3], v[238:241], v[210:213], v[0:3]
	s_barrier
	ds_read_b128 v[128:131], v226 offset:32768
	ds_read_b128 v[132:135], v226 offset:33792
	ds_read_b128 v[136:139], v226 offset:34816
	ds_read_b128 v[140:143], v226 offset:35840
	ds_read_b128 v[144:147], v228 offset:32768
	ds_read_b128 v[148:151], v228 offset:33792
	ds_read_b128 v[152:155], v228 offset:34816
	ds_read_b128 v[194:197], v228 offset:35840
	ds_read_b128 v[198:201], v228 offset:36864
	ds_read_b128 v[202:205], v228 offset:37888
	ds_read_b128 v[206:209], v228 offset:38912
	ds_read_b128 v[210:213], v228 offset:39936
	s_add_i32 s43, 0, 0x18000
	s_add_u32 s20, s26, 0x90000
	s_addc_u32 s21, s27, 0
	s_mov_b32 m0, s36
	s_nop 0
	global_load_lds_dwordx4 v188, s[20:21]
	s_mov_b32 m0, s37
	s_nop 0
	global_load_lds_dwordx4 v186, s[20:21]
	s_waitcnt lgkmcnt(8)
	s_setprio 1
	s_barrier
	s_waitcnt lgkmcnt(0)
	v_mfma_f32_16x16x32_bf16 v[124:127], v[128:131], v[144:147], v[124:127]
	v_mfma_f32_16x16x32_bf16 v[120:123], v[136:139], v[144:147], v[120:123]
	v_mfma_f32_16x16x32_bf16 v[116:119], v[128:131], v[152:155], v[116:119]
	v_mfma_f32_16x16x32_bf16 v[112:115], v[136:139], v[152:155], v[112:115]
	v_mfma_f32_16x16x32_bf16 v[108:111], v[128:131], v[198:201], v[108:111]
	v_mfma_f32_16x16x32_bf16 v[104:107], v[136:139], v[198:201], v[104:107]
	v_mfma_f32_16x16x32_bf16 v[100:103], v[128:131], v[206:209], v[100:103]
	v_mfma_f32_16x16x32_bf16 v[96:99], v[136:139], v[206:209], v[96:99]
	v_mfma_f32_16x16x32_bf16 v[124:127], v[132:135], v[148:151], v[124:127]
	v_mfma_f32_16x16x32_bf16 v[120:123], v[140:143], v[148:151], v[120:123]
	v_mfma_f32_16x16x32_bf16 v[116:119], v[132:135], v[194:197], v[116:119]
	v_mfma_f32_16x16x32_bf16 v[112:115], v[140:143], v[194:197], v[112:115]
	v_mfma_f32_16x16x32_bf16 v[108:111], v[132:135], v[202:205], v[108:111]
	v_mfma_f32_16x16x32_bf16 v[104:107], v[140:143], v[202:205], v[104:107]
	v_mfma_f32_16x16x32_bf16 v[100:103], v[132:135], v[210:213], v[100:103]
	s_setprio 0
	v_mfma_f32_16x16x32_bf16 v[96:99], v[140:143], v[210:213], v[96:99]
	s_barrier
	ds_read_b128 v[214:217], v226 offset:49152
	ds_read_b128 v[230:233], v226 offset:50176
	ds_read_b128 v[234:237], v226 offset:51200
	ds_read_b128 v[238:241], v226 offset:52224
	s_add_i32 s26, 0, 0x1c000
	s_add_i32 s20, s43, s31
	s_add_i32 m0, s20, 0xffffff80
	s_nop 0
	global_load_lds_dwordx4 v188, s[24:25] offset:128
	s_add_i32 m0, s20, 0x1f80
	s_nop 0
	global_load_lds_dwordx4 v186, s[24:25] offset:128
	s_waitcnt lgkmcnt(0)
	s_setprio 1
	s_barrier
	v_mfma_f32_16x16x32_bf16 v[60:63], v[214:217], v[144:147], v[60:63]
	v_mfma_f32_16x16x32_bf16 v[56:59], v[234:237], v[144:147], v[56:59]
	v_mfma_f32_16x16x32_bf16 v[52:55], v[214:217], v[152:155], v[52:55]
	v_mfma_f32_16x16x32_bf16 v[48:51], v[234:237], v[152:155], v[48:51]
	v_mfma_f32_16x16x32_bf16 v[44:47], v[214:217], v[198:201], v[44:47]
	v_mfma_f32_16x16x32_bf16 v[40:43], v[234:237], v[198:201], v[40:43]
	v_mfma_f32_16x16x32_bf16 v[36:39], v[214:217], v[206:209], v[36:39]
	v_mfma_f32_16x16x32_bf16 v[32:35], v[234:237], v[206:209], v[32:35]
	v_mfma_f32_16x16x32_bf16 v[60:63], v[230:233], v[148:151], v[60:63]
	v_mfma_f32_16x16x32_bf16 v[56:59], v[238:241], v[148:151], v[56:59]
	v_mfma_f32_16x16x32_bf16 v[52:55], v[230:233], v[194:197], v[52:55]
	v_mfma_f32_16x16x32_bf16 v[48:51], v[238:241], v[194:197], v[48:51]
	v_mfma_f32_16x16x32_bf16 v[44:47], v[230:233], v[202:205], v[44:47]
	v_mfma_f32_16x16x32_bf16 v[40:43], v[238:241], v[202:205], v[40:43]
	v_mfma_f32_16x16x32_bf16 v[36:39], v[230:233], v[210:213], v[36:39]
	s_setprio 0
	v_mfma_f32_16x16x32_bf16 v[32:35], v[238:241], v[210:213], v[32:35]
	s_barrier
	ds_read_b128 v[144:147], v228 offset:49152
	ds_read_b128 v[148:151], v228 offset:50176
	ds_read_b128 v[152:155], v228 offset:51200
	ds_read_b128 v[194:197], v228 offset:52224
	ds_read_b128 v[198:201], v228 offset:53248
	ds_read_b128 v[202:205], v228 offset:54272
	ds_read_b128 v[206:209], v228 offset:55296
	ds_read_b128 v[210:213], v228 offset:56320
	s_add_i32 m0, s38, 0xffffff80
	s_nop 0
	global_load_lds_dwordx4 v188, s[100:101] offset:128
	s_add_i32 m0, s39, 0xffffff80
	s_nop 0
	global_load_lds_dwordx4 v186, s[100:101] offset:128
	s_waitcnt lgkmcnt(0)
	s_setprio 1
	s_barrier
; #define PG8_WAIT_V(n) asm volatile("s_waitcnt vmcnt(" #n ")" ::: "memory")
; #define PG8_WAIT_L(n) asm volatile("s_waitcnt lgkmcnt(" #n ")" ::: "memory")
; template <class Epi>
; DI void gemm_phase(LAS unsigned char* lds, const Gemm g, const StaticOrder& S, const Epi& E) {
;     ...
;             PG8_BAR; PG8_WAIT_L(0); PG8_MMA(1, 0, At, B0); PG8_BAR; PG8_SCHED;
;             PG8_STAGE(PG8_SB(1, 1), b3 + hstep);
;             PG8_WAIT_V(6); PG8_BAR; PG8_MMA(1, 1, At, B1); PG8_BAR;
;     template <bool LN, int BJ, int LO, int HI> DI void batch(const f32x4 (&acc)[2][2][4][2], unsigned row0, unsigned col0, const f32x4 (&gv)[2], const f32x4 (&bv)[2]) const {
;         f32x4 r[HI - LO]; float mean[(HI - LO) / 2], rstd[(HI - LO) / 2];
; #pragma unroll
;         for (int i = LO; i < HI; ++i) { const int ai = i >> 3, m = (i >> 1) & 3, n = i & 1; const unsigned row = row0 + ai * HALF + m * 16;
;             if (n == 0) { mean[(i - LO) >> 1] = 0.f; rstd[(i - LO) >> 1] = 1.f;
;                 if (LN) { const float2 st = *(const float2*)(stats + row * 2u); mean[(i - LO) >> 1] = st.x; rstd[(i - LO) >> 1] = st.y; } }
;             r[i - LO] = *(const f32x4*)(src + (row * (unsigned)DM + col0 + BJ * HALF + n * 16)); }
; #pragma unroll
;         for (int i = LO; i < HI; ++i) { const int ai = i >> 3, m = (i >> 1) & 3, n = i & 1; const unsigned row = row0 + ai * HALF + m * 16;
;             *(f32x4*)(Y + (row * (unsigned)DM + col0 + BJ * HALF + n * 16)) = acc[ai][BJ][m][n] + ((r[i - LO] - mean[(i - LO) >> 1]) * rstd[(i - LO) >> 1]) * gv[n] + bv[n]; }
;         __builtin_amdgcn_sched_barrier(0);
;     }
;     template <bool LN, int BJ> DI void load_gb(unsigned col0, f32x4 (&gv)[2], f32x4 (&bv)[2]) const {
; #pragma unroll
;         for (int n = 0; n < 2; ++n) {
;             if (LN) { gv[n] = *(const f32x4*)(gam + col0 + BJ * HALF + n * 16) * ALPHA; bv[n] = *(const f32x4*)(bet + col0 + BJ * HALF + n * 16) * ALPHA; }
;             else { gv[n] = (f32x4){ALPHA, ALPHA, ALPHA, ALPHA}; bv[n] = (f32x4){0.f, 0.f, 0.f, 0.f}; }
;         }
;     }
;     template <bool LN> DI void run(const f32x4 (&acc)[2][2][4][2], const Unit& u, int wr, int wc, int fr, int fq) const {
;         const unsigned row0 = u.pm * BM + wr * 64 + fr, col0 = u.pn * BM + wc * 32 + 4 * fq;
;         f32x4 gv[2], bv[2];
;         load_gb<LN, 0>(col0, gv, bv);
;         batch<LN, 0, 0, 4>(acc, row0, col0, gv, bv);
	v_mfma_f32_16x16x32_bf16 v[92:95], v[128:131], v[144:147], v[92:95]
	v_mfma_f32_16x16x32_bf16 v[88:91], v[136:139], v[144:147], v[88:91]
	v_mfma_f32_16x16x32_bf16 v[84:87], v[128:131], v[152:155], v[84:87]
	v_mfma_f32_16x16x32_bf16 v[80:83], v[136:139], v[152:155], v[80:83]
	v_mfma_f32_16x16x32_bf16 v[76:79], v[128:131], v[198:201], v[76:79]
	v_mfma_f32_16x16x32_bf16 v[72:75], v[136:139], v[198:201], v[72:75]
	v_mfma_f32_16x16x32_bf16 v[68:71], v[128:131], v[206:209], v[68:71]
	v_mfma_f32_16x16x32_bf16 v[64:67], v[136:139], v[206:209], v[64:67]
	v_mfma_f32_16x16x32_bf16 v[92:95], v[132:135], v[148:151], v[92:95]
	v_mfma_f32_16x16x32_bf16 v[88:91], v[140:143], v[148:151], v[88:91]
	v_mfma_f32_16x16x32_bf16 v[84:87], v[132:135], v[194:197], v[84:87]
	v_mfma_f32_16x16x32_bf16 v[80:83], v[140:143], v[194:197], v[80:83]
	v_mfma_f32_16x16x32_bf16 v[76:79], v[132:135], v[202:205], v[76:79]
	v_mfma_f32_16x16x32_bf16 v[72:75], v[140:143], v[202:205], v[72:75]
	v_mfma_f32_16x16x32_bf16 v[68:71], v[132:135], v[210:213], v[68:71]
	s_setprio 0
	v_mfma_f32_16x16x32_bf16 v[64:67], v[140:143], v[210:213], v[64:67]
	s_barrier
	s_add_u32 s20, s24, 0x90080
	s_addc_u32 s21, s25, 0
	s_add_i32 s24, s26, s31
	s_mov_b32 m0, s24
	s_nop 0
	global_load_lds_dwordx4 v188, s[20:21]
	s_add_i32 m0, s24, 0x2000
	s_nop 0
	global_load_lds_dwordx4 v186, s[20:21]
	s_waitcnt vmcnt(6)
	s_setprio 1
	s_barrier
	v_mfma_f32_16x16x32_bf16 v[28:31], v[214:217], v[144:147], v[28:31]
	v_mfma_f32_16x16x32_bf16 v[24:27], v[234:237], v[144:147], v[24:27]
	v_mfma_f32_16x16x32_bf16 v[20:23], v[214:217], v[152:155], v[20:23]
	v_mfma_f32_16x16x32_bf16 v[16:19], v[234:237], v[152:155], v[16:19]
	v_mfma_f32_16x16x32_bf16 v[12:15], v[214:217], v[198:201], v[12:15]
	v_mfma_f32_16x16x32_bf16 v[8:11], v[234:237], v[198:201], v[8:11]
	v_mfma_f32_16x16x32_bf16 v[4:7], v[214:217], v[206:209], v[4:7]
	v_mfma_f32_16x16x32_bf16 v[0:3], v[234:237], v[206:209], v[0:3]
	v_mfma_f32_16x16x32_bf16 v[28:31], v[230:233], v[148:151], v[28:31]
	s_add_i32 s33, s33, 2
	v_mfma_f32_16x16x32_bf16 v[24:27], v[238:241], v[148:151], v[24:27]
	s_add_u32 s4, s4, 0x100
	v_mfma_f32_16x16x32_bf16 v[20:23], v[230:233], v[194:197], v[20:23]
	s_addc_u32 s5, s5, 0
	v_mfma_f32_16x16x32_bf16 v[16:19], v[238:241], v[194:197], v[16:19]
	s_cmp_gt_u32 s33, 33
	v_mfma_f32_16x16x32_bf16 v[12:15], v[230:233], v[202:205], v[12:15]
	s_mov_b64 s[20:21], s[22:23]
	v_mfma_f32_16x16x32_bf16 v[8:11], v[238:241], v[202:205], v[8:11]
	v_mfma_f32_16x16x32_bf16 v[4:7], v[230:233], v[210:213], v[4:7]
	s_setprio 0
	v_mfma_f32_16x16x32_bf16 v[0:3], v[238:241], v[210:213], v[0:3]
	s_barrier
	s_cbranch_scc0 .LBB0_77
	v_lshl_add_u32 v206, s3, 8, v225
	v_lshl_or_b32 v158, s2, 8, v227
	v_lshlrev_b32_e32 v232, 11, v206
	s_andn2_b64 vcc, exec, s[14:15]
	v_or_b32_e32 v231, 16, v158
	v_add_u32_e32 v194, v232, v158
	v_or_b32_e32 v230, 0x80, v158
	v_or_b32_e32 v229, 0x90, v158
	s_cbranch_vccnz .LBB0_80
	v_lshlrev_b64 v[132:133], 2, v[158:159]
	v_lshl_add_u64 v[140:141], s[16:17], 0, v[132:133]
	global_load_dwordx4 v[128:131], v[140:141], off
	v_lshl_add_u64 v[142:143], s[18:19], 0, v[132:133]
	v_readlane_b32 s2, v253, 8
	v_mov_b32_e32 v195, v159
	v_lshlrev_b32_e32 v136, 1, v206
	v_mov_b32_e32 v137, v159
	v_readlane_b32 s3, v253, 9
	v_lshlrev_b64 v[212:213], 2, v[194:195]
	v_add_u32_e32 v146, v232, v231
	v_lshl_add_u64 v[144:145], v[136:137], 2, s[2:3]
	v_lshl_add_u64 v[136:137], s[88:89], 0, v[212:213]
	v_mov_b32_e32 v147, v159
	v_lshl_add_u64 v[146:147], v[146:147], 2, s[88:89]
	v_or_b32_e32 v195, 16, v206
	v_mov_b32_e32 v201, v159
	v_mov_b32_e32 v209, v159
	v_lshl_add_u64 v[212:213], s[90:91], 0, v[212:213]
	s_waitcnt vmcnt(0)
	v_pk_mul_f32 v[152:153], v[130:131], s[78:79] op_sel_hi:[1,0]
	v_pk_mul_f32 v[154:155], v[128:129], s[78:79] op_sel_hi:[1,0]
	global_load_dwordx4 v[132:135], v[142:143], off
	global_load_dwordx4 v[128:131], v[140:141], off offset:64
	global_load_dwordx2 v[204:205], v[144:145], off
	global_load_dwordx4 v[196:199], v[146:147], off
	v_lshlrev_b32_e32 v146, 1, v195
	global_load_dwordx4 v[136:139], v[136:137], off
	v_lshlrev_b32_e32 v195, 11, v195
	v_mov_b32_e32 v147, v159
	v_add_u32_e32 v200, v195, v158
	v_lshl_add_u64 v[146:147], v[146:147], 2, s[2:3]
	v_lshl_add_u64 v[200:201], v[200:201], 2, s[88:89]
	global_load_dwordx2 v[214:215], v[146:147], off
	v_add_u32_e32 v208, v195, v231
	global_load_dwordx4 v[200:203], v[200:201], off
	v_lshl_add_u64 v[208:209], v[208:209], 2, s[88:89]
	global_load_dwordx4 v[208:211], v[208:209], off
	s_waitcnt vmcnt(0)
	v_pk_mul_f32 v[148:149], v[130:131], s[78:79] op_sel_hi:[1,0]
	v_pk_mul_f32 v[150:151], v[128:129], s[78:79] op_sel_hi:[1,0]
	global_load_dwordx4 v[128:131], v[142:143], off offset:64
	v_sub_f32_e32 v137, v137, v204
	v_sub_f32_e32 v136, v136, v204
	v_sub_f32_e32 v139, v139, v204
	v_sub_f32_e32 v138, v138, v204
	v_pk_mul_f32 v[138:139], v[204:205], v[138:139] op_sel:[1,0]
	v_pk_mul_f32 v[136:137], v[204:205], v[136:137] op_sel:[1,0]
	v_pk_fma_f32 v[138:139], v[152:153], v[138:139], v[126:127]
	v_pk_fma_f32 v[136:137], v[154:155], v[136:137], v[124:125]
	v_pk_fma_f32 v[138:139], v[134:135], s[78:79], v[138:139] op_sel_hi:[1,0,1]
	v_pk_fma_f32 v[136:137], v[132:133], s[78:79], v[136:137] op_sel_hi:[1,0,1]
	global_store_dwordx4 v[212:213], v[136:139], off
	s_nop 1
	v_sub_f32_e32 v137, v197, v204
	v_sub_f32_e32 v136, v196, v204
	v_sub_f32_e32 v139, v199, v204
	v_sub_f32_e32 v138, v198, v204
	v_pk_mul_f32 v[138:139], v[204:205], v[138:139] op_sel:[1,0]
	v_pk_mul_f32 v[136:137], v[204:205], v[136:137] op_sel:[1,0]
	v_pk_fma_f32 v[138:139], v[148:149], v[138:139], v[122:123]
	v_pk_fma_f32 v[136:137], v[150:151], v[136:137], v[120:121]
	v_or_b32_e32 v196, 16, v194
	v_mov_b32_e32 v197, v159
	v_lshl_add_u64 v[196:197], v[196:197], 2, s[90:91]
	s_waitcnt vmcnt(0)
;     template <bool LN, int BJ, int LO, int HI> DI void batch(const f32x4 (&acc)[2][2][4][2], unsigned row0, unsigned col0, const f32x4 (&gv)[2], const f32x4 (&bv)[2]) const {
;         f32x4 r[HI - LO]; float mean[(HI - LO) / 2], rstd[(HI - LO) / 2];
; #pragma unroll
;         for (int i = LO; i < HI; ++i) { const int ai = i >> 3, m = (i >> 1) & 3, n = i & 1; const unsigned row = row0 + ai * HALF + m * 16;
;             if (n == 0) { mean[(i - LO) >> 1] = 0.f; rstd[(i - LO) >> 1] = 1.f;
;                 if (LN) { const float2 st = *(const float2*)(stats + row * 2u); mean[(i - LO) >> 1] = st.x; rstd[(i - LO) >> 1] = st.y; } }
;             r[i - LO] = *(const f32x4*)(src + (row * (unsigned)DM + col0 + BJ * HALF + n * 16)); }
; #pragma unroll
;         for (int i = LO; i < HI; ++i) { const int ai = i >> 3, m = (i >> 1) & 3, n = i & 1; const unsigned row = row0 + ai * HALF + m * 16;
;             *(f32x4*)(Y + (row * (unsigned)DM + col0 + BJ * HALF + n * 16)) = acc[ai][BJ][m][n] + ((r[i - LO] - mean[(i - LO) >> 1]) * rstd[(i - LO) >> 1]) * gv[n] + bv[n]; }
	v_pk_fma_f32 v[138:139], v[130:131], s[78:79], v[138:139] op_sel_hi:[1,0,1]
	v_pk_fma_f32 v[136:137], v[128:129], s[78:79], v[136:137] op_sel_hi:[1,0,1]
	global_store_dwordx4 v[196:197], v[136:139], off
	v_add_u32_e32 v196, 0x8000, v194
	v_mov_b32_e32 v197, v159
	v_sub_f32_e32 v137, v201, v214
	v_sub_f32_e32 v136, v200, v214
	v_sub_f32_e32 v139, v203, v214
	v_sub_f32_e32 v138, v202, v214
	v_pk_mul_f32 v[138:139], v[214:215], v[138:139] op_sel:[1,0]
	v_pk_mul_f32 v[136:137], v[214:215], v[136:137] op_sel:[1,0]
	v_pk_fma_f32 v[138:139], v[152:153], v[138:139], v[118:119]
	v_pk_fma_f32 v[136:137], v[154:155], v[136:137], v[116:117]
	v_pk_fma_f32 v[138:139], v[134:135], s[78:79], v[138:139] op_sel_hi:[1,0,1]
	v_pk_fma_f32 v[136:137], v[132:133], s[78:79], v[136:137] op_sel_hi:[1,0,1]
	v_lshl_add_u64 v[196:197], v[196:197], 2, s[90:91]
	global_store_dwordx4 v[196:197], v[136:139], off
	v_add_u32_e32 v196, 0x8010, v194
	v_mov_b32_e32 v197, v159
	v_sub_f32_e32 v137, v209, v214
	v_sub_f32_e32 v136, v208, v214
	v_sub_f32_e32 v139, v211, v214
	v_sub_f32_e32 v138, v210, v214
	v_pk_mul_f32 v[138:139], v[214:215], v[138:139] op_sel:[1,0]
	v_pk_mul_f32 v[136:137], v[214:215], v[136:137] op_sel:[1,0]
	v_pk_fma_f32 v[138:139], v[148:149], v[138:139], v[114:115]
	v_pk_fma_f32 v[136:137], v[150:151], v[136:137], v[112:113]
	v_pk_fma_f32 v[138:139], v[130:131], s[78:79], v[138:139] op_sel_hi:[1,0,1]
	v_pk_fma_f32 v[136:137], v[128:129], s[78:79], v[136:137] op_sel_hi:[1,0,1]
	v_lshl_add_u64 v[196:197], v[196:197], 2, s[90:91]
	global_store_dwordx4 v[196:197], v[136:139], off
	s_nop 1
	v_or_b32_e32 v138, 32, v206
	v_lshlrev_b32_e32 v136, 1, v138
	v_mov_b32_e32 v137, v159
	v_lshlrev_b32_e32 v236, 11, v138
	v_lshl_add_u64 v[200:201], v[136:137], 2, s[2:3]
	v_add_u32_e32 v136, v236, v158
	v_lshl_add_u64 v[136:137], v[136:137], 2, s[88:89]
	global_load_dwordx2 v[204:205], v[200:201], off
	v_add_u32_e32 v196, v236, v231
	global_load_dwordx4 v[136:139], v[136:137], off
	v_mov_b32_e32 v197, v159
	v_lshl_add_u64 v[196:197], v[196:197], 2, s[88:89]
	global_load_dwordx4 v[196:199], v[196:197], off
	v_or_b32_e32 v207, 48, v206
	v_lshlrev_b32_e32 v235, 11, v207
	v_lshlrev_b32_e32 v202, 1, v207
	v_mov_b32_e32 v203, v159
	v_add_u32_e32 v208, v235, v158
	v_mov_b32_e32 v209, v159
	v_lshl_add_u64 v[202:203], v[202:203], 2, s[2:3]
	v_lshl_add_u64 v[208:209], v[208:209], 2, s[88:89]
	global_load_dwordx2 v[216:217], v[202:203], off
	v_add_u32_e32 v212, v235, v231
	global_load_dwordx4 v[208:211], v[208:209], off
	v_mov_b32_e32 v213, v159
	v_lshl_add_u64 v[212:213], v[212:213], 2, s[88:89]
	global_load_dwordx4 v[212:215], v[212:213], off
	v_add_u32_e32 v218, 0x10000, v194
	v_mov_b32_e32 v219, v159
	v_lshl_add_u64 v[218:219], v[218:219], 2, s[90:91]
	s_waitcnt vmcnt(0)
	v_sub_f32_e32 v137, v137, v204
	v_sub_f32_e32 v136, v136, v204
	v_sub_f32_e32 v139, v139, v204
	v_sub_f32_e32 v138, v138, v204
	v_pk_mul_f32 v[138:139], v[204:205], v[138:139] op_sel:[1,0]
	v_pk_mul_f32 v[136:137], v[204:205], v[136:137] op_sel:[1,0]
	v_pk_fma_f32 v[138:139], v[152:153], v[138:139], v[110:111]
	v_pk_fma_f32 v[136:137], v[154:155], v[136:137], v[108:109]
	v_pk_fma_f32 v[138:139], v[134:135], s[78:79], v[138:139] op_sel_hi:[1,0,1]
	v_pk_fma_f32 v[136:137], v[132:133], s[78:79], v[136:137] op_sel_hi:[1,0,1]
	global_store_dwordx4 v[218:219], v[136:139], off
	s_nop 1
	v_sub_f32_e32 v137, v197, v204
	v_sub_f32_e32 v136, v196, v204
	v_sub_f32_e32 v139, v199, v204
	v_sub_f32_e32 v138, v198, v204
	v_pk_mul_f32 v[138:139], v[204:205], v[138:139] op_sel:[1,0]
	v_pk_mul_f32 v[136:137], v[204:205], v[136:137] op_sel:[1,0]
	v_pk_fma_f32 v[138:139], v[148:149], v[138:139], v[106:107]
	v_pk_fma_f32 v[136:137], v[150:151], v[136:137], v[104:105]
	v_add_u32_e32 v196, 0x10010, v194
	v_mov_b32_e32 v197, v159
	v_pk_fma_f32 v[138:139], v[130:131], s[78:79], v[138:139] op_sel_hi:[1,0,1]
	v_pk_fma_f32 v[136:137], v[128:129], s[78:79], v[136:137] op_sel_hi:[1,0,1]
	v_lshl_add_u64 v[196:197], v[196:197], 2, s[90:91]
	global_store_dwordx4 v[196:197], v[136:139], off
	v_add_u32_e32 v196, 0x18000, v194
	v_mov_b32_e32 v197, v159
	v_sub_f32_e32 v137, v209, v216
	v_sub_f32_e32 v136, v208, v216
	v_sub_f32_e32 v139, v211, v216
	v_sub_f32_e32 v138, v210, v216
	v_pk_mul_f32 v[138:139], v[216:217], v[138:139] op_sel:[1,0]
	v_pk_mul_f32 v[136:137], v[216:217], v[136:137] op_sel:[1,0]
	v_pk_fma_f32 v[138:139], v[152:153], v[138:139], v[102:103]
	v_pk_fma_f32 v[136:137], v[154:155], v[136:137], v[100:101]
	v_pk_fma_f32 v[138:139], v[134:135], s[78:79], v[138:139] op_sel_hi:[1,0,1]
	v_pk_fma_f32 v[136:137], v[132:133], s[78:79], v[136:137] op_sel_hi:[1,0,1]
	v_lshl_add_u64 v[196:197], v[196:197], 2, s[90:91]
	global_store_dwordx4 v[196:197], v[136:139], off
	v_add_u32_e32 v196, 0x18010, v194
	v_mov_b32_e32 v197, v159
	v_sub_f32_e32 v137, v213, v216
	v_sub_f32_e32 v136, v212, v216
	v_sub_f32_e32 v139, v215, v216
	v_sub_f32_e32 v138, v214, v216
	v_pk_mul_f32 v[138:139], v[216:217], v[138:139] op_sel:[1,0]
	v_pk_mul_f32 v[136:137], v[216:217], v[136:137] op_sel:[1,0]
	v_pk_fma_f32 v[138:139], v[148:149], v[138:139], v[98:99]
	v_pk_fma_f32 v[136:137], v[150:151], v[136:137], v[96:97]
	v_pk_fma_f32 v[138:139], v[130:131], s[78:79], v[138:139] op_sel_hi:[1,0,1]
	v_pk_fma_f32 v[136:137], v[128:129], s[78:79], v[136:137] op_sel_hi:[1,0,1]
	v_lshl_add_u64 v[196:197], v[196:197], 2, s[90:91]
	global_store_dwordx4 v[196:197], v[136:139], off
	s_nop 1
	v_add_u32_e32 v138, 0x80, v206
	v_lshlrev_b32_e32 v136, 1, v138
	v_mov_b32_e32 v137, v159
	v_lshlrev_b32_e32 v233, 11, v138
	v_lshl_add_u64 v[196:197], v[136:137], 2, s[2:3]
	v_add_u32_e32 v136, v233, v158
	v_lshl_add_u64 v[136:137], v[136:137], 2, s[88:89]
	global_load_dwordx2 v[204:205], v[196:197], off
	v_add_u32_e32 v198, v233, v231
	global_load_dwordx4 v[136:139], v[136:137], off
	v_mov_b32_e32 v199, v159
	v_add_u32_e32 v207, 0x90, v206
	v_lshl_add_u64 v[198:199], v[198:199], 2, s[88:89]
	v_lshlrev_b32_e32 v234, 11, v207
	global_load_dwordx4 v[208:211], v[198:199], off
	v_add_u32_e32 v212, v234, v158
	v_mov_b32_e32 v213, v159
	v_lshl_add_u64 v[212:213], v[212:213], 2, s[88:89]
	global_load_dwordx4 v[212:215], v[212:213], off
	v_lshlrev_b32_e32 v198, 1, v207
	v_mov_b32_e32 v199, v159
	v_lshl_add_u64 v[198:199], v[198:199], 2, s[2:3]
	global_load_dwordx2 v[220:221], v[198:199], off
	v_add_u32_e32 v216, v234, v231
	v_mov_b32_e32 v217, v159
	v_lshl_add_u64 v[216:217], v[216:217], 2, s[88:89]
	global_load_dwordx4 v[216:219], v[216:217], off
	v_add_u32_e32 v238, 0x40000, v194
	v_mov_b32_e32 v239, v159
	v_lshl_add_u64 v[238:239], v[238:239], 2, s[90:91]
	s_waitcnt vmcnt(0)
;     template <bool LN, int BJ, int LO, int HI> DI void batch(const f32x4 (&acc)[2][2][4][2], unsigned row0, unsigned col0, const f32x4 (&gv)[2], const f32x4 (&bv)[2]) const {
;         f32x4 r[HI - LO]; float mean[(HI - LO) / 2], rstd[(HI - LO) / 2];
; #pragma unroll
;         for (int i = LO; i < HI; ++i) { const int ai = i >> 3, m = (i >> 1) & 3, n = i & 1; const unsigned row = row0 + ai * HALF + m * 16;
;             if (n == 0) { mean[(i - LO) >> 1] = 0.f; rstd[(i - LO) >> 1] = 1.f;
;                 if (LN) { const float2 st = *(const float2*)(stats + row * 2u); mean[(i - LO) >> 1] = st.x; rstd[(i - LO) >> 1] = st.y; } }
;             r[i - LO] = *(const f32x4*)(src + (row * (unsigned)DM + col0 + BJ * HALF + n * 16)); }
; #pragma unroll
;         for (int i = LO; i < HI; ++i) { const int ai = i >> 3, m = (i >> 1) & 3, n = i & 1; const unsigned row = row0 + ai * HALF + m * 16;
;             *(f32x4*)(Y + (row * (unsigned)DM + col0 + BJ * HALF + n * 16)) = acc[ai][BJ][m][n] + ((r[i - LO] - mean[(i - LO) >> 1]) * rstd[(i - LO) >> 1]) * gv[n] + bv[n]; }
;         __builtin_amdgcn_sched_barrier(0);
;     }
;     template <bool LN, int BJ> DI void load_gb(unsigned col0, f32x4 (&gv)[2], f32x4 (&bv)[2]) const {
; #pragma unroll
;         for (int n = 0; n < 2; ++n) {
;             if (LN) { gv[n] = *(const f32x4*)(gam + col0 + BJ * HALF + n * 16) * ALPHA; bv[n] = *(const f32x4*)(bet + col0 + BJ * HALF + n * 16) * ALPHA; }
	v_sub_f32_e32 v137, v137, v204
	v_sub_f32_e32 v136, v136, v204
	v_sub_f32_e32 v139, v139, v204
	v_sub_f32_e32 v138, v138, v204
	v_pk_mul_f32 v[138:139], v[204:205], v[138:139] op_sel:[1,0]
	v_pk_mul_f32 v[136:137], v[204:205], v[136:137] op_sel:[1,0]
	v_pk_fma_f32 v[138:139], v[152:153], v[138:139], v[94:95]
	v_pk_fma_f32 v[136:137], v[154:155], v[136:137], v[92:93]
	v_pk_fma_f32 v[138:139], v[134:135], s[78:79], v[138:139] op_sel_hi:[1,0,1]
	v_pk_fma_f32 v[136:137], v[132:133], s[78:79], v[136:137] op_sel_hi:[1,0,1]
	global_store_dwordx4 v[238:239], v[136:139], off
	s_nop 1
	v_sub_f32_e32 v137, v209, v204
	v_sub_f32_e32 v136, v208, v204
	v_sub_f32_e32 v139, v211, v204
	v_sub_f32_e32 v138, v210, v204
	v_pk_mul_f32 v[138:139], v[204:205], v[138:139] op_sel:[1,0]
	v_pk_mul_f32 v[136:137], v[204:205], v[136:137] op_sel:[1,0]
	v_pk_fma_f32 v[138:139], v[148:149], v[138:139], v[90:91]
	v_pk_fma_f32 v[136:137], v[150:151], v[136:137], v[88:89]
	v_add_u32_e32 v204, 0x40010, v194
	v_mov_b32_e32 v205, v159
	v_pk_fma_f32 v[138:139], v[130:131], s[78:79], v[138:139] op_sel_hi:[1,0,1]
	v_pk_fma_f32 v[136:137], v[128:129], s[78:79], v[136:137] op_sel_hi:[1,0,1]
	v_lshl_add_u64 v[204:205], v[204:205], 2, s[90:91]
	global_store_dwordx4 v[204:205], v[136:139], off
	v_add_u32_e32 v204, 0x48000, v194
	v_mov_b32_e32 v205, v159
	v_sub_f32_e32 v137, v213, v220
	v_sub_f32_e32 v136, v212, v220
	v_sub_f32_e32 v139, v215, v220
	v_sub_f32_e32 v138, v214, v220
	v_pk_mul_f32 v[138:139], v[220:221], v[138:139] op_sel:[1,0]
	v_pk_mul_f32 v[136:137], v[220:221], v[136:137] op_sel:[1,0]
	v_pk_fma_f32 v[138:139], v[152:153], v[138:139], v[86:87]
	v_pk_fma_f32 v[136:137], v[154:155], v[136:137], v[84:85]
	v_pk_fma_f32 v[138:139], v[134:135], s[78:79], v[138:139] op_sel_hi:[1,0,1]
	v_pk_fma_f32 v[136:137], v[132:133], s[78:79], v[136:137] op_sel_hi:[1,0,1]
	v_lshl_add_u64 v[204:205], v[204:205], 2, s[90:91]
	global_store_dwordx4 v[204:205], v[136:139], off
	v_add_u32_e32 v204, 0x48010, v194
	v_mov_b32_e32 v205, v159
	v_sub_f32_e32 v137, v217, v220
	v_sub_f32_e32 v136, v216, v220
	v_sub_f32_e32 v139, v219, v220
	v_sub_f32_e32 v138, v218, v220
	v_pk_mul_f32 v[138:139], v[220:221], v[138:139] op_sel:[1,0]
	v_pk_mul_f32 v[136:137], v[220:221], v[136:137] op_sel:[1,0]
	v_pk_fma_f32 v[138:139], v[148:149], v[138:139], v[82:83]
	v_pk_fma_f32 v[136:137], v[150:151], v[136:137], v[80:81]
	v_pk_fma_f32 v[138:139], v[130:131], s[78:79], v[138:139] op_sel_hi:[1,0,1]
	v_pk_fma_f32 v[136:137], v[128:129], s[78:79], v[136:137] op_sel_hi:[1,0,1]
	v_lshl_add_u64 v[204:205], v[204:205], 2, s[90:91]
	global_store_dwordx4 v[204:205], v[136:139], off
	s_nop 1
	v_add_u32_e32 v138, 0xa0, v206
	v_lshlrev_b32_e32 v136, 1, v138
	v_mov_b32_e32 v137, v159
	v_lshlrev_b32_e32 v237, 11, v138
	v_lshl_add_u64 v[204:205], v[136:137], 2, s[2:3]
	v_add_u32_e32 v136, v237, v158
	v_lshl_add_u64 v[136:137], v[136:137], 2, s[88:89]
	global_load_dwordx2 v[220:221], v[204:205], off
	v_add_u32_e32 v208, v237, v231
	global_load_dwordx4 v[136:139], v[136:137], off
	v_mov_b32_e32 v209, v159
	v_lshl_add_u64 v[208:209], v[208:209], 2, s[88:89]
	global_load_dwordx4 v[212:215], v[208:209], off
	v_add_u32_e32 v208, 0xb0, v206
	v_lshlrev_b32_e32 v206, 1, v208
	v_mov_b32_e32 v207, v159
	v_lshlrev_b32_e32 v238, 11, v208
	v_lshl_add_u64 v[210:211], v[206:207], 2, s[2:3]
	v_add_u32_e32 v206, v238, v158
	v_lshl_add_u64 v[206:207], v[206:207], 2, s[88:89]
	global_load_dwordx2 v[240:241], v[210:211], off
	v_add_u32_e32 v216, v238, v231
	global_load_dwordx4 v[206:209], v[206:207], off
	v_mov_b32_e32 v217, v159
	v_lshl_add_u64 v[216:217], v[216:217], 2, s[88:89]
	global_load_dwordx4 v[216:219], v[216:217], off
	v_add_u32_e32 v242, 0x50000, v194
	v_mov_b32_e32 v243, v159
	v_lshl_add_u64 v[242:243], v[242:243], 2, s[90:91]
	s_waitcnt vmcnt(0)
	v_sub_f32_e32 v137, v137, v220
	v_sub_f32_e32 v136, v136, v220
	v_sub_f32_e32 v139, v139, v220
	v_sub_f32_e32 v138, v138, v220
	v_pk_mul_f32 v[138:139], v[220:221], v[138:139] op_sel:[1,0]
	v_pk_mul_f32 v[136:137], v[220:221], v[136:137] op_sel:[1,0]
	v_pk_fma_f32 v[138:139], v[152:153], v[138:139], v[78:79]
	v_pk_fma_f32 v[136:137], v[154:155], v[136:137], v[76:77]
	v_pk_fma_f32 v[138:139], v[134:135], s[78:79], v[138:139] op_sel_hi:[1,0,1]
	v_pk_fma_f32 v[136:137], v[132:133], s[78:79], v[136:137] op_sel_hi:[1,0,1]
	global_store_dwordx4 v[242:243], v[136:139], off
	s_nop 1
	v_sub_f32_e32 v137, v213, v220
	v_sub_f32_e32 v136, v212, v220
	v_sub_f32_e32 v139, v215, v220
	v_sub_f32_e32 v138, v214, v220
	v_pk_mul_f32 v[138:139], v[220:221], v[138:139] op_sel:[1,0]
	v_pk_mul_f32 v[136:137], v[220:221], v[136:137] op_sel:[1,0]
	v_pk_fma_f32 v[138:139], v[148:149], v[138:139], v[74:75]
	v_pk_fma_f32 v[136:137], v[150:151], v[136:137], v[72:73]
	v_add_u32_e32 v212, 0x50010, v194
	v_mov_b32_e32 v213, v159
	v_pk_fma_f32 v[138:139], v[130:131], s[78:79], v[138:139] op_sel_hi:[1,0,1]
	v_pk_fma_f32 v[136:137], v[128:129], s[78:79], v[136:137] op_sel_hi:[1,0,1]
	v_lshl_add_u64 v[212:213], v[212:213], 2, s[90:91]
	global_store_dwordx4 v[212:213], v[136:139], off
	s_nop 1
	v_sub_f32_e32 v137, v207, v240
	v_sub_f32_e32 v136, v206, v240
	v_sub_f32_e32 v139, v209, v240
	v_sub_f32_e32 v138, v208, v240
	v_pk_mul_f32 v[136:137], v[240:241], v[136:137] op_sel:[1,0]
	v_pk_mul_f32 v[138:139], v[240:241], v[138:139] op_sel:[1,0]
	v_pk_fma_f32 v[136:137], v[154:155], v[136:137], v[68:69]
	v_pk_fma_f32 v[138:139], v[152:153], v[138:139], v[70:71]
	v_pk_fma_f32 v[132:133], v[132:133], s[78:79], v[136:137] op_sel_hi:[1,0,1]
	v_add_u32_e32 v136, 0x58000, v194
	v_mov_b32_e32 v137, v159
	v_pk_fma_f32 v[134:135], v[134:135], s[78:79], v[138:139] op_sel_hi:[1,0,1]
	v_lshl_add_u64 v[136:137], v[136:137], 2, s[90:91]
	global_store_dwordx4 v[136:137], v[132:135], off
	s_nop 1
	v_sub_f32_e32 v133, v217, v240
	v_sub_f32_e32 v132, v216, v240
	v_sub_f32_e32 v135, v219, v240
	v_sub_f32_e32 v134, v218, v240
	v_pk_mul_f32 v[132:133], v[240:241], v[132:133] op_sel:[1,0]
	v_pk_mul_f32 v[134:135], v[240:241], v[134:135] op_sel:[1,0]
	v_pk_fma_f32 v[132:133], v[150:151], v[132:133], v[64:65]
	v_pk_fma_f32 v[134:135], v[148:149], v[134:135], v[66:67]
	v_pk_fma_f32 v[128:129], v[128:129], s[78:79], v[132:133] op_sel_hi:[1,0,1]
	v_add_u32_e32 v132, 0x58010, v194
	v_mov_b32_e32 v133, v159
	v_pk_fma_f32 v[130:131], v[130:131], s[78:79], v[134:135] op_sel_hi:[1,0,1]
	v_lshl_add_u64 v[132:133], v[132:133], 2, s[90:91]
	global_store_dwordx4 v[132:133], v[128:131], off
	global_load_dwordx4 v[128:131], v[140:141], off offset:512
	v_add_u32_e32 v136, v232, v230
	v_mov_b32_e32 v137, v159
	v_lshl_add_u64 v[136:137], v[136:137], 2, s[88:89]
	s_waitcnt vmcnt(0)
;     template <bool LN, int BJ, int LO, int HI> DI void batch(const f32x4 (&acc)[2][2][4][2], unsigned row0, unsigned col0, const f32x4 (&gv)[2], const f32x4 (&bv)[2]) const {
;         f32x4 r[HI - LO]; float mean[(HI - LO) / 2], rstd[(HI - LO) / 2];
; #pragma unroll
;         for (int i = LO; i < HI; ++i) { const int ai = i >> 3, m = (i >> 1) & 3, n = i & 1; const unsigned row = row0 + ai * HALF + m * 16;
;             if (n == 0) { mean[(i - LO) >> 1] = 0.f; rstd[(i - LO) >> 1] = 1.f;
;                 if (LN) { const float2 st = *(const float2*)(stats + row * 2u); mean[(i - LO) >> 1] = st.x; rstd[(i - LO) >> 1] = st.y; } }
;             r[i - LO] = *(const f32x4*)(src + (row * (unsigned)DM + col0 + BJ * HALF + n * 16)); }
; #pragma unroll
;         for (int i = LO; i < HI; ++i) { const int ai = i >> 3, m = (i >> 1) & 3, n = i & 1; const unsigned row = row0 + ai * HALF + m * 16;
;             *(f32x4*)(Y + (row * (unsigned)DM + col0 + BJ * HALF + n * 16)) = acc[ai][BJ][m][n] + ((r[i - LO] - mean[(i - LO) >> 1]) * rstd[(i - LO) >> 1]) * gv[n] + bv[n]; }
;         __builtin_amdgcn_sched_barrier(0);
;     }
;     template <bool LN, int BJ> DI void load_gb(unsigned col0, f32x4 (&gv)[2], f32x4 (&bv)[2]) const {
; #pragma unroll
;         for (int n = 0; n < 2; ++n) {
;             if (LN) { gv[n] = *(const f32x4*)(gam + col0 + BJ * HALF + n * 16) * ALPHA; bv[n] = *(const f32x4*)(bet + col0 + BJ * HALF + n * 16) * ALPHA; }
;             else { gv[n] = (f32x4){ALPHA, ALPHA, ALPHA, ALPHA}; bv[n] = (f32x4){0.f, 0.f, 0.f, 0.f}; }
;         }
;     }
;     template <bool LN> DI void run(const f32x4 (&acc)[2][2][4][2], const Unit& u, int wr, int wc, int fr, int fq) const {
;         const unsigned row0 = u.pm * BM + wr * 64 + fr, col0 = u.pn * BM + wc * 32 + 4 * fq;
;         f32x4 gv[2], bv[2];
;         load_gb<LN, 0>(col0, gv, bv);
;         batch<LN, 0, 0, 4>(acc, row0, col0, gv, bv);
;         batch<LN, 0, 4, 8>(acc, row0, col0, gv, bv);
;         batch<LN, 0, 8, 12>(acc, row0, col0, gv, bv);
;         batch<LN, 0, 12, 16>(acc, row0, col0, gv, bv);
;         load_gb<LN, 1>(col0, gv, bv);
;         batch<LN, 1, 0, 8>(acc, row0, col0, gv, bv);
;         batch<LN, 1, 8, 16>(acc, row0, col0, gv, bv);
	v_pk_mul_f32 v[212:213], v[130:131], s[78:79] op_sel_hi:[1,0]
	v_pk_mul_f32 v[214:215], v[128:129], s[78:79] op_sel_hi:[1,0]
	global_load_dwordx4 v[132:135], v[142:143], off offset:512
	global_load_dwordx4 v[128:131], v[140:141], off offset:576
	s_waitcnt vmcnt(0)
	v_pk_mul_f32 v[206:207], v[130:131], s[78:79] op_sel_hi:[1,0]
	v_pk_mul_f32 v[208:209], v[128:129], s[78:79] op_sel_hi:[1,0]
	global_load_dwordx4 v[128:131], v[142:143], off offset:576
	global_load_dwordx2 v[220:221], v[144:145], off
	global_load_dwordx4 v[240:243], v[136:137], off
	v_add_u32_e32 v136, v232, v229
	v_mov_b32_e32 v137, v159
	v_lshl_add_u64 v[136:137], v[136:137], 2, s[88:89]
	global_load_dwordx4 v[244:247], v[136:137], off
	global_load_dwordx2 v[218:219], v[146:147], off
	v_add_u32_e32 v136, v195, v230
	v_mov_b32_e32 v137, v159
	v_lshl_add_u64 v[136:137], v[136:137], 2, s[88:89]
	global_load_dwordx4 v[248:251], v[136:137], off
	v_add_u32_e32 v136, v195, v229
	v_mov_b32_e32 v137, v159
	v_lshl_add_u64 v[136:137], v[136:137], 2, s[88:89]
	global_load_dwordx4 v[152:155], v[136:137], off
	global_load_dwordx2 v[216:217], v[200:201], off
	v_add_u32_e32 v136, v236, v230
	v_mov_b32_e32 v137, v159
	v_lshl_add_u64 v[136:137], v[136:137], 2, s[88:89]
	global_load_dwordx4 v[148:151], v[136:137], off
	v_add_u32_e32 v136, v236, v229
	v_mov_b32_e32 v137, v159
	v_lshl_add_u64 v[136:137], v[136:137], 2, s[88:89]
	global_load_dwordx4 v[144:147], v[136:137], off
	global_load_dwordx2 v[200:201], v[202:203], off
	v_add_u32_e32 v136, v235, v230
	v_mov_b32_e32 v137, v159
	v_lshl_add_u64 v[136:137], v[136:137], 2, s[88:89]
	global_load_dwordx4 v[140:143], v[136:137], off
	v_add_u32_e32 v136, v235, v229
	v_mov_b32_e32 v137, v159
	v_lshl_add_u64 v[136:137], v[136:137], 2, s[88:89]
	global_load_dwordx4 v[136:139], v[136:137], off
	v_add_u32_e32 v202, 0x80, v194
	v_mov_b32_e32 v203, v159
	v_lshl_add_u64 v[202:203], v[202:203], 2, s[90:91]
	s_waitcnt vmcnt(0)
	v_sub_f32_e32 v241, v241, v220
	v_sub_f32_e32 v240, v240, v220
	v_sub_f32_e32 v243, v243, v220
	v_sub_f32_e32 v242, v242, v220
	v_pk_mul_f32 v[242:243], v[220:221], v[242:243] op_sel:[1,0]
	v_pk_mul_f32 v[240:241], v[220:221], v[240:241] op_sel:[1,0]
	v_pk_fma_f32 v[242:243], v[212:213], v[242:243], v[62:63]
	v_pk_fma_f32 v[240:241], v[214:215], v[240:241], v[60:61]
	v_pk_fma_f32 v[242:243], v[134:135], s[78:79], v[242:243] op_sel_hi:[1,0,1]
	v_pk_fma_f32 v[240:241], v[132:133], s[78:79], v[240:241] op_sel_hi:[1,0,1]
	global_store_dwordx4 v[202:203], v[240:243], off
	v_sub_f32_e32 v203, v245, v220
	v_sub_f32_e32 v202, v244, v220
	v_sub_f32_e32 v241, v247, v220
	v_sub_f32_e32 v240, v246, v220
	v_pk_mul_f32 v[202:203], v[220:221], v[202:203] op_sel:[1,0]
	v_pk_mul_f32 v[240:241], v[220:221], v[240:241] op_sel:[1,0]
	v_pk_fma_f32 v[202:203], v[208:209], v[202:203], v[56:57]
	v_pk_fma_f32 v[220:221], v[206:207], v[240:241], v[58:59]
	v_pk_fma_f32 v[240:241], v[128:129], s[78:79], v[202:203] op_sel_hi:[1,0,1]
	v_add_u32_e32 v202, 0x90, v194
	v_mov_b32_e32 v203, v159
	v_pk_fma_f32 v[242:243], v[130:131], s[78:79], v[220:221] op_sel_hi:[1,0,1]
	v_lshl_add_u64 v[202:203], v[202:203], 2, s[90:91]
	global_store_dwordx4 v[202:203], v[240:243], off
	v_sub_f32_e32 v203, v249, v218
	v_sub_f32_e32 v202, v248, v218
	v_sub_f32_e32 v221, v251, v218
	v_sub_f32_e32 v220, v250, v218
	v_pk_mul_f32 v[202:203], v[218:219], v[202:203] op_sel:[1,0]
	v_pk_mul_f32 v[220:221], v[218:219], v[220:221] op_sel:[1,0]
	v_pk_fma_f32 v[202:203], v[214:215], v[202:203], v[52:53]
	v_pk_fma_f32 v[220:221], v[212:213], v[220:221], v[54:55]
	v_pk_fma_f32 v[240:241], v[132:133], s[78:79], v[202:203] op_sel_hi:[1,0,1]
	v_add_u32_e32 v202, 0x8080, v194
	v_mov_b32_e32 v203, v159
	v_sub_f32_e32 v153, v153, v218
	v_sub_f32_e32 v152, v152, v218
	v_sub_f32_e32 v155, v155, v218
	v_sub_f32_e32 v154, v154, v218
	v_pk_fma_f32 v[242:243], v[134:135], s[78:79], v[220:221] op_sel_hi:[1,0,1]
	v_lshl_add_u64 v[202:203], v[202:203], 2, s[90:91]
	v_pk_mul_f32 v[154:155], v[218:219], v[154:155] op_sel:[1,0]
	v_pk_mul_f32 v[152:153], v[218:219], v[152:153] op_sel:[1,0]
	global_store_dwordx4 v[202:203], v[240:243], off
	v_pk_fma_f32 v[152:153], v[208:209], v[152:153], v[48:49]
	v_pk_fma_f32 v[154:155], v[206:207], v[154:155], v[50:51]
	v_add_u32_e32 v202, 0x8090, v194
	v_mov_b32_e32 v203, v159
	v_sub_f32_e32 v149, v149, v216
	v_sub_f32_e32 v148, v148, v216
	v_sub_f32_e32 v151, v151, v216
	v_sub_f32_e32 v150, v150, v216
	v_pk_fma_f32 v[154:155], v[130:131], s[78:79], v[154:155] op_sel_hi:[1,0,1]
	v_pk_fma_f32 v[152:153], v[128:129], s[78:79], v[152:153] op_sel_hi:[1,0,1]
	v_lshl_add_u64 v[202:203], v[202:203], 2, s[90:91]
	v_pk_mul_f32 v[150:151], v[216:217], v[150:151] op_sel:[1,0]
	v_pk_mul_f32 v[148:149], v[216:217], v[148:149] op_sel:[1,0]
	global_store_dwordx4 v[202:203], v[152:155], off
	v_pk_fma_f32 v[148:149], v[214:215], v[148:149], v[44:45]
	v_pk_fma_f32 v[150:151], v[212:213], v[150:151], v[46:47]
	v_add_u32_e32 v152, 0x10080, v194
	v_mov_b32_e32 v153, v159
	v_sub_f32_e32 v145, v145, v216
	v_sub_f32_e32 v144, v144, v216
	v_sub_f32_e32 v147, v147, v216
	v_sub_f32_e32 v146, v146, v216
	v_pk_fma_f32 v[150:151], v[134:135], s[78:79], v[150:151] op_sel_hi:[1,0,1]
	v_pk_fma_f32 v[148:149], v[132:133], s[78:79], v[148:149] op_sel_hi:[1,0,1]
	v_lshl_add_u64 v[152:153], v[152:153], 2, s[90:91]
	v_pk_mul_f32 v[146:147], v[216:217], v[146:147] op_sel:[1,0]
	v_pk_mul_f32 v[144:145], v[216:217], v[144:145] op_sel:[1,0]
	global_store_dwordx4 v[152:153], v[148:151], off
	v_pk_fma_f32 v[144:145], v[208:209], v[144:145], v[40:41]
	v_pk_fma_f32 v[146:147], v[206:207], v[146:147], v[42:43]
;     template <bool LN, int BJ, int LO, int HI> DI void batch(const f32x4 (&acc)[2][2][4][2], unsigned row0, unsigned col0, const f32x4 (&gv)[2], const f32x4 (&bv)[2]) const {
;         f32x4 r[HI - LO]; float mean[(HI - LO) / 2], rstd[(HI - LO) / 2];
; #pragma unroll
;         for (int i = LO; i < HI; ++i) { const int ai = i >> 3, m = (i >> 1) & 3, n = i & 1; const unsigned row = row0 + ai * HALF + m * 16;
;             if (n == 0) { mean[(i - LO) >> 1] = 0.f; rstd[(i - LO) >> 1] = 1.f;
;                 if (LN) { const float2 st = *(const float2*)(stats + row * 2u); mean[(i - LO) >> 1] = st.x; rstd[(i - LO) >> 1] = st.y; } }
;             r[i - LO] = *(const f32x4*)(src + (row * (unsigned)DM + col0 + BJ * HALF + n * 16)); }
; #pragma unroll
;         for (int i = LO; i < HI; ++i) { const int ai = i >> 3, m = (i >> 1) & 3, n = i & 1; const unsigned row = row0 + ai * HALF + m * 16;
;             *(f32x4*)(Y + (row * (unsigned)DM + col0 + BJ * HALF + n * 16)) = acc[ai][BJ][m][n] + ((r[i - LO] - mean[(i - LO) >> 1]) * rstd[(i - LO) >> 1]) * gv[n] + bv[n]; }
	v_add_u32_e32 v148, 0x10090, v194
	v_mov_b32_e32 v149, v159
	v_sub_f32_e32 v141, v141, v200
	v_sub_f32_e32 v140, v140, v200
	v_sub_f32_e32 v143, v143, v200
	v_sub_f32_e32 v142, v142, v200
	v_pk_fma_f32 v[146:147], v[130:131], s[78:79], v[146:147] op_sel_hi:[1,0,1]
	v_pk_fma_f32 v[144:145], v[128:129], s[78:79], v[144:145] op_sel_hi:[1,0,1]
	v_lshl_add_u64 v[148:149], v[148:149], 2, s[90:91]
	v_pk_mul_f32 v[142:143], v[200:201], v[142:143] op_sel:[1,0]
	v_pk_mul_f32 v[140:141], v[200:201], v[140:141] op_sel:[1,0]
	global_store_dwordx4 v[148:149], v[144:147], off
	v_pk_fma_f32 v[140:141], v[214:215], v[140:141], v[36:37]
	v_pk_fma_f32 v[142:143], v[212:213], v[142:143], v[38:39]
	v_add_u32_e32 v144, 0x18080, v194
	v_mov_b32_e32 v145, v159
	v_sub_f32_e32 v137, v137, v200
	v_sub_f32_e32 v136, v136, v200
	v_sub_f32_e32 v139, v139, v200
	v_sub_f32_e32 v138, v138, v200
	v_pk_fma_f32 v[142:143], v[134:135], s[78:79], v[142:143] op_sel_hi:[1,0,1]
	v_pk_fma_f32 v[140:141], v[132:133], s[78:79], v[140:141] op_sel_hi:[1,0,1]
	v_lshl_add_u64 v[144:145], v[144:145], 2, s[90:91]
	v_pk_mul_f32 v[138:139], v[200:201], v[138:139] op_sel:[1,0]
	v_pk_mul_f32 v[136:137], v[200:201], v[136:137] op_sel:[1,0]
	global_store_dwordx4 v[144:145], v[140:143], off
	v_pk_fma_f32 v[136:137], v[208:209], v[136:137], v[32:33]
	v_pk_fma_f32 v[138:139], v[206:207], v[138:139], v[34:35]
	v_add_u32_e32 v140, 0x18090, v194
	v_mov_b32_e32 v141, v159
	v_pk_fma_f32 v[138:139], v[130:131], s[78:79], v[138:139] op_sel_hi:[1,0,1]
	v_pk_fma_f32 v[136:137], v[128:129], s[78:79], v[136:137] op_sel_hi:[1,0,1]
	v_lshl_add_u64 v[140:141], v[140:141], 2, s[90:91]
	global_store_dwordx4 v[140:141], v[136:139], off
	s_nop 1
	v_add_u32_e32 v136, v233, v230
	v_mov_b32_e32 v137, v159
	v_lshl_add_u64 v[136:137], v[136:137], 2, s[88:89]
	global_load_dwordx2 v[220:221], v[196:197], off
	global_load_dwordx4 v[216:219], v[136:137], off
	v_add_u32_e32 v136, v233, v229
	v_mov_b32_e32 v137, v159
	v_lshl_add_u64 v[136:137], v[136:137], 2, s[88:89]
	global_load_dwordx4 v[240:243], v[136:137], off
	global_load_dwordx2 v[200:201], v[198:199], off
	v_add_u32_e32 v136, v234, v230
	v_mov_b32_e32 v137, v159
	v_lshl_add_u64 v[136:137], v[136:137], 2, s[88:89]
	global_load_dwordx4 v[244:247], v[136:137], off
	v_add_u32_e32 v136, v234, v229
	v_mov_b32_e32 v137, v159
	v_lshl_add_u64 v[136:137], v[136:137], 2, s[88:89]
	global_load_dwordx4 v[152:155], v[136:137], off
	global_load_dwordx2 v[198:199], v[204:205], off
	v_add_u32_e32 v136, v237, v230
	v_mov_b32_e32 v137, v159
	v_lshl_add_u64 v[136:137], v[136:137], 2, s[88:89]
	global_load_dwordx4 v[148:151], v[136:137], off
	v_add_u32_e32 v136, v237, v229
	v_mov_b32_e32 v137, v159
	v_lshl_add_u64 v[136:137], v[136:137], 2, s[88:89]
	global_load_dwordx4 v[144:147], v[136:137], off
	global_load_dwordx2 v[196:197], v[210:211], off
	v_add_u32_e32 v136, v238, v230
	v_mov_b32_e32 v137, v159
	v_lshl_add_u64 v[136:137], v[136:137], 2, s[88:89]
	global_load_dwordx4 v[140:143], v[136:137], off
	v_add_u32_e32 v136, v238, v229
	v_mov_b32_e32 v137, v159
	v_lshl_add_u64 v[136:137], v[136:137], 2, s[88:89]
	global_load_dwordx4 v[136:139], v[136:137], off
	v_add_u32_e32 v210, 0x40080, v194
	v_mov_b32_e32 v211, v159
	v_lshl_add_u64 v[210:211], v[210:211], 2, s[90:91]
	s_waitcnt vmcnt(0)
;     template <bool LN, int BJ, int LO, int HI> DI void batch(const f32x4 (&acc)[2][2][4][2], unsigned row0, unsigned col0, const f32x4 (&gv)[2], const f32x4 (&bv)[2]) const {
;         f32x4 r[HI - LO]; float mean[(HI - LO) / 2], rstd[(HI - LO) / 2];
; #pragma unroll
;         for (int i = LO; i < HI; ++i) { const int ai = i >> 3, m = (i >> 1) & 3, n = i & 1; const unsigned row = row0 + ai * HALF + m * 16;
;             if (n == 0) { mean[(i - LO) >> 1] = 0.f; rstd[(i - LO) >> 1] = 1.f;
;                 if (LN) { const float2 st = *(const float2*)(stats + row * 2u); mean[(i - LO) >> 1] = st.x; rstd[(i - LO) >> 1] = st.y; } }
;             r[i - LO] = *(const f32x4*)(src + (row * (unsigned)DM + col0 + BJ * HALF + n * 16)); }
; #pragma unroll
;         for (int i = LO; i < HI; ++i) { const int ai = i >> 3, m = (i >> 1) & 3, n = i & 1; const unsigned row = row0 + ai * HALF + m * 16;
;             *(f32x4*)(Y + (row * (unsigned)DM + col0 + BJ * HALF + n * 16)) = acc[ai][BJ][m][n] + ((r[i - LO] - mean[(i - LO) >> 1]) * rstd[(i - LO) >> 1]) * gv[n] + bv[n]; }
	v_sub_f32_e32 v203, v217, v220
	v_sub_f32_e32 v202, v216, v220
	v_sub_f32_e32 v205, v219, v220
	v_sub_f32_e32 v204, v218, v220
	v_pk_mul_f32 v[204:205], v[220:221], v[204:205] op_sel:[1,0]
	v_pk_mul_f32 v[202:203], v[220:221], v[202:203] op_sel:[1,0]
	v_pk_fma_f32 v[204:205], v[212:213], v[204:205], v[30:31]
	v_pk_fma_f32 v[202:203], v[214:215], v[202:203], v[28:29]
	v_pk_fma_f32 v[204:205], v[134:135], s[78:79], v[204:205] op_sel_hi:[1,0,1]
	v_pk_fma_f32 v[202:203], v[132:133], s[78:79], v[202:203] op_sel_hi:[1,0,1]
	global_store_dwordx4 v[210:211], v[202:205], off
	v_add_u32_e32 v210, 0x40090, v194
	v_mov_b32_e32 v211, v159
	v_sub_f32_e32 v203, v241, v220
	v_sub_f32_e32 v202, v240, v220
	v_sub_f32_e32 v205, v243, v220
	v_sub_f32_e32 v204, v242, v220
	v_pk_mul_f32 v[204:205], v[220:221], v[204:205] op_sel:[1,0]
	v_pk_mul_f32 v[202:203], v[220:221], v[202:203] op_sel:[1,0]
	v_pk_fma_f32 v[204:205], v[206:207], v[204:205], v[26:27]
	v_pk_fma_f32 v[202:203], v[208:209], v[202:203], v[24:25]
	v_pk_fma_f32 v[204:205], v[130:131], s[78:79], v[204:205] op_sel_hi:[1,0,1]
	v_pk_fma_f32 v[202:203], v[128:129], s[78:79], v[202:203] op_sel_hi:[1,0,1]
	v_lshl_add_u64 v[210:211], v[210:211], 2, s[90:91]
	global_store_dwordx4 v[210:211], v[202:205], off
	v_sub_f32_e32 v149, v149, v198
	v_sub_f32_e32 v148, v148, v198
	v_sub_f32_e32 v203, v245, v200
	v_sub_f32_e32 v202, v244, v200
	v_sub_f32_e32 v141, v141, v196
	v_sub_f32_e32 v140, v140, v196
	v_sub_f32_e32 v205, v247, v200
	v_sub_f32_e32 v204, v246, v200
	v_pk_mul_f32 v[202:203], v[200:201], v[202:203] op_sel:[1,0]
	v_sub_f32_e32 v151, v151, v198
	v_sub_f32_e32 v150, v150, v198
	v_pk_mul_f32 v[148:149], v[198:199], v[148:149] op_sel:[1,0]
	v_sub_f32_e32 v143, v143, v196
	v_sub_f32_e32 v142, v142, v196
	v_pk_mul_f32 v[140:141], v[196:197], v[140:141] op_sel:[1,0]
	v_pk_mul_f32 v[204:205], v[200:201], v[204:205] op_sel:[1,0]
	v_pk_fma_f32 v[202:203], v[214:215], v[202:203], v[20:21]
	v_sub_f32_e32 v153, v153, v200
	v_sub_f32_e32 v152, v152, v200
	v_sub_f32_e32 v155, v155, v200
	v_sub_f32_e32 v154, v154, v200
	v_pk_mul_f32 v[150:151], v[198:199], v[150:151] op_sel:[1,0]
	v_pk_fma_f32 v[148:149], v[214:215], v[148:149], v[12:13]
	v_pk_mul_f32 v[142:143], v[196:197], v[142:143] op_sel:[1,0]
	v_pk_fma_f32 v[140:141], v[214:215], v[140:141], v[4:5]
	v_pk_fma_f32 v[204:205], v[212:213], v[204:205], v[22:23]
	v_pk_fma_f32 v[202:203], v[132:133], s[78:79], v[202:203] op_sel_hi:[1,0,1]
	v_pk_mul_f32 v[154:155], v[200:201], v[154:155] op_sel:[1,0]
	v_pk_mul_f32 v[152:153], v[200:201], v[152:153] op_sel:[1,0]
	v_pk_fma_f32 v[150:151], v[212:213], v[150:151], v[14:15]
	v_pk_fma_f32 v[148:149], v[132:133], s[78:79], v[148:149] op_sel_hi:[1,0,1]
	v_pk_fma_f32 v[142:143], v[212:213], v[142:143], v[6:7]
	v_pk_fma_f32 v[132:133], v[132:133], s[78:79], v[140:141] op_sel_hi:[1,0,1]
	v_add_u32_e32 v140, 0x58080, v194
	v_mov_b32_e32 v141, v159
	v_pk_fma_f32 v[204:205], v[134:135], s[78:79], v[204:205] op_sel_hi:[1,0,1]
	v_pk_fma_f32 v[152:153], v[208:209], v[152:153], v[16:17]
	v_pk_fma_f32 v[154:155], v[206:207], v[154:155], v[18:19]
	v_add_u32_e32 v200, 0x48090, v194
	v_mov_b32_e32 v201, v159
	v_pk_fma_f32 v[150:151], v[134:135], s[78:79], v[150:151] op_sel_hi:[1,0,1]
	v_pk_fma_f32 v[134:135], v[134:135], s[78:79], v[142:143] op_sel_hi:[1,0,1]
	v_lshl_add_u64 v[140:141], v[140:141], 2, s[90:91]
	v_pk_fma_f32 v[154:155], v[130:131], s[78:79], v[154:155] op_sel_hi:[1,0,1]
	v_pk_fma_f32 v[152:153], v[128:129], s[78:79], v[152:153] op_sel_hi:[1,0,1]
	v_lshl_add_u64 v[200:201], v[200:201], 2, s[90:91]
	v_sub_f32_e32 v145, v145, v198
	v_sub_f32_e32 v144, v144, v198
	global_store_dwordx4 v[140:141], v[132:135], off
	global_store_dwordx4 v[200:201], v[152:155], off
	v_sub_f32_e32 v147, v147, v198
	v_sub_f32_e32 v133, v137, v196
	v_sub_f32_e32 v132, v136, v196
	v_add_u32_e32 v152, 0x50080, v194
	v_mov_b32_e32 v153, v159
	v_sub_f32_e32 v146, v146, v198
	v_pk_mul_f32 v[144:145], v[198:199], v[144:145] op_sel:[1,0]
	v_sub_f32_e32 v135, v139, v196
	v_sub_f32_e32 v134, v138, v196
	v_pk_mul_f32 v[132:133], v[196:197], v[132:133] op_sel:[1,0]
	v_lshl_add_u64 v[152:153], v[152:153], 2, s[90:91]
	v_pk_mul_f32 v[146:147], v[198:199], v[146:147] op_sel:[1,0]
	v_pk_fma_f32 v[144:145], v[208:209], v[144:145], v[8:9]
	v_pk_mul_f32 v[134:135], v[196:197], v[134:135] op_sel:[1,0]
	v_pk_fma_f32 v[132:133], v[208:209], v[132:133], v[0:1]
	v_add_u32_e32 v210, 0x48080, v194
	v_mov_b32_e32 v211, v159
	global_store_dwordx4 v[152:153], v[148:151], off
	v_pk_fma_f32 v[146:147], v[206:207], v[146:147], v[10:11]
	v_pk_fma_f32 v[144:145], v[128:129], s[78:79], v[144:145] op_sel_hi:[1,0,1]
	v_add_u32_e32 v148, 0x50090, v194
	v_mov_b32_e32 v149, v159
	v_pk_fma_f32 v[134:135], v[206:207], v[134:135], v[2:3]
	v_pk_fma_f32 v[128:129], v[128:129], s[78:79], v[132:133] op_sel_hi:[1,0,1]
	v_add_u32_e32 v132, 0x58090, v194
	v_mov_b32_e32 v133, v159
	v_lshl_add_u64 v[210:211], v[210:211], 2, s[90:91]
	v_pk_fma_f32 v[146:147], v[130:131], s[78:79], v[146:147] op_sel_hi:[1,0,1]
	v_lshl_add_u64 v[148:149], v[148:149], 2, s[90:91]
	v_pk_fma_f32 v[130:131], v[130:131], s[78:79], v[134:135] op_sel_hi:[1,0,1]
	v_lshl_add_u64 v[132:133], v[132:133], 2, s[90:91]
	global_store_dwordx4 v[210:211], v[202:205], off
	global_store_dwordx4 v[148:149], v[144:147], off
	global_store_dwordx4 v[132:133], v[128:131], off
	s_mov_b64 s[20:21], 0
	s_branch .LBB0_81

; #define PG8_STAGE(bufoff, gbase) do { _Pragma("unroll") for (int _i = 0; _i < 2; ++_i) \
;         __builtin_amdgcn_global_load_lds((const unsigned*)((const char*)(gbase) + voff[_i]), (LAS unsigned*)(lds + (bufoff) + ldsw + _i * 8192), 16, 0, 0); } while (0)
; #define PG8_LDA(dst, b, h) do { _Pragma("unroll") for (int m = 0; m < 4; ++m) _Pragma("unroll") for (int k = 0; k < 2; ++k) dst[m][k] = *(const LAS bf16x8*)(lds + PG8_SA(b, h) + aoff + m * 2048 + k * 1024); } while (0)
; #define PG8_LDB(dst, b, h) do { _Pragma("unroll") for (int n = 0; n < 2; ++n) _Pragma("unroll") for (int k = 0; k < 2; ++k) dst[n][k] = *(const LAS bf16x8*)(lds + PG8_SB(b, h) + boff + n * 2048 + k * 1024); } while (0)
; #define PG8_MMA(ai, bj, At, Bt) do { __builtin_amdgcn_s_setprio(1); _Pragma("unroll") for (int m = 0; m < 4; ++m) _Pragma("unroll") for (int n = 0; n < 2; ++n) _Pragma("unroll") for (int k = 0; k < 2; ++k) \
;         acc[ai][bj][m][n] = __builtin_amdgcn_mfma_f32_16x16x32_bf16(Bt[n][k], At[m][k], acc[ai][bj][m][n], 0, 0, 0); __builtin_amdgcn_s_setprio(0); } while (0)
; template <class Epi>
; DI void gemm_phase(LAS unsigned char* lds, const Gemm g, const StaticOrder& S, const Epi& E) {
;     ...
;         const bool has_next = S.next(ui + 1, nxt);
;         const char* nA = has_next ? (const char*)g.A + (size_t)nxt.pm * tstep : cA; const char* nB = has_next ? (const char*)g.Bt + (size_t)nxt.pn * tstep : cB;
;         for (int t = 0; t < nt; t += 2) {
;             const bool last = (t == nt - 2);
;             const char* a1 = cA + (size_t)(t + 1) * kstep;
;             const char* a2 = last ? nA : cA + (size_t)(t + 2) * kstep; const char* b2 = last ? nB : cB + (size_t)(t + 2) * kstep;
;             const char* a3 = a2 + kstep; const char* b3 = b2 + kstep;
;             PG8_LDB(B0, 0, 0); PG8_SCHED; PG8_LDA(At, 0, 0); PG8_STAGE(PG8_SA(1, 1), a1 + hstep);
;             PG8_WAIT_L(8); PG8_BAR; PG8_WAIT_L(0); PG8_MMA(0, 0, At, B0); PG8_BAR; PG8_SCHED;
;             PG8_LDB(B1, 0, 1); PG8_STAGE(PG8_SB(0, 0), b2);
;             PG8_BAR; PG8_WAIT_L(0); PG8_MMA(0, 1, At, B1); PG8_BAR;
;             PG8_LDA(At, 0, 1); PG8_STAGE(PG8_SA(0, 0), a2);
;             PG8_BAR; PG8_WAIT_L(0); PG8_MMA(1, 0, At, B0); PG8_BAR; PG8_SCHED;
;             PG8_STAGE(PG8_SB(0, 1), b2 + hstep);
;             PG8_WAIT_V(6); PG8_BAR; PG8_MMA(1, 1, At, B1); PG8_BAR;
.LBB0_134:
	ds_read_b128 v[96:99], v199
	ds_read_b128 v[100:103], v199 offset:1024
	ds_read_b128 v[136:139], v199 offset:2048
	ds_read_b128 v[148:151], v199 offset:3072
	ds_read_b128 v[152:155], v201
	ds_read_b128 v[186:189], v201 offset:1024
	ds_read_b128 v[190:193], v201 offset:2048
	ds_read_b128 v[194:197], v201 offset:3072
	ds_read_b128 v[202:205], v201 offset:4096
	ds_read_b128 v[206:209], v201 offset:5120
	ds_read_b128 v[210:213], v201 offset:6144
	ds_read_b128 v[214:217], v201 offset:7168
	s_add_u32 s18, s16, 0x100
	s_addc_u32 s19, s17, 0
	s_add_i32 s39, 0, 0x10000
	s_cmpk_eq_i32 s33, 0x54
	s_cselect_b32 s23, s9, s19
	s_cselect_b32 s22, s8, s18
	s_cselect_b32 s21, s11, s5
	s_cselect_b32 s20, s10, s4
	s_add_i32 m0, s28, 0xc000
	s_nop 0
	global_load_lds_dwordx4 v144, s[16:17]
	s_add_i32 m0, s28, 0xe000
	s_nop 0
	global_load_lds_dwordx4 v146, s[16:17]
	s_waitcnt lgkmcnt(8)
	s_setprio 1
	s_barrier
	s_waitcnt lgkmcnt(0)
	v_mfma_f32_16x16x32_bf16 v[132:135], v[96:99], v[152:155], v[132:135]
	v_mfma_f32_16x16x32_bf16 v[128:131], v[136:139], v[152:155], v[128:131]
	v_mfma_f32_16x16x32_bf16 v[124:127], v[96:99], v[190:193], v[124:127]
	v_mfma_f32_16x16x32_bf16 v[120:123], v[136:139], v[190:193], v[120:123]
	v_mfma_f32_16x16x32_bf16 v[116:119], v[96:99], v[202:205], v[116:119]
	v_mfma_f32_16x16x32_bf16 v[112:115], v[136:139], v[202:205], v[112:115]
	v_mfma_f32_16x16x32_bf16 v[108:111], v[96:99], v[210:213], v[108:111]
	v_mfma_f32_16x16x32_bf16 v[104:107], v[136:139], v[210:213], v[104:107]
	v_mfma_f32_16x16x32_bf16 v[132:135], v[100:103], v[186:189], v[132:135]
	v_mfma_f32_16x16x32_bf16 v[128:131], v[148:151], v[186:189], v[128:131]
	v_mfma_f32_16x16x32_bf16 v[124:127], v[100:103], v[194:197], v[124:127]
	v_mfma_f32_16x16x32_bf16 v[120:123], v[148:151], v[194:197], v[120:123]
	v_mfma_f32_16x16x32_bf16 v[116:119], v[100:103], v[206:209], v[116:119]
	v_mfma_f32_16x16x32_bf16 v[112:115], v[148:151], v[206:209], v[112:115]
	v_mfma_f32_16x16x32_bf16 v[108:111], v[100:103], v[214:217], v[108:111]
	s_setprio 0
	v_mfma_f32_16x16x32_bf16 v[104:107], v[148:151], v[214:217], v[104:107]
	s_barrier
	ds_read_b128 v[226:229], v199 offset:16384
	ds_read_b128 v[230:233], v199 offset:17408
	ds_read_b128 v[234:237], v199 offset:18432
	ds_read_b128 v[238:241], v199 offset:19456
	s_add_i32 s40, 0, 0x14000
	s_add_i32 s16, s39, s27
	s_mov_b32 m0, s16
	s_nop 0
	global_load_lds_dwordx4 v142, s[20:21]
	s_add_i32 m0, s16, 0x2000
	s_nop 0
	global_load_lds_dwordx4 v140, s[20:21]
	s_waitcnt lgkmcnt(0)
	s_setprio 1
	s_barrier
	v_mfma_f32_16x16x32_bf16 v[60:63], v[226:229], v[152:155], v[60:63]
	v_mfma_f32_16x16x32_bf16 v[56:59], v[234:237], v[152:155], v[56:59]
	v_mfma_f32_16x16x32_bf16 v[52:55], v[226:229], v[190:193], v[52:55]
	v_mfma_f32_16x16x32_bf16 v[48:51], v[234:237], v[190:193], v[48:51]
	v_mfma_f32_16x16x32_bf16 v[44:47], v[226:229], v[202:205], v[44:47]
	v_mfma_f32_16x16x32_bf16 v[40:43], v[234:237], v[202:205], v[40:43]
	v_mfma_f32_16x16x32_bf16 v[36:39], v[226:229], v[210:213], v[36:39]
	v_mfma_f32_16x16x32_bf16 v[32:35], v[234:237], v[210:213], v[32:35]
	v_mfma_f32_16x16x32_bf16 v[60:63], v[230:233], v[186:189], v[60:63]
	v_mfma_f32_16x16x32_bf16 v[56:59], v[238:241], v[186:189], v[56:59]
	v_mfma_f32_16x16x32_bf16 v[52:55], v[230:233], v[194:197], v[52:55]
	v_mfma_f32_16x16x32_bf16 v[48:51], v[238:241], v[194:197], v[48:51]
	v_mfma_f32_16x16x32_bf16 v[44:47], v[230:233], v[206:209], v[44:47]
	v_mfma_f32_16x16x32_bf16 v[40:43], v[238:241], v[206:209], v[40:43]
	v_mfma_f32_16x16x32_bf16 v[36:39], v[230:233], v[214:217], v[36:39]
	s_setprio 0
	v_mfma_f32_16x16x32_bf16 v[32:35], v[238:241], v[214:217], v[32:35]
	s_barrier
	ds_read_b128 v[152:155], v201 offset:16384
	ds_read_b128 v[186:189], v201 offset:17408
	ds_read_b128 v[190:193], v201 offset:18432
	ds_read_b128 v[194:197], v201 offset:19456
	ds_read_b128 v[202:205], v201 offset:20480
	ds_read_b128 v[206:209], v201 offset:21504
	ds_read_b128 v[210:213], v201 offset:22528
	ds_read_b128 v[214:217], v201 offset:23552
	s_mov_b32 m0, s28
	s_nop 0
	global_load_lds_dwordx4 v142, s[22:23]
	s_mov_b32 m0, s29
	s_mov_b64 s[100:101], s[22:23]
	global_load_lds_dwordx4 v140, s[22:23]
	s_waitcnt lgkmcnt(0)
	s_setprio 1
	s_barrier
	v_mfma_f32_16x16x32_bf16 v[92:95], v[96:99], v[152:155], v[92:95]
	v_mfma_f32_16x16x32_bf16 v[88:91], v[136:139], v[152:155], v[88:91]
	v_mfma_f32_16x16x32_bf16 v[84:87], v[96:99], v[190:193], v[84:87]
	v_mfma_f32_16x16x32_bf16 v[80:83], v[136:139], v[190:193], v[80:83]
	v_mfma_f32_16x16x32_bf16 v[76:79], v[96:99], v[202:205], v[76:79]
	v_mfma_f32_16x16x32_bf16 v[72:75], v[136:139], v[202:205], v[72:75]
	v_mfma_f32_16x16x32_bf16 v[68:71], v[96:99], v[210:213], v[68:71]
	v_mfma_f32_16x16x32_bf16 v[64:67], v[136:139], v[210:213], v[64:67]
	v_mfma_f32_16x16x32_bf16 v[92:95], v[100:103], v[186:189], v[92:95]
	v_mfma_f32_16x16x32_bf16 v[88:91], v[148:151], v[186:189], v[88:91]
	v_mfma_f32_16x16x32_bf16 v[84:87], v[100:103], v[194:197], v[84:87]
	v_mfma_f32_16x16x32_bf16 v[80:83], v[148:151], v[194:197], v[80:83]
	v_mfma_f32_16x16x32_bf16 v[76:79], v[100:103], v[206:209], v[76:79]
	v_mfma_f32_16x16x32_bf16 v[72:75], v[148:151], v[206:209], v[72:75]
	v_mfma_f32_16x16x32_bf16 v[68:71], v[100:103], v[214:217], v[68:71]
	s_setprio 0
	v_mfma_f32_16x16x32_bf16 v[64:67], v[148:151], v[214:217], v[64:67]
	s_barrier
	s_add_u32 s16, s20, 0x160000
	s_addc_u32 s17, s21, 0
	s_add_i32 s39, s40, s27
	s_mov_b32 m0, s39
	s_nop 0
	global_load_lds_dwordx4 v142, s[16:17]
	s_add_i32 m0, s39, 0x2000
	s_nop 0
	global_load_lds_dwordx4 v140, s[16:17]
	s_waitcnt vmcnt(6)
	s_setprio 1
	s_barrier
; #define PG8_STAGE(bufoff, gbase) do { _Pragma("unroll") for (int _i = 0; _i < 2; ++_i) \
;         __builtin_amdgcn_global_load_lds((const unsigned*)((const char*)(gbase) + voff[_i]), (LAS unsigned*)(lds + (bufoff) + ldsw + _i * 8192), 16, 0, 0); } while (0)
; #define PG8_LDA(dst, b, h) do { _Pragma("unroll") for (int m = 0; m < 4; ++m) _Pragma("unroll") for (int k = 0; k < 2; ++k) dst[m][k] = *(const LAS bf16x8*)(lds + PG8_SA(b, h) + aoff + m * 2048 + k * 1024); } while (0)
; #define PG8_LDB(dst, b, h) do { _Pragma("unroll") for (int n = 0; n < 2; ++n) _Pragma("unroll") for (int k = 0; k < 2; ++k) dst[n][k] = *(const LAS bf16x8*)(lds + PG8_SB(b, h) + boff + n * 2048 + k * 1024); } while (0)
; #define PG8_MMA(ai, bj, At, Bt) do { __builtin_amdgcn_s_setprio(1); _Pragma("unroll") for (int m = 0; m < 4; ++m) _Pragma("unroll") for (int n = 0; n < 2; ++n) _Pragma("unroll") for (int k = 0; k < 2; ++k) \
;         acc[ai][bj][m][n] = __builtin_amdgcn_mfma_f32_16x16x32_bf16(Bt[n][k], At[m][k], acc[ai][bj][m][n], 0, 0, 0); __builtin_amdgcn_s_setprio(0); } while (0)
; #define PG8_WAIT_V(n) asm volatile("s_waitcnt vmcnt(" #n ")" ::: "memory")
; #define PG8_WAIT_L(n) asm volatile("s_waitcnt lgkmcnt(" #n ")" ::: "memory")
; #define PG8_BAR __builtin_amdgcn_s_barrier()
; #define PG8_SCHED __builtin_amdgcn_sched_barrier(0)
; template <class Epi>
; DI void gemm_phase(LAS unsigned char* lds, const Gemm g, const StaticOrder& S, const Epi& E) {
;     ...
;             PG8_WAIT_V(6); PG8_BAR; PG8_MMA(1, 1, At, B1); PG8_BAR;
;             PG8_LDB(B0, 1, 0); PG8_SCHED; PG8_LDA(At, 1, 0); PG8_STAGE(PG8_SA(0, 1), a2 + hstep);
;             PG8_WAIT_L(8); PG8_BAR; PG8_WAIT_L(0); PG8_MMA(0, 0, At, B0); PG8_BAR; PG8_SCHED;
;             PG8_LDB(B1, 1, 1); PG8_STAGE(PG8_SB(1, 0), b3);
;             PG8_BAR; PG8_WAIT_L(0); PG8_MMA(0, 1, At, B1); PG8_BAR;
;             PG8_LDA(At, 1, 1); PG8_STAGE(PG8_SA(1, 0), a3);
;             PG8_BAR; PG8_WAIT_L(0); PG8_MMA(1, 0, At, B0); PG8_BAR; PG8_SCHED;
	v_mfma_f32_16x16x32_bf16 v[28:31], v[226:229], v[152:155], v[28:31]
	v_mfma_f32_16x16x32_bf16 v[24:27], v[234:237], v[152:155], v[24:27]
	v_mfma_f32_16x16x32_bf16 v[20:23], v[226:229], v[190:193], v[20:23]
	v_mfma_f32_16x16x32_bf16 v[16:19], v[234:237], v[190:193], v[16:19]
	v_mfma_f32_16x16x32_bf16 v[12:15], v[226:229], v[202:205], v[12:15]
	v_mfma_f32_16x16x32_bf16 v[8:11], v[234:237], v[202:205], v[8:11]
	v_mfma_f32_16x16x32_bf16 v[4:7], v[226:229], v[210:213], v[4:7]
	v_mfma_f32_16x16x32_bf16 v[0:3], v[234:237], v[210:213], v[0:3]
	v_mfma_f32_16x16x32_bf16 v[28:31], v[230:233], v[186:189], v[28:31]
	v_mfma_f32_16x16x32_bf16 v[24:27], v[238:241], v[186:189], v[24:27]
	v_mfma_f32_16x16x32_bf16 v[20:23], v[230:233], v[194:197], v[20:23]
	v_mfma_f32_16x16x32_bf16 v[16:19], v[238:241], v[194:197], v[16:19]
	v_mfma_f32_16x16x32_bf16 v[12:15], v[230:233], v[206:209], v[12:15]
	v_mfma_f32_16x16x32_bf16 v[8:11], v[238:241], v[206:209], v[8:11]
	v_mfma_f32_16x16x32_bf16 v[4:7], v[230:233], v[214:217], v[4:7]
	s_setprio 0
	v_mfma_f32_16x16x32_bf16 v[0:3], v[238:241], v[214:217], v[0:3]
	s_barrier
	ds_read_b128 v[96:99], v199 offset:32768
	ds_read_b128 v[100:103], v199 offset:33792
	ds_read_b128 v[136:139], v199 offset:34816
	ds_read_b128 v[148:151], v199 offset:35840
	ds_read_b128 v[152:155], v201 offset:32768
	ds_read_b128 v[186:189], v201 offset:33792
	ds_read_b128 v[190:193], v201 offset:34816
	ds_read_b128 v[194:197], v201 offset:35840
	ds_read_b128 v[202:205], v201 offset:36864
	ds_read_b128 v[206:209], v201 offset:37888
	ds_read_b128 v[210:213], v201 offset:38912
	ds_read_b128 v[214:217], v201 offset:39936
	s_add_i32 s39, 0, 0x18000
	s_add_u32 s16, s22, 0x160000
	s_addc_u32 s17, s23, 0
	s_mov_b32 m0, s30
	s_nop 0
	global_load_lds_dwordx4 v142, s[16:17]
	s_mov_b32 m0, s31
	s_nop 0
	global_load_lds_dwordx4 v140, s[16:17]
	s_waitcnt lgkmcnt(8)
	s_setprio 1
	s_barrier
	s_waitcnt lgkmcnt(0)
	v_mfma_f32_16x16x32_bf16 v[132:135], v[96:99], v[152:155], v[132:135]
	v_mfma_f32_16x16x32_bf16 v[128:131], v[136:139], v[152:155], v[128:131]
	v_mfma_f32_16x16x32_bf16 v[124:127], v[96:99], v[190:193], v[124:127]
	v_mfma_f32_16x16x32_bf16 v[120:123], v[136:139], v[190:193], v[120:123]
	v_mfma_f32_16x16x32_bf16 v[116:119], v[96:99], v[202:205], v[116:119]
	v_mfma_f32_16x16x32_bf16 v[112:115], v[136:139], v[202:205], v[112:115]
	v_mfma_f32_16x16x32_bf16 v[108:111], v[96:99], v[210:213], v[108:111]
	v_mfma_f32_16x16x32_bf16 v[104:107], v[136:139], v[210:213], v[104:107]
	v_mfma_f32_16x16x32_bf16 v[132:135], v[100:103], v[186:189], v[132:135]
	v_mfma_f32_16x16x32_bf16 v[128:131], v[148:151], v[186:189], v[128:131]
	v_mfma_f32_16x16x32_bf16 v[124:127], v[100:103], v[194:197], v[124:127]
	v_mfma_f32_16x16x32_bf16 v[120:123], v[148:151], v[194:197], v[120:123]
	v_mfma_f32_16x16x32_bf16 v[116:119], v[100:103], v[206:209], v[116:119]
	v_mfma_f32_16x16x32_bf16 v[112:115], v[148:151], v[206:209], v[112:115]
	v_mfma_f32_16x16x32_bf16 v[108:111], v[100:103], v[214:217], v[108:111]
	s_setprio 0
	v_mfma_f32_16x16x32_bf16 v[104:107], v[148:151], v[214:217], v[104:107]
	s_barrier
	ds_read_b128 v[226:229], v199 offset:49152
	ds_read_b128 v[230:233], v199 offset:50176
	ds_read_b128 v[234:237], v199 offset:51200
	ds_read_b128 v[238:241], v199 offset:52224
	s_add_i32 s22, 0, 0x1c000
	s_add_i32 s16, s39, s27
	s_add_i32 m0, s16, 0xffffff80
	s_nop 0
	global_load_lds_dwordx4 v142, s[20:21] offset:128
	s_add_i32 m0, s16, 0x1f80
	s_nop 0
	global_load_lds_dwordx4 v140, s[20:21] offset:128
	s_waitcnt lgkmcnt(0)
	s_setprio 1
	s_barrier
	v_mfma_f32_16x16x32_bf16 v[60:63], v[226:229], v[152:155], v[60:63]
	v_mfma_f32_16x16x32_bf16 v[56:59], v[234:237], v[152:155], v[56:59]
	v_mfma_f32_16x16x32_bf16 v[52:55], v[226:229], v[190:193], v[52:55]
	v_mfma_f32_16x16x32_bf16 v[48:51], v[234:237], v[190:193], v[48:51]
	v_mfma_f32_16x16x32_bf16 v[44:47], v[226:229], v[202:205], v[44:47]
	v_mfma_f32_16x16x32_bf16 v[40:43], v[234:237], v[202:205], v[40:43]
	v_mfma_f32_16x16x32_bf16 v[36:39], v[226:229], v[210:213], v[36:39]
	v_mfma_f32_16x16x32_bf16 v[32:35], v[234:237], v[210:213], v[32:35]
	v_mfma_f32_16x16x32_bf16 v[60:63], v[230:233], v[186:189], v[60:63]
	v_mfma_f32_16x16x32_bf16 v[56:59], v[238:241], v[186:189], v[56:59]
	v_mfma_f32_16x16x32_bf16 v[52:55], v[230:233], v[194:197], v[52:55]
	v_mfma_f32_16x16x32_bf16 v[48:51], v[238:241], v[194:197], v[48:51]
	v_mfma_f32_16x16x32_bf16 v[44:47], v[230:233], v[206:209], v[44:47]
	v_mfma_f32_16x16x32_bf16 v[40:43], v[238:241], v[206:209], v[40:43]
	v_mfma_f32_16x16x32_bf16 v[36:39], v[230:233], v[214:217], v[36:39]
	s_setprio 0
	v_mfma_f32_16x16x32_bf16 v[32:35], v[238:241], v[214:217], v[32:35]
	s_barrier
	ds_read_b128 v[152:155], v201 offset:49152
	ds_read_b128 v[186:189], v201 offset:50176
	ds_read_b128 v[190:193], v201 offset:51200
	ds_read_b128 v[194:197], v201 offset:52224
	ds_read_b128 v[202:205], v201 offset:53248
	ds_read_b128 v[206:209], v201 offset:54272
	ds_read_b128 v[210:213], v201 offset:55296
	ds_read_b128 v[214:217], v201 offset:56320
	s_add_i32 m0, s34, 0xffffff80
	s_nop 0
	global_load_lds_dwordx4 v142, s[100:101] offset:128
	s_add_i32 m0, s35, 0xffffff80
	s_nop 0
	global_load_lds_dwordx4 v140, s[100:101] offset:128
	s_waitcnt lgkmcnt(0)
	s_setprio 1
	s_barrier
; #define PG8_WAIT_V(n) asm volatile("s_waitcnt vmcnt(" #n ")" ::: "memory")
; template <class Epi>
; DI void gemm_phase(LAS unsigned char* lds, const Gemm g, const StaticOrder& S, const Epi& E) {
;     ...
;             PG8_BAR; PG8_WAIT_L(0); PG8_MMA(1, 0, At, B0); PG8_BAR; PG8_SCHED;
;             PG8_STAGE(PG8_SB(1, 1), b3 + hstep);
;             PG8_WAIT_V(6); PG8_BAR; PG8_MMA(1, 1, At, B1); PG8_BAR;
;         }
;         E(acc, cur, wr, wc, fr, fq);
;     template <bool LN, int BJ, int LO, int HI> DI void batch(const f32x4 (&acc)[2][2][4][2], unsigned row0, unsigned col0, const f32x4 (&gv)[2], const f32x4 (&bv)[2]) const {
;         f32x4 r[HI - LO]; float mean[(HI - LO) / 2], rstd[(HI - LO) / 2];
; #pragma unroll
;         for (int i = LO; i < HI; ++i) { const int ai = i >> 3, m = (i >> 1) & 3, n = i & 1; const unsigned row = row0 + ai * HALF + m * 16;
;             if (n == 0) { mean[(i - LO) >> 1] = 0.f; rstd[(i - LO) >> 1] = 1.f;
;                 if (LN) { const float2 st = *(const float2*)(stats + row * 2u); mean[(i - LO) >> 1] = st.x; rstd[(i - LO) >> 1] = st.y; } }
;             r[i - LO] = *(const f32x4*)(src + (row * (unsigned)DM + col0 + BJ * HALF + n * 16)); }
; #pragma unroll
;         for (int i = LO; i < HI; ++i) { const int ai = i >> 3, m = (i >> 1) & 3, n = i & 1; const unsigned row = row0 + ai * HALF + m * 16;
;             *(f32x4*)(Y + (row * (unsigned)DM + col0 + BJ * HALF + n * 16)) = acc[ai][BJ][m][n] + ((r[i - LO] - mean[(i - LO) >> 1]) * rstd[(i - LO) >> 1]) * gv[n] + bv[n]; }
;         __builtin_amdgcn_sched_barrier(0);
;     }
;     template <bool LN, int BJ> DI void load_gb(unsigned col0, f32x4 (&gv)[2], f32x4 (&bv)[2]) const {
; #pragma unroll
;         for (int n = 0; n < 2; ++n) {
;             if (LN) { gv[n] = *(const f32x4*)(gam + col0 + BJ * HALF + n * 16) * ALPHA; bv[n] = *(const f32x4*)(bet + col0 + BJ * HALF + n * 16) * ALPHA; }
;             else { gv[n] = (f32x4){ALPHA, ALPHA, ALPHA, ALPHA}; bv[n] = (f32x4){0.f, 0.f, 0.f, 0.f}; }
;         }
;     }
;     template <bool LN> DI void run(const f32x4 (&acc)[2][2][4][2], const Unit& u, int wr, int wc, int fr, int fq) const {
;         const unsigned row0 = u.pm * BM + wr * 64 + fr, col0 = u.pn * BM + wc * 32 + 4 * fq;
;         f32x4 gv[2], bv[2];
;         load_gb<LN, 0>(col0, gv, bv);
;         batch<LN, 0, 0, 4>(acc, row0, col0, gv, bv);
	v_mfma_f32_16x16x32_bf16 v[92:95], v[96:99], v[152:155], v[92:95]
	v_mfma_f32_16x16x32_bf16 v[88:91], v[136:139], v[152:155], v[88:91]
	v_mfma_f32_16x16x32_bf16 v[84:87], v[96:99], v[190:193], v[84:87]
	v_mfma_f32_16x16x32_bf16 v[80:83], v[136:139], v[190:193], v[80:83]
	v_mfma_f32_16x16x32_bf16 v[76:79], v[96:99], v[202:205], v[76:79]
	v_mfma_f32_16x16x32_bf16 v[72:75], v[136:139], v[202:205], v[72:75]
	v_mfma_f32_16x16x32_bf16 v[68:71], v[96:99], v[210:213], v[68:71]
	v_mfma_f32_16x16x32_bf16 v[64:67], v[136:139], v[210:213], v[64:67]
	v_mfma_f32_16x16x32_bf16 v[92:95], v[100:103], v[186:189], v[92:95]
	v_mfma_f32_16x16x32_bf16 v[88:91], v[148:151], v[186:189], v[88:91]
	v_mfma_f32_16x16x32_bf16 v[84:87], v[100:103], v[194:197], v[84:87]
	v_mfma_f32_16x16x32_bf16 v[80:83], v[148:151], v[194:197], v[80:83]
	v_mfma_f32_16x16x32_bf16 v[76:79], v[100:103], v[206:209], v[76:79]
	v_mfma_f32_16x16x32_bf16 v[72:75], v[148:151], v[206:209], v[72:75]
	v_mfma_f32_16x16x32_bf16 v[68:71], v[100:103], v[214:217], v[68:71]
	s_setprio 0
	v_mfma_f32_16x16x32_bf16 v[64:67], v[148:151], v[214:217], v[64:67]
	s_barrier
	s_add_u32 s16, s20, 0x160080
	s_addc_u32 s17, s21, 0
	s_add_i32 s20, s22, s27
	s_mov_b32 m0, s20
	s_nop 0
	global_load_lds_dwordx4 v142, s[16:17]
	s_add_i32 m0, s20, 0x2000
	s_nop 0
	global_load_lds_dwordx4 v140, s[16:17]
	s_waitcnt vmcnt(6)
	s_setprio 1
	s_barrier
	v_mfma_f32_16x16x32_bf16 v[28:31], v[226:229], v[152:155], v[28:31]
	v_mfma_f32_16x16x32_bf16 v[24:27], v[234:237], v[152:155], v[24:27]
	v_mfma_f32_16x16x32_bf16 v[20:23], v[226:229], v[190:193], v[20:23]
	v_mfma_f32_16x16x32_bf16 v[16:19], v[234:237], v[190:193], v[16:19]
	v_mfma_f32_16x16x32_bf16 v[12:15], v[226:229], v[202:205], v[12:15]
	v_mfma_f32_16x16x32_bf16 v[8:11], v[234:237], v[202:205], v[8:11]
	v_mfma_f32_16x16x32_bf16 v[4:7], v[226:229], v[210:213], v[4:7]
	v_mfma_f32_16x16x32_bf16 v[0:3], v[234:237], v[210:213], v[0:3]
	v_mfma_f32_16x16x32_bf16 v[28:31], v[230:233], v[186:189], v[28:31]
	s_add_i32 s33, s33, 2
	v_mfma_f32_16x16x32_bf16 v[24:27], v[238:241], v[186:189], v[24:27]
	s_add_u32 s4, s4, 0x100
	v_mfma_f32_16x16x32_bf16 v[20:23], v[230:233], v[194:197], v[20:23]
	s_addc_u32 s5, s5, 0
	v_mfma_f32_16x16x32_bf16 v[16:19], v[238:241], v[194:197], v[16:19]
	s_cmpk_gt_u32 s33, 0x55
	v_mfma_f32_16x16x32_bf16 v[12:15], v[230:233], v[206:209], v[12:15]
	s_mov_b64 s[16:17], s[18:19]
	v_mfma_f32_16x16x32_bf16 v[8:11], v[238:241], v[206:209], v[8:11]
	v_mfma_f32_16x16x32_bf16 v[4:7], v[230:233], v[214:217], v[4:7]
	s_setprio 0
	v_mfma_f32_16x16x32_bf16 v[0:3], v[238:241], v[214:217], v[0:3]
	s_barrier
	s_cbranch_scc0 .LBB0_134
	v_lshl_or_b32 v158, s2, 8, v200
	v_lshlrev_b64 v[100:101], 2, v[158:159]
	v_lshl_add_u64 v[150:151], s[12:13], 0, v[100:101]
	global_load_dwordx4 v[96:99], v[150:151], off
	v_lshl_add_u64 v[152:153], s[14:15], 0, v[100:101]
	v_lshl_add_u32 v203, s3, 8, v198
	v_lshlrev_b32_e32 v202, 11, v203
	v_add_u32_e32 v148, v202, v158
	v_mov_b32_e32 v149, v159
	v_lshlrev_b32_e32 v136, 1, v203
	v_mov_b32_e32 v137, v159
	v_lshlrev_b64 v[220:221], 2, v[148:149]
	v_lshl_add_u64 v[154:155], v[136:137], 2, s[96:97]
	v_lshl_add_u64 v[136:137], s[90:91], 0, v[220:221]
	v_or_b32_e32 v204, 16, v158
	v_or_b32_e32 v138, 16, v203
	v_lshlrev_b32_e32 v149, 11, v138
	s_waitcnt vmcnt(0)
	v_pk_mul_f32 v[192:193], v[98:99], s[78:79] op_sel_hi:[1,0]
	v_pk_mul_f32 v[194:195], v[96:97], s[78:79] op_sel_hi:[1,0]
	global_load_dwordx4 v[100:103], v[152:153], off
	global_load_dwordx4 v[96:99], v[150:151], off offset:64
	global_load_dwordx2 v[218:219], v[154:155], off
	global_load_dwordx4 v[206:209], v[136:137], off
	v_add_u32_e32 v136, v202, v204
	v_mov_b32_e32 v137, v159
	v_lshl_add_u64 v[136:137], v[136:137], 2, s[90:91]
	global_load_dwordx4 v[210:213], v[136:137], off
	v_lshlrev_b32_e32 v136, 1, v138
	v_mov_b32_e32 v137, v159
	v_lshl_add_u64 v[186:187], v[136:137], 2, s[96:97]
	v_add_u32_e32 v136, v149, v158
	v_lshl_add_u64 v[136:137], v[136:137], 2, s[90:91]
	global_load_dwordx2 v[196:197], v[186:187], off
	global_load_dwordx4 v[214:217], v[136:137], off
	v_add_u32_e32 v136, v149, v204
	v_mov_b32_e32 v137, v159
	v_lshl_add_u64 v[136:137], v[136:137], 2, s[90:91]
	global_load_dwordx4 v[136:139], v[136:137], off
	s_waitcnt vmcnt(0)
	v_pk_mul_f32 v[188:189], v[98:99], s[78:79] op_sel_hi:[1,0]
	v_pk_mul_f32 v[190:191], v[96:97], s[78:79] op_sel_hi:[1,0]
	global_load_dwordx4 v[96:99], v[152:153], off offset:64
	v_sub_f32_e32 v207, v207, v218
	v_sub_f32_e32 v206, v206, v218
	v_sub_f32_e32 v209, v209, v218
	v_sub_f32_e32 v208, v208, v218
	v_pk_mul_f32 v[208:209], v[218:219], v[208:209] op_sel:[1,0]
	v_pk_mul_f32 v[206:207], v[218:219], v[206:207] op_sel:[1,0]
	v_pk_fma_f32 v[134:135], v[192:193], v[208:209], v[134:135]
	v_pk_fma_f32 v[132:133], v[194:195], v[206:207], v[132:133]
	v_pk_fma_f32 v[134:135], v[102:103], s[78:79], v[134:135] op_sel_hi:[1,0,1]
	v_pk_fma_f32 v[132:133], v[100:101], s[78:79], v[132:133] op_sel_hi:[1,0,1]
	v_lshl_add_u64 v[206:207], s[88:89], 0, v[220:221]
	global_store_dwordx4 v[206:207], v[132:135], off
	s_nop 1
	v_sub_f32_e32 v133, v211, v218
	v_sub_f32_e32 v132, v210, v218
	v_sub_f32_e32 v135, v213, v218
	v_sub_f32_e32 v134, v212, v218
	v_pk_mul_f32 v[134:135], v[218:219], v[134:135] op_sel:[1,0]
	v_pk_mul_f32 v[132:133], v[218:219], v[132:133] op_sel:[1,0]
	v_pk_fma_f32 v[130:131], v[188:189], v[134:135], v[130:131]
	v_pk_fma_f32 v[128:129], v[190:191], v[132:133], v[128:129]
	v_or_b32_e32 v132, 16, v148
	v_mov_b32_e32 v133, v159
	v_lshl_add_u64 v[132:133], v[132:133], 2, s[88:89]
	s_waitcnt vmcnt(0)
;     template <bool LN, int BJ, int LO, int HI> DI void batch(const f32x4 (&acc)[2][2][4][2], unsigned row0, unsigned col0, const f32x4 (&gv)[2], const f32x4 (&bv)[2]) const {
;         f32x4 r[HI - LO]; float mean[(HI - LO) / 2], rstd[(HI - LO) / 2];
; #pragma unroll
;         for (int i = LO; i < HI; ++i) { const int ai = i >> 3, m = (i >> 1) & 3, n = i & 1; const unsigned row = row0 + ai * HALF + m * 16;
;             if (n == 0) { mean[(i - LO) >> 1] = 0.f; rstd[(i - LO) >> 1] = 1.f;
;                 if (LN) { const float2 st = *(const float2*)(stats + row * 2u); mean[(i - LO) >> 1] = st.x; rstd[(i - LO) >> 1] = st.y; } }
;             r[i - LO] = *(const f32x4*)(src + (row * (unsigned)DM + col0 + BJ * HALF + n * 16)); }
; #pragma unroll
;         for (int i = LO; i < HI; ++i) { const int ai = i >> 3, m = (i >> 1) & 3, n = i & 1; const unsigned row = row0 + ai * HALF + m * 16;
;             *(f32x4*)(Y + (row * (unsigned)DM + col0 + BJ * HALF + n * 16)) = acc[ai][BJ][m][n] + ((r[i - LO] - mean[(i - LO) >> 1]) * rstd[(i - LO) >> 1]) * gv[n] + bv[n]; }
;         __builtin_amdgcn_sched_barrier(0);
;     }
;     template <bool LN, int BJ> DI void load_gb(unsigned col0, f32x4 (&gv)[2], f32x4 (&bv)[2]) const {
; #pragma unroll
;         for (int n = 0; n < 2; ++n) {
;             if (LN) { gv[n] = *(const f32x4*)(gam + col0 + BJ * HALF + n * 16) * ALPHA; bv[n] = *(const f32x4*)(bet + col0 + BJ * HALF + n * 16) * ALPHA; }
;             else { gv[n] = (f32x4){ALPHA, ALPHA, ALPHA, ALPHA}; bv[n] = (f32x4){0.f, 0.f, 0.f, 0.f}; }
;         }
;     }
;     template <bool LN> DI void run(const f32x4 (&acc)[2][2][4][2], const Unit& u, int wr, int wc, int fr, int fq) const {
;         const unsigned row0 = u.pm * BM + wr * 64 + fr, col0 = u.pn * BM + wc * 32 + 4 * fq;
;         f32x4 gv[2], bv[2];
;         load_gb<LN, 0>(col0, gv, bv);
;         batch<LN, 0, 0, 4>(acc, row0, col0, gv, bv);
;         batch<LN, 0, 4, 8>(acc, row0, col0, gv, bv);
;         batch<LN, 0, 8, 12>(acc, row0, col0, gv, bv);
;         batch<LN, 0, 12, 16>(acc, row0, col0, gv, bv);
	v_pk_fma_f32 v[130:131], v[98:99], s[78:79], v[130:131] op_sel_hi:[1,0,1]
	v_pk_fma_f32 v[128:129], v[96:97], s[78:79], v[128:129] op_sel_hi:[1,0,1]
	global_store_dwordx4 v[132:133], v[128:131], off
	s_nop 1
	v_sub_f32_e32 v129, v215, v196
	v_sub_f32_e32 v128, v214, v196
	v_sub_f32_e32 v131, v217, v196
	v_sub_f32_e32 v130, v216, v196
	v_pk_mul_f32 v[130:131], v[196:197], v[130:131] op_sel:[1,0]
	v_pk_mul_f32 v[128:129], v[196:197], v[128:129] op_sel:[1,0]
	v_pk_fma_f32 v[126:127], v[192:193], v[130:131], v[126:127]
	v_pk_fma_f32 v[124:125], v[194:195], v[128:129], v[124:125]
	v_add_u32_e32 v128, 0x8000, v148
	v_mov_b32_e32 v129, v159
	v_pk_fma_f32 v[126:127], v[102:103], s[78:79], v[126:127] op_sel_hi:[1,0,1]
	v_pk_fma_f32 v[124:125], v[100:101], s[78:79], v[124:125] op_sel_hi:[1,0,1]
	v_lshl_add_u64 v[128:129], v[128:129], 2, s[88:89]
	global_store_dwordx4 v[128:129], v[124:127], off
	s_nop 1
	v_sub_f32_e32 v125, v137, v196
	v_sub_f32_e32 v124, v136, v196
	v_sub_f32_e32 v127, v139, v196
	v_sub_f32_e32 v126, v138, v196
	v_pk_mul_f32 v[126:127], v[196:197], v[126:127] op_sel:[1,0]
	v_pk_mul_f32 v[124:125], v[196:197], v[124:125] op_sel:[1,0]
	v_pk_fma_f32 v[122:123], v[188:189], v[126:127], v[122:123]
	v_pk_fma_f32 v[120:121], v[190:191], v[124:125], v[120:121]
	v_add_u32_e32 v124, 0x8010, v148
	v_mov_b32_e32 v125, v159
	v_pk_fma_f32 v[122:123], v[98:99], s[78:79], v[122:123] op_sel_hi:[1,0,1]
	v_pk_fma_f32 v[120:121], v[96:97], s[78:79], v[120:121] op_sel_hi:[1,0,1]
	v_lshl_add_u64 v[124:125], v[124:125], 2, s[88:89]
	global_store_dwordx4 v[124:125], v[120:123], off
	s_nop 1
	v_or_b32_e32 v122, 32, v203
	v_lshlrev_b32_e32 v124, 11, v122
	v_lshlrev_b32_e32 v120, 1, v122
	v_mov_b32_e32 v121, v159
	v_add_u32_e32 v122, v124, v158
	v_mov_b32_e32 v123, v159
	v_lshl_add_u64 v[120:121], v[120:121], 2, s[96:97]
	v_lshl_add_u64 v[122:123], v[122:123], 2, s[90:91]
	global_load_dwordx2 v[138:139], v[120:121], off
	global_load_dwordx4 v[126:129], v[122:123], off
	v_add_u32_e32 v122, v124, v204
	v_mov_b32_e32 v123, v159
	v_lshl_add_u64 v[122:123], v[122:123], 2, s[90:91]
	global_load_dwordx4 v[130:133], v[122:123], off
	v_or_b32_e32 v125, 48, v203
	v_lshlrev_b32_e32 v122, 1, v125
	v_lshlrev_b32_e32 v125, 11, v125
	v_mov_b32_e32 v123, v159
	v_add_u32_e32 v134, v125, v158
	v_mov_b32_e32 v135, v159
	v_lshl_add_u64 v[122:123], v[122:123], 2, s[96:97]
	v_lshl_add_u64 v[134:135], v[134:135], 2, s[90:91]
	global_load_dwordx2 v[196:197], v[122:123], off
	v_add_u32_e32 v206, v125, v204
	global_load_dwordx4 v[134:137], v[134:135], off
	v_mov_b32_e32 v207, v159
	v_lshl_add_u64 v[206:207], v[206:207], 2, s[90:91]
	global_load_dwordx4 v[206:209], v[206:207], off
	s_waitcnt vmcnt(0)
	v_sub_f32_e32 v127, v127, v138
	v_sub_f32_e32 v126, v126, v138
	v_sub_f32_e32 v129, v129, v138
	v_sub_f32_e32 v128, v128, v138
	v_pk_mul_f32 v[128:129], v[138:139], v[128:129] op_sel:[1,0]
	v_pk_mul_f32 v[126:127], v[138:139], v[126:127] op_sel:[1,0]
	v_pk_fma_f32 v[118:119], v[192:193], v[128:129], v[118:119]
	v_pk_fma_f32 v[116:117], v[194:195], v[126:127], v[116:117]
	v_add_u32_e32 v126, 0x10000, v148
	v_mov_b32_e32 v127, v159
	v_pk_fma_f32 v[118:119], v[102:103], s[78:79], v[118:119] op_sel_hi:[1,0,1]
	v_pk_fma_f32 v[116:117], v[100:101], s[78:79], v[116:117] op_sel_hi:[1,0,1]
	v_lshl_add_u64 v[126:127], v[126:127], 2, s[88:89]
	global_store_dwordx4 v[126:127], v[116:119], off
	s_nop 1
	v_sub_f32_e32 v117, v131, v138
	v_sub_f32_e32 v116, v130, v138
	v_sub_f32_e32 v119, v133, v138
	v_sub_f32_e32 v118, v132, v138
	v_pk_mul_f32 v[118:119], v[138:139], v[118:119] op_sel:[1,0]
	v_pk_mul_f32 v[116:117], v[138:139], v[116:117] op_sel:[1,0]
	v_pk_fma_f32 v[114:115], v[188:189], v[118:119], v[114:115]
	v_pk_fma_f32 v[112:113], v[190:191], v[116:117], v[112:113]
	v_add_u32_e32 v116, 0x10010, v148
	v_mov_b32_e32 v117, v159
	v_pk_fma_f32 v[114:115], v[98:99], s[78:79], v[114:115] op_sel_hi:[1,0,1]
	v_pk_fma_f32 v[112:113], v[96:97], s[78:79], v[112:113] op_sel_hi:[1,0,1]
	v_lshl_add_u64 v[116:117], v[116:117], 2, s[88:89]
	global_store_dwordx4 v[116:117], v[112:115], off
	s_nop 1
	v_sub_f32_e32 v113, v135, v196
	v_sub_f32_e32 v112, v134, v196
	v_sub_f32_e32 v115, v137, v196
	v_sub_f32_e32 v114, v136, v196
	v_pk_mul_f32 v[114:115], v[196:197], v[114:115] op_sel:[1,0]
	v_pk_mul_f32 v[112:113], v[196:197], v[112:113] op_sel:[1,0]
	v_pk_fma_f32 v[110:111], v[192:193], v[114:115], v[110:111]
	v_pk_fma_f32 v[108:109], v[194:195], v[112:113], v[108:109]
	v_add_u32_e32 v112, 0x18000, v148
	v_mov_b32_e32 v113, v159
	v_pk_fma_f32 v[110:111], v[102:103], s[78:79], v[110:111] op_sel_hi:[1,0,1]
	v_pk_fma_f32 v[108:109], v[100:101], s[78:79], v[108:109] op_sel_hi:[1,0,1]
	v_lshl_add_u64 v[112:113], v[112:113], 2, s[88:89]
	global_store_dwordx4 v[112:113], v[108:111], off
	s_nop 1
	v_sub_f32_e32 v109, v207, v196
	v_sub_f32_e32 v108, v206, v196
	v_sub_f32_e32 v111, v209, v196
	v_sub_f32_e32 v110, v208, v196
	v_pk_mul_f32 v[110:111], v[196:197], v[110:111] op_sel:[1,0]
	v_pk_mul_f32 v[108:109], v[196:197], v[108:109] op_sel:[1,0]
	v_pk_fma_f32 v[106:107], v[188:189], v[110:111], v[106:107]
	v_pk_fma_f32 v[104:105], v[190:191], v[108:109], v[104:105]
	v_add_u32_e32 v108, 0x18010, v148
	v_mov_b32_e32 v109, v159
	v_pk_fma_f32 v[106:107], v[98:99], s[78:79], v[106:107] op_sel_hi:[1,0,1]
	v_pk_fma_f32 v[104:105], v[96:97], s[78:79], v[104:105] op_sel_hi:[1,0,1]
	v_lshl_add_u64 v[108:109], v[108:109], 2, s[88:89]
	global_store_dwordx4 v[108:109], v[104:107], off
	s_nop 1
	v_add_u32_e32 v106, 0x80, v203
	v_lshlrev_b32_e32 v114, 11, v106
	v_lshlrev_b32_e32 v104, 1, v106
	v_mov_b32_e32 v105, v159
	v_add_u32_e32 v106, v114, v158
	v_mov_b32_e32 v107, v159
	v_lshl_add_u64 v[104:105], v[104:105], 2, s[96:97]
	v_lshl_add_u64 v[106:107], v[106:107], 2, s[90:91]
	global_load_dwordx2 v[112:113], v[104:105], off
	global_load_dwordx4 v[108:111], v[106:107], off
	v_add_u32_e32 v106, v114, v204
	v_mov_b32_e32 v107, v159
	v_lshl_add_u64 v[106:107], v[106:107], 2, s[90:91]
	global_load_dwordx4 v[116:119], v[106:107], off
	v_add_u32_e32 v115, 0x90, v203
	v_lshlrev_b32_e32 v106, 1, v115
	v_lshlrev_b32_e32 v115, 11, v115
	v_mov_b32_e32 v107, v159
	v_add_u32_e32 v126, v115, v158
	v_mov_b32_e32 v127, v159
	v_lshl_add_u64 v[106:107], v[106:107], 2, s[96:97]
	v_lshl_add_u64 v[126:127], v[126:127], 2, s[90:91]
	global_load_dwordx2 v[134:135], v[106:107], off
	v_add_u32_e32 v130, v115, v204
	global_load_dwordx4 v[126:129], v[126:127], off
	v_mov_b32_e32 v131, v159
	v_lshl_add_u64 v[130:131], v[130:131], 2, s[90:91]
	global_load_dwordx4 v[130:133], v[130:131], off
	s_waitcnt vmcnt(0)
;     template <bool LN, int BJ, int LO, int HI> DI void batch(const f32x4 (&acc)[2][2][4][2], unsigned row0, unsigned col0, const f32x4 (&gv)[2], const f32x4 (&bv)[2]) const {
;         f32x4 r[HI - LO]; float mean[(HI - LO) / 2], rstd[(HI - LO) / 2];
; #pragma unroll
;         for (int i = LO; i < HI; ++i) { const int ai = i >> 3, m = (i >> 1) & 3, n = i & 1; const unsigned row = row0 + ai * HALF + m * 16;
;             if (n == 0) { mean[(i - LO) >> 1] = 0.f; rstd[(i - LO) >> 1] = 1.f;
;                 if (LN) { const float2 st = *(const float2*)(stats + row * 2u); mean[(i - LO) >> 1] = st.x; rstd[(i - LO) >> 1] = st.y; } }
;             r[i - LO] = *(const f32x4*)(src + (row * (unsigned)DM + col0 + BJ * HALF + n * 16)); }
; #pragma unroll
;         for (int i = LO; i < HI; ++i) { const int ai = i >> 3, m = (i >> 1) & 3, n = i & 1; const unsigned row = row0 + ai * HALF + m * 16;
;             *(f32x4*)(Y + (row * (unsigned)DM + col0 + BJ * HALF + n * 16)) = acc[ai][BJ][m][n] + ((r[i - LO] - mean[(i - LO) >> 1]) * rstd[(i - LO) >> 1]) * gv[n] + bv[n]; }
;         __builtin_amdgcn_sched_barrier(0);
;     }
;     template <bool LN, int BJ> DI void load_gb(unsigned col0, f32x4 (&gv)[2], f32x4 (&bv)[2]) const {
; #pragma unroll
;         for (int n = 0; n < 2; ++n) {
;             if (LN) { gv[n] = *(const f32x4*)(gam + col0 + BJ * HALF + n * 16) * ALPHA; bv[n] = *(const f32x4*)(bet + col0 + BJ * HALF + n * 16) * ALPHA; }
;             else { gv[n] = (f32x4){ALPHA, ALPHA, ALPHA, ALPHA}; bv[n] = (f32x4){0.f, 0.f, 0.f, 0.f}; }
;         }
;     }
;     template <bool LN> DI void run(const f32x4 (&acc)[2][2][4][2], const Unit& u, int wr, int wc, int fr, int fq) const {
;         const unsigned row0 = u.pm * BM + wr * 64 + fr, col0 = u.pn * BM + wc * 32 + 4 * fq;
;         f32x4 gv[2], bv[2];
;         load_gb<LN, 0>(col0, gv, bv);
;         batch<LN, 0, 0, 4>(acc, row0, col0, gv, bv);
;         batch<LN, 0, 4, 8>(acc, row0, col0, gv, bv);
;         batch<LN, 0, 8, 12>(acc, row0, col0, gv, bv);
;         batch<LN, 0, 12, 16>(acc, row0, col0, gv, bv);
;         load_gb<LN, 1>(col0, gv, bv);
	v_sub_f32_e32 v109, v109, v112
	v_sub_f32_e32 v108, v108, v112
	v_sub_f32_e32 v111, v111, v112
	v_sub_f32_e32 v110, v110, v112
	v_pk_mul_f32 v[110:111], v[112:113], v[110:111] op_sel:[1,0]
	v_pk_mul_f32 v[108:109], v[112:113], v[108:109] op_sel:[1,0]
	v_pk_fma_f32 v[94:95], v[192:193], v[110:111], v[94:95]
	v_pk_fma_f32 v[92:93], v[194:195], v[108:109], v[92:93]
	v_add_u32_e32 v108, 0x40000, v148
	v_mov_b32_e32 v109, v159
	v_pk_fma_f32 v[94:95], v[102:103], s[78:79], v[94:95] op_sel_hi:[1,0,1]
	v_pk_fma_f32 v[92:93], v[100:101], s[78:79], v[92:93] op_sel_hi:[1,0,1]
	v_lshl_add_u64 v[108:109], v[108:109], 2, s[88:89]
	global_store_dwordx4 v[108:109], v[92:95], off
	s_nop 1
	v_sub_f32_e32 v93, v117, v112
	v_sub_f32_e32 v92, v116, v112
	v_sub_f32_e32 v95, v119, v112
	v_sub_f32_e32 v94, v118, v112
	v_pk_mul_f32 v[94:95], v[112:113], v[94:95] op_sel:[1,0]
	v_pk_mul_f32 v[92:93], v[112:113], v[92:93] op_sel:[1,0]
	v_pk_fma_f32 v[90:91], v[188:189], v[94:95], v[90:91]
	v_pk_fma_f32 v[88:89], v[190:191], v[92:93], v[88:89]
	v_add_u32_e32 v92, 0x40010, v148
	v_mov_b32_e32 v93, v159
	v_pk_fma_f32 v[90:91], v[98:99], s[78:79], v[90:91] op_sel_hi:[1,0,1]
	v_pk_fma_f32 v[88:89], v[96:97], s[78:79], v[88:89] op_sel_hi:[1,0,1]
	v_lshl_add_u64 v[92:93], v[92:93], 2, s[88:89]
	global_store_dwordx4 v[92:93], v[88:91], off
	s_nop 1
	v_sub_f32_e32 v89, v127, v134
	v_sub_f32_e32 v88, v126, v134
	v_sub_f32_e32 v91, v129, v134
	v_sub_f32_e32 v90, v128, v134
	v_pk_mul_f32 v[90:91], v[134:135], v[90:91] op_sel:[1,0]
	v_pk_mul_f32 v[88:89], v[134:135], v[88:89] op_sel:[1,0]
	v_pk_fma_f32 v[86:87], v[192:193], v[90:91], v[86:87]
	v_pk_fma_f32 v[84:85], v[194:195], v[88:89], v[84:85]
	v_add_u32_e32 v88, 0x48000, v148
	v_mov_b32_e32 v89, v159
	v_pk_fma_f32 v[86:87], v[102:103], s[78:79], v[86:87] op_sel_hi:[1,0,1]
	v_pk_fma_f32 v[84:85], v[100:101], s[78:79], v[84:85] op_sel_hi:[1,0,1]
	v_lshl_add_u64 v[88:89], v[88:89], 2, s[88:89]
	global_store_dwordx4 v[88:89], v[84:87], off
	s_nop 1
	v_sub_f32_e32 v85, v131, v134
	v_sub_f32_e32 v84, v130, v134
	v_sub_f32_e32 v87, v133, v134
	v_sub_f32_e32 v86, v132, v134
	v_pk_mul_f32 v[86:87], v[134:135], v[86:87] op_sel:[1,0]
	v_pk_mul_f32 v[84:85], v[134:135], v[84:85] op_sel:[1,0]
	v_pk_fma_f32 v[82:83], v[188:189], v[86:87], v[82:83]
	v_pk_fma_f32 v[80:81], v[190:191], v[84:85], v[80:81]
	v_add_u32_e32 v84, 0x48010, v148
	v_mov_b32_e32 v85, v159
	v_pk_fma_f32 v[82:83], v[98:99], s[78:79], v[82:83] op_sel_hi:[1,0,1]
	v_pk_fma_f32 v[80:81], v[96:97], s[78:79], v[80:81] op_sel_hi:[1,0,1]
	v_lshl_add_u64 v[84:85], v[84:85], 2, s[88:89]
	global_store_dwordx4 v[84:85], v[80:83], off
	s_nop 1
	v_add_u32_e32 v82, 0xa0, v203
	v_lshlrev_b32_e32 v80, 1, v82
	v_mov_b32_e32 v81, v159
	v_lshlrev_b32_e32 v116, 11, v82
	v_lshl_add_u64 v[108:109], v[80:81], 2, s[96:97]
	v_add_u32_e32 v80, v116, v158
	v_lshl_add_u64 v[80:81], v[80:81], 2, s[90:91]
	global_load_dwordx2 v[112:113], v[108:109], off
	v_add_u32_e32 v84, v116, v204
	global_load_dwordx4 v[80:83], v[80:81], off
	v_mov_b32_e32 v85, v159
	v_lshl_add_u64 v[84:85], v[84:85], 2, s[90:91]
	global_load_dwordx4 v[84:87], v[84:85], off
	v_add_u32_e32 v90, 0xb0, v203
	v_lshlrev_b32_e32 v88, 1, v90
	v_mov_b32_e32 v89, v159
	v_lshlrev_b32_e32 v117, 11, v90
	v_lshl_add_u64 v[110:111], v[88:89], 2, s[96:97]
	v_add_u32_e32 v88, v117, v158
	v_lshl_add_u64 v[88:89], v[88:89], 2, s[90:91]
	global_load_dwordx2 v[118:119], v[110:111], off
	v_add_u32_e32 v92, v117, v204
	global_load_dwordx4 v[88:91], v[88:89], off
	v_mov_b32_e32 v93, v159
	v_lshl_add_u64 v[92:93], v[92:93], 2, s[90:91]
	global_load_dwordx4 v[92:95], v[92:93], off
	s_waitcnt vmcnt(0)
	v_sub_f32_e32 v81, v81, v112
	v_sub_f32_e32 v80, v80, v112
	v_sub_f32_e32 v83, v83, v112
	v_sub_f32_e32 v82, v82, v112
	v_pk_mul_f32 v[82:83], v[112:113], v[82:83] op_sel:[1,0]
	v_pk_mul_f32 v[80:81], v[112:113], v[80:81] op_sel:[1,0]
	v_pk_fma_f32 v[78:79], v[192:193], v[82:83], v[78:79]
	v_pk_fma_f32 v[76:77], v[194:195], v[80:81], v[76:77]
	v_add_u32_e32 v80, 0x50000, v148
	v_mov_b32_e32 v81, v159
	v_pk_fma_f32 v[78:79], v[102:103], s[78:79], v[78:79] op_sel_hi:[1,0,1]
	v_pk_fma_f32 v[76:77], v[100:101], s[78:79], v[76:77] op_sel_hi:[1,0,1]
	v_lshl_add_u64 v[80:81], v[80:81], 2, s[88:89]
	global_store_dwordx4 v[80:81], v[76:79], off
	s_nop 1
	v_sub_f32_e32 v77, v85, v112
	v_sub_f32_e32 v76, v84, v112
	v_sub_f32_e32 v79, v87, v112
	v_sub_f32_e32 v78, v86, v112
	v_pk_mul_f32 v[78:79], v[112:113], v[78:79] op_sel:[1,0]
	v_pk_mul_f32 v[76:77], v[112:113], v[76:77] op_sel:[1,0]
	v_pk_fma_f32 v[74:75], v[188:189], v[78:79], v[74:75]
	v_pk_fma_f32 v[72:73], v[190:191], v[76:77], v[72:73]
	v_add_u32_e32 v76, 0x50010, v148
	v_mov_b32_e32 v77, v159
	v_pk_fma_f32 v[74:75], v[98:99], s[78:79], v[74:75] op_sel_hi:[1,0,1]
	v_pk_fma_f32 v[72:73], v[96:97], s[78:79], v[72:73] op_sel_hi:[1,0,1]
	v_lshl_add_u64 v[76:77], v[76:77], 2, s[88:89]
	global_store_dwordx4 v[76:77], v[72:75], off
	s_nop 1
	v_sub_f32_e32 v73, v89, v118
	v_sub_f32_e32 v72, v88, v118
	v_sub_f32_e32 v75, v91, v118
	v_sub_f32_e32 v74, v90, v118
	v_pk_mul_f32 v[74:75], v[118:119], v[74:75] op_sel:[1,0]
	v_pk_mul_f32 v[72:73], v[118:119], v[72:73] op_sel:[1,0]
	v_pk_fma_f32 v[70:71], v[192:193], v[74:75], v[70:71]
	v_pk_fma_f32 v[68:69], v[194:195], v[72:73], v[68:69]
	v_add_u32_e32 v72, 0x58000, v148
	v_mov_b32_e32 v73, v159
	v_pk_fma_f32 v[70:71], v[102:103], s[78:79], v[70:71] op_sel_hi:[1,0,1]
	v_pk_fma_f32 v[68:69], v[100:101], s[78:79], v[68:69] op_sel_hi:[1,0,1]
	v_lshl_add_u64 v[72:73], v[72:73], 2, s[88:89]
	global_store_dwordx4 v[72:73], v[68:71], off
	s_nop 1
	v_sub_f32_e32 v69, v93, v118
	v_sub_f32_e32 v68, v92, v118
	v_sub_f32_e32 v71, v95, v118
	v_sub_f32_e32 v70, v94, v118
	v_pk_mul_f32 v[70:71], v[118:119], v[70:71] op_sel:[1,0]
	v_pk_mul_f32 v[68:69], v[118:119], v[68:69] op_sel:[1,0]
	v_pk_fma_f32 v[66:67], v[188:189], v[70:71], v[66:67]
	v_pk_fma_f32 v[64:65], v[190:191], v[68:69], v[64:65]
	v_add_u32_e32 v68, 0x58010, v148
	v_mov_b32_e32 v69, v159
	v_pk_fma_f32 v[66:67], v[98:99], s[78:79], v[66:67] op_sel_hi:[1,0,1]
	v_pk_fma_f32 v[64:65], v[96:97], s[78:79], v[64:65] op_sel_hi:[1,0,1]
	v_lshl_add_u64 v[68:69], v[68:69], 2, s[88:89]
	global_store_dwordx4 v[68:69], v[64:67], off
	global_load_dwordx4 v[64:67], v[150:151], off offset:512
	v_or_b32_e32 v119, 0x80, v158
	v_add_u32_e32 v72, v202, v119
	v_mov_b32_e32 v73, v159
	v_lshl_add_u64 v[72:73], v[72:73], 2, s[90:91]
	v_or_b32_e32 v118, 0x90, v158
	v_add_u32_e32 v158, v202, v118
	s_waitcnt vmcnt(0)
;     template <bool LN, int BJ, int LO, int HI> DI void batch(const f32x4 (&acc)[2][2][4][2], unsigned row0, unsigned col0, const f32x4 (&gv)[2], const f32x4 (&bv)[2]) const {
;         f32x4 r[HI - LO]; float mean[(HI - LO) / 2], rstd[(HI - LO) / 2];
; #pragma unroll
;         for (int i = LO; i < HI; ++i) { const int ai = i >> 3, m = (i >> 1) & 3, n = i & 1; const unsigned row = row0 + ai * HALF + m * 16;
;             if (n == 0) { mean[(i - LO) >> 1] = 0.f; rstd[(i - LO) >> 1] = 1.f;
;                 if (LN) { const float2 st = *(const float2*)(stats + row * 2u); mean[(i - LO) >> 1] = st.x; rstd[(i - LO) >> 1] = st.y; } }
;             r[i - LO] = *(const f32x4*)(src + (row * (unsigned)DM + col0 + BJ * HALF + n * 16)); }
; #pragma unroll
;         for (int i = LO; i < HI; ++i) { const int ai = i >> 3, m = (i >> 1) & 3, n = i & 1; const unsigned row = row0 + ai * HALF + m * 16;
;             *(f32x4*)(Y + (row * (unsigned)DM + col0 + BJ * HALF + n * 16)) = acc[ai][BJ][m][n] + ((r[i - LO] - mean[(i - LO) >> 1]) * rstd[(i - LO) >> 1]) * gv[n] + bv[n]; }
;         __builtin_amdgcn_sched_barrier(0);
;     }
;     template <bool LN, int BJ> DI void load_gb(unsigned col0, f32x4 (&gv)[2], f32x4 (&bv)[2]) const {
; #pragma unroll
;         for (int n = 0; n < 2; ++n) {
;             if (LN) { gv[n] = *(const f32x4*)(gam + col0 + BJ * HALF + n * 16) * ALPHA; bv[n] = *(const f32x4*)(bet + col0 + BJ * HALF + n * 16) * ALPHA; }
;             else { gv[n] = (f32x4){ALPHA, ALPHA, ALPHA, ALPHA}; bv[n] = (f32x4){0.f, 0.f, 0.f, 0.f}; }
;         }
;     }
;     template <bool LN> DI void run(const f32x4 (&acc)[2][2][4][2], const Unit& u, int wr, int wc, int fr, int fq) const {
;         const unsigned row0 = u.pm * BM + wr * 64 + fr, col0 = u.pn * BM + wc * 32 + 4 * fq;
;         f32x4 gv[2], bv[2];
;         load_gb<LN, 0>(col0, gv, bv);
;         batch<LN, 0, 0, 4>(acc, row0, col0, gv, bv);
;         batch<LN, 0, 4, 8>(acc, row0, col0, gv, bv);
;         batch<LN, 0, 8, 12>(acc, row0, col0, gv, bv);
;         batch<LN, 0, 12, 16>(acc, row0, col0, gv, bv);
;         load_gb<LN, 1>(col0, gv, bv);
;         batch<LN, 1, 0, 8>(acc, row0, col0, gv, bv);
;         batch<LN, 1, 8, 16>(acc, row0, col0, gv, bv);
	v_pk_mul_f32 v[96:97], v[66:67], s[78:79] op_sel_hi:[1,0]
	v_pk_mul_f32 v[98:99], v[64:65], s[78:79] op_sel_hi:[1,0]
	global_load_dwordx4 v[68:71], v[152:153], off offset:512
	global_load_dwordx4 v[64:67], v[150:151], off offset:576
	global_load_dwordx2 v[138:139], v[154:155], off
	global_load_dwordx4 v[126:129], v[72:73], off
	v_lshl_add_u64 v[72:73], v[158:159], 2, s[90:91]
	v_add_u32_e32 v158, v149, v119
	s_waitcnt vmcnt(0)
	v_pk_mul_f32 v[92:93], v[66:67], s[78:79] op_sel_hi:[1,0]
	v_pk_mul_f32 v[94:95], v[64:65], s[78:79] op_sel_hi:[1,0]
	global_load_dwordx4 v[64:67], v[152:153], off offset:576
	global_load_dwordx4 v[130:133], v[72:73], off
	global_load_dwordx2 v[112:113], v[186:187], off
	v_lshl_add_u64 v[72:73], v[158:159], 2, s[90:91]
	global_load_dwordx4 v[134:137], v[72:73], off
	v_add_u32_e32 v158, v149, v118
	v_lshl_add_u64 v[72:73], v[158:159], 2, s[90:91]
	global_load_dwordx4 v[88:91], v[72:73], off
	global_load_dwordx2 v[102:103], v[120:121], off
	v_add_u32_e32 v158, v124, v119
	v_lshl_add_u64 v[72:73], v[158:159], 2, s[90:91]
	global_load_dwordx4 v[84:87], v[72:73], off
	v_add_u32_e32 v158, v124, v118
	v_lshl_add_u64 v[72:73], v[158:159], 2, s[90:91]
	global_load_dwordx4 v[80:83], v[72:73], off
	global_load_dwordx2 v[100:101], v[122:123], off
	v_add_u32_e32 v158, v125, v119
	v_lshl_add_u64 v[72:73], v[158:159], 2, s[90:91]
	global_load_dwordx4 v[76:79], v[72:73], off
	v_add_u32_e32 v158, v125, v118
	v_lshl_add_u64 v[72:73], v[158:159], 2, s[90:91]
	global_load_dwordx4 v[72:75], v[72:73], off
	v_sub_f32_e32 v121, v127, v138
	v_sub_f32_e32 v120, v126, v138
	v_sub_f32_e32 v123, v129, v138
	v_sub_f32_e32 v122, v128, v138
	v_pk_mul_f32 v[122:123], v[138:139], v[122:123] op_sel:[1,0]
	v_pk_mul_f32 v[120:121], v[138:139], v[120:121] op_sel:[1,0]
	v_or_b32_e32 v158, 0x80, v148
	v_pk_fma_f32 v[60:61], v[98:99], v[120:121], v[60:61]
	v_pk_fma_f32 v[62:63], v[96:97], v[122:123], v[62:63]
	v_pk_fma_f32 v[60:61], v[68:69], s[78:79], v[60:61] op_sel_hi:[1,0,1]
	v_pk_fma_f32 v[62:63], v[70:71], s[78:79], v[62:63] op_sel_hi:[1,0,1]
	v_lshl_add_u64 v[120:121], v[158:159], 2, s[88:89]
	global_store_dwordx4 v[120:121], v[60:63], off
	v_or_b32_e32 v158, 0x90, v148
	s_waitcnt vmcnt(0)
	v_sub_f32_e32 v61, v131, v138
	v_sub_f32_e32 v60, v130, v138
	v_sub_f32_e32 v63, v133, v138
	v_sub_f32_e32 v62, v132, v138
	v_pk_mul_f32 v[62:63], v[138:139], v[62:63] op_sel:[1,0]
	v_pk_mul_f32 v[60:61], v[138:139], v[60:61] op_sel:[1,0]
	v_pk_fma_f32 v[58:59], v[92:93], v[62:63], v[58:59]
	v_pk_fma_f32 v[56:57], v[94:95], v[60:61], v[56:57]
	v_pk_fma_f32 v[58:59], v[66:67], s[78:79], v[58:59] op_sel_hi:[1,0,1]
	v_pk_fma_f32 v[56:57], v[64:65], s[78:79], v[56:57] op_sel_hi:[1,0,1]
	v_lshl_add_u64 v[60:61], v[158:159], 2, s[88:89]
	global_store_dwordx4 v[60:61], v[56:59], off
	v_add_u32_e32 v158, 0x8080, v148
	s_nop 0
	v_sub_f32_e32 v57, v135, v112
	v_sub_f32_e32 v56, v134, v112
	v_sub_f32_e32 v59, v137, v112
	v_sub_f32_e32 v58, v136, v112
	v_pk_mul_f32 v[58:59], v[112:113], v[58:59] op_sel:[1,0]
	v_pk_mul_f32 v[56:57], v[112:113], v[56:57] op_sel:[1,0]
	v_pk_fma_f32 v[54:55], v[96:97], v[58:59], v[54:55]
	v_pk_fma_f32 v[52:53], v[98:99], v[56:57], v[52:53]
	v_pk_fma_f32 v[54:55], v[70:71], s[78:79], v[54:55] op_sel_hi:[1,0,1]
	v_pk_fma_f32 v[52:53], v[68:69], s[78:79], v[52:53] op_sel_hi:[1,0,1]
	v_lshl_add_u64 v[56:57], v[158:159], 2, s[88:89]
	global_store_dwordx4 v[56:57], v[52:55], off
	v_add_u32_e32 v158, 0x8090, v148
	s_nop 0
	v_sub_f32_e32 v53, v89, v112
	v_sub_f32_e32 v52, v88, v112
	v_sub_f32_e32 v55, v91, v112
	v_sub_f32_e32 v54, v90, v112
	v_pk_mul_f32 v[54:55], v[112:113], v[54:55] op_sel:[1,0]
	v_pk_mul_f32 v[52:53], v[112:113], v[52:53] op_sel:[1,0]
	v_pk_fma_f32 v[50:51], v[92:93], v[54:55], v[50:51]
	v_pk_fma_f32 v[48:49], v[94:95], v[52:53], v[48:49]
	v_pk_fma_f32 v[50:51], v[66:67], s[78:79], v[50:51] op_sel_hi:[1,0,1]
	v_pk_fma_f32 v[48:49], v[64:65], s[78:79], v[48:49] op_sel_hi:[1,0,1]
	v_lshl_add_u64 v[52:53], v[158:159], 2, s[88:89]
	global_store_dwordx4 v[52:53], v[48:51], off
	v_add_u32_e32 v158, 0x10080, v148
	s_nop 0
	v_sub_f32_e32 v49, v85, v102
	v_sub_f32_e32 v48, v84, v102
	v_sub_f32_e32 v51, v87, v102
	v_sub_f32_e32 v50, v86, v102
	v_pk_mul_f32 v[50:51], v[102:103], v[50:51] op_sel:[1,0]
	v_pk_mul_f32 v[48:49], v[102:103], v[48:49] op_sel:[1,0]
	v_pk_fma_f32 v[46:47], v[96:97], v[50:51], v[46:47]
	v_pk_fma_f32 v[44:45], v[98:99], v[48:49], v[44:45]
	v_pk_fma_f32 v[46:47], v[70:71], s[78:79], v[46:47] op_sel_hi:[1,0,1]
	v_pk_fma_f32 v[44:45], v[68:69], s[78:79], v[44:45] op_sel_hi:[1,0,1]
	v_lshl_add_u64 v[48:49], v[158:159], 2, s[88:89]
	global_store_dwordx4 v[48:49], v[44:47], off
	v_add_u32_e32 v158, 0x10090, v148
	s_nop 0
	v_sub_f32_e32 v45, v81, v102
	v_sub_f32_e32 v44, v80, v102
	v_sub_f32_e32 v47, v83, v102
	v_sub_f32_e32 v46, v82, v102
	v_pk_mul_f32 v[46:47], v[102:103], v[46:47] op_sel:[1,0]
	v_pk_mul_f32 v[44:45], v[102:103], v[44:45] op_sel:[1,0]
	v_pk_fma_f32 v[42:43], v[92:93], v[46:47], v[42:43]
	v_pk_fma_f32 v[40:41], v[94:95], v[44:45], v[40:41]
	v_pk_fma_f32 v[42:43], v[66:67], s[78:79], v[42:43] op_sel_hi:[1,0,1]
	v_pk_fma_f32 v[40:41], v[64:65], s[78:79], v[40:41] op_sel_hi:[1,0,1]
	v_lshl_add_u64 v[44:45], v[158:159], 2, s[88:89]
	global_store_dwordx4 v[44:45], v[40:43], off
	v_add_u32_e32 v158, 0x18080, v148
	s_nop 0
	v_sub_f32_e32 v41, v77, v100
	v_sub_f32_e32 v40, v76, v100
	v_sub_f32_e32 v43, v79, v100
	v_sub_f32_e32 v42, v78, v100
	v_pk_mul_f32 v[42:43], v[100:101], v[42:43] op_sel:[1,0]
	v_pk_mul_f32 v[40:41], v[100:101], v[40:41] op_sel:[1,0]
	v_pk_fma_f32 v[38:39], v[96:97], v[42:43], v[38:39]
;     template <bool LN, int BJ, int LO, int HI> DI void batch(const f32x4 (&acc)[2][2][4][2], unsigned row0, unsigned col0, const f32x4 (&gv)[2], const f32x4 (&bv)[2]) const {
;         f32x4 r[HI - LO]; float mean[(HI - LO) / 2], rstd[(HI - LO) / 2];
; #pragma unroll
;         for (int i = LO; i < HI; ++i) { const int ai = i >> 3, m = (i >> 1) & 3, n = i & 1; const unsigned row = row0 + ai * HALF + m * 16;
;             if (n == 0) { mean[(i - LO) >> 1] = 0.f; rstd[(i - LO) >> 1] = 1.f;
;                 if (LN) { const float2 st = *(const float2*)(stats + row * 2u); mean[(i - LO) >> 1] = st.x; rstd[(i - LO) >> 1] = st.y; } }
;             r[i - LO] = *(const f32x4*)(src + (row * (unsigned)DM + col0 + BJ * HALF + n * 16)); }
; #pragma unroll
;         for (int i = LO; i < HI; ++i) { const int ai = i >> 3, m = (i >> 1) & 3, n = i & 1; const unsigned row = row0 + ai * HALF + m * 16;
;             *(f32x4*)(Y + (row * (unsigned)DM + col0 + BJ * HALF + n * 16)) = acc[ai][BJ][m][n] + ((r[i - LO] - mean[(i - LO) >> 1]) * rstd[(i - LO) >> 1]) * gv[n] + bv[n]; }
	v_pk_fma_f32 v[36:37], v[98:99], v[40:41], v[36:37]
	v_pk_fma_f32 v[38:39], v[70:71], s[78:79], v[38:39] op_sel_hi:[1,0,1]
	v_pk_fma_f32 v[36:37], v[68:69], s[78:79], v[36:37] op_sel_hi:[1,0,1]
	v_lshl_add_u64 v[40:41], v[158:159], 2, s[88:89]
	global_store_dwordx4 v[40:41], v[36:39], off
	v_add_u32_e32 v158, 0x18090, v148
	s_nop 0
	v_sub_f32_e32 v37, v73, v100
	v_sub_f32_e32 v36, v72, v100
	v_sub_f32_e32 v39, v75, v100
	v_sub_f32_e32 v38, v74, v100
	v_pk_mul_f32 v[38:39], v[100:101], v[38:39] op_sel:[1,0]
	v_pk_mul_f32 v[36:37], v[100:101], v[36:37] op_sel:[1,0]
	v_pk_fma_f32 v[34:35], v[92:93], v[38:39], v[34:35]
	v_pk_fma_f32 v[32:33], v[94:95], v[36:37], v[32:33]
	v_pk_fma_f32 v[34:35], v[66:67], s[78:79], v[34:35] op_sel_hi:[1,0,1]
	v_pk_fma_f32 v[32:33], v[64:65], s[78:79], v[32:33] op_sel_hi:[1,0,1]
	v_lshl_add_u64 v[36:37], v[158:159], 2, s[88:89]
	global_store_dwordx4 v[36:37], v[32:35], off
	v_add_u32_e32 v158, v114, v119
	s_nop 0
	v_lshl_add_u64 v[32:33], v[158:159], 2, s[90:91]
	global_load_dwordx2 v[62:63], v[104:105], off
	global_load_dwordx4 v[54:57], v[32:33], off
	v_add_u32_e32 v158, v114, v118
	v_lshl_add_u64 v[32:33], v[158:159], 2, s[90:91]
	global_load_dwordx4 v[58:61], v[32:33], off
	global_load_dwordx2 v[52:53], v[106:107], off
	v_add_u32_e32 v158, v115, v119
	v_lshl_add_u64 v[32:33], v[158:159], 2, s[90:91]
	global_load_dwordx4 v[72:75], v[32:33], off
	v_add_u32_e32 v158, v115, v118
	v_lshl_add_u64 v[32:33], v[158:159], 2, s[90:91]
	global_load_dwordx4 v[76:79], v[32:33], off
	global_load_dwordx2 v[50:51], v[108:109], off
	v_add_u32_e32 v158, v116, v119
	v_lshl_add_u64 v[32:33], v[158:159], 2, s[90:91]
	global_load_dwordx4 v[44:47], v[32:33], off
	v_add_u32_e32 v158, v116, v118
	v_lshl_add_u64 v[32:33], v[158:159], 2, s[90:91]
	global_load_dwordx4 v[40:43], v[32:33], off
	global_load_dwordx2 v[48:49], v[110:111], off
	v_add_u32_e32 v158, v117, v119
	v_lshl_add_u64 v[32:33], v[158:159], 2, s[90:91]
	global_load_dwordx4 v[36:39], v[32:33], off
	v_add_u32_e32 v158, v117, v118
	v_lshl_add_u64 v[32:33], v[158:159], 2, s[90:91]
	global_load_dwordx4 v[32:35], v[32:33], off
	v_add_u32_e32 v158, 0x40080, v148
	s_waitcnt vmcnt(0)
; #define PG8_WAIT_V(n) asm volatile("s_waitcnt vmcnt(" #n ")" ::: "memory")
; #define PG8_BAR __builtin_amdgcn_s_barrier()
; template <class Epi>
; DI void gemm_phase(LAS unsigned char* lds, const Gemm g, const StaticOrder& S, const Epi& E) {
;     ...
;         E(acc, cur, wr, wc, fr, fq);
;         if (!has_next) break;
; #pragma unroll
;         for (int a = 0; a < 2; ++a)
; #pragma unroll
;             for (int b = 0; b < 2; ++b)
; #pragma unroll
;                 for (int m = 0; m < 4; ++m)
; #pragma unroll
;                     for (int n = 0; n < 2; ++n) acc[a][b][m][n] = (f32x4){0.f, 0.f, 0.f, 0.f};
;         cur = nxt; cA = nA; cB = nB; ++ui;
;     }
;     PG8_WAIT_V(0);
;     if (wr == 0) PG8_BAR;
;     PG8_BAR;
;     template <bool LN, int BJ, int LO, int HI> DI void batch(const f32x4 (&acc)[2][2][4][2], unsigned row0, unsigned col0, const f32x4 (&gv)[2], const f32x4 (&bv)[2]) const {
;         f32x4 r[HI - LO]; float mean[(HI - LO) / 2], rstd[(HI - LO) / 2];
; #pragma unroll
;         for (int i = LO; i < HI; ++i) { const int ai = i >> 3, m = (i >> 1) & 3, n = i & 1; const unsigned row = row0 + ai * HALF + m * 16;
;             if (n == 0) { mean[(i - LO) >> 1] = 0.f; rstd[(i - LO) >> 1] = 1.f;
;                 if (LN) { const float2 st = *(const float2*)(stats + row * 2u); mean[(i - LO) >> 1] = st.x; rstd[(i - LO) >> 1] = st.y; } }
;             r[i - LO] = *(const f32x4*)(src + (row * (unsigned)DM + col0 + BJ * HALF + n * 16)); }
; #pragma unroll
;         for (int i = LO; i < HI; ++i) { const int ai = i >> 3, m = (i >> 1) & 3, n = i & 1; const unsigned row = row0 + ai * HALF + m * 16;
;             *(f32x4*)(Y + (row * (unsigned)DM + col0 + BJ * HALF + n * 16)) = acc[ai][BJ][m][n] + ((r[i - LO] - mean[(i - LO) >> 1]) * rstd[(i - LO) >> 1]) * gv[n] + bv[n]; }
	v_sub_f32_e32 v55, v55, v62
	v_sub_f32_e32 v54, v54, v62
	v_sub_f32_e32 v57, v57, v62
	v_sub_f32_e32 v56, v56, v62
	v_pk_mul_f32 v[56:57], v[62:63], v[56:57] op_sel:[1,0]
	v_pk_mul_f32 v[54:55], v[62:63], v[54:55] op_sel:[1,0]
	v_pk_fma_f32 v[30:31], v[96:97], v[56:57], v[30:31]
	v_pk_fma_f32 v[28:29], v[98:99], v[54:55], v[28:29]
	v_pk_fma_f32 v[30:31], v[70:71], s[78:79], v[30:31] op_sel_hi:[1,0,1]
	v_pk_fma_f32 v[28:29], v[68:69], s[78:79], v[28:29] op_sel_hi:[1,0,1]
	v_lshl_add_u64 v[54:55], v[158:159], 2, s[88:89]
	global_store_dwordx4 v[54:55], v[28:31], off
	v_add_u32_e32 v158, 0x40090, v148
	s_nop 0
	v_sub_f32_e32 v29, v59, v62
	v_sub_f32_e32 v28, v58, v62
	v_sub_f32_e32 v31, v61, v62
	v_sub_f32_e32 v30, v60, v62
	v_pk_mul_f32 v[30:31], v[62:63], v[30:31] op_sel:[1,0]
	v_pk_mul_f32 v[28:29], v[62:63], v[28:29] op_sel:[1,0]
	v_pk_fma_f32 v[26:27], v[92:93], v[30:31], v[26:27]
	v_pk_fma_f32 v[24:25], v[94:95], v[28:29], v[24:25]
	v_pk_fma_f32 v[26:27], v[66:67], s[78:79], v[26:27] op_sel_hi:[1,0,1]
	v_pk_fma_f32 v[24:25], v[64:65], s[78:79], v[24:25] op_sel_hi:[1,0,1]
	v_lshl_add_u64 v[28:29], v[158:159], 2, s[88:89]
	global_store_dwordx4 v[28:29], v[24:27], off
	v_add_u32_e32 v158, 0x48080, v148
	s_nop 0
	v_sub_f32_e32 v25, v73, v52
	v_sub_f32_e32 v24, v72, v52
	v_sub_f32_e32 v27, v75, v52
	v_sub_f32_e32 v26, v74, v52
	v_pk_mul_f32 v[26:27], v[52:53], v[26:27] op_sel:[1,0]
	v_pk_mul_f32 v[24:25], v[52:53], v[24:25] op_sel:[1,0]
	v_pk_fma_f32 v[22:23], v[96:97], v[26:27], v[22:23]
	v_pk_fma_f32 v[20:21], v[98:99], v[24:25], v[20:21]
	v_pk_fma_f32 v[22:23], v[70:71], s[78:79], v[22:23] op_sel_hi:[1,0,1]
	v_pk_fma_f32 v[20:21], v[68:69], s[78:79], v[20:21] op_sel_hi:[1,0,1]
	v_lshl_add_u64 v[24:25], v[158:159], 2, s[88:89]
	global_store_dwordx4 v[24:25], v[20:23], off
	v_add_u32_e32 v158, 0x48090, v148
	s_nop 0
	v_sub_f32_e32 v21, v77, v52
	v_sub_f32_e32 v20, v76, v52
	v_sub_f32_e32 v23, v79, v52
	v_sub_f32_e32 v22, v78, v52
	v_pk_mul_f32 v[22:23], v[52:53], v[22:23] op_sel:[1,0]
	v_pk_mul_f32 v[20:21], v[52:53], v[20:21] op_sel:[1,0]
	v_pk_fma_f32 v[18:19], v[92:93], v[22:23], v[18:19]
	v_pk_fma_f32 v[16:17], v[94:95], v[20:21], v[16:17]
	v_pk_fma_f32 v[18:19], v[66:67], s[78:79], v[18:19] op_sel_hi:[1,0,1]
	v_pk_fma_f32 v[16:17], v[64:65], s[78:79], v[16:17] op_sel_hi:[1,0,1]
	v_lshl_add_u64 v[20:21], v[158:159], 2, s[88:89]
	global_store_dwordx4 v[20:21], v[16:19], off
	v_add_u32_e32 v158, 0x50080, v148
	s_nop 0
	v_sub_f32_e32 v17, v45, v50
	v_sub_f32_e32 v16, v44, v50
	v_sub_f32_e32 v19, v47, v50
	v_sub_f32_e32 v18, v46, v50
	v_pk_mul_f32 v[18:19], v[50:51], v[18:19] op_sel:[1,0]
	v_pk_mul_f32 v[16:17], v[50:51], v[16:17] op_sel:[1,0]
	v_pk_fma_f32 v[14:15], v[96:97], v[18:19], v[14:15]
	v_pk_fma_f32 v[12:13], v[98:99], v[16:17], v[12:13]
	v_pk_fma_f32 v[14:15], v[70:71], s[78:79], v[14:15] op_sel_hi:[1,0,1]
	v_pk_fma_f32 v[12:13], v[68:69], s[78:79], v[12:13] op_sel_hi:[1,0,1]
	v_lshl_add_u64 v[16:17], v[158:159], 2, s[88:89]
	global_store_dwordx4 v[16:17], v[12:15], off
	v_add_u32_e32 v158, 0x50090, v148
	s_nop 0
	v_sub_f32_e32 v13, v41, v50
	v_sub_f32_e32 v12, v40, v50
	v_sub_f32_e32 v15, v43, v50
	v_sub_f32_e32 v14, v42, v50
	v_pk_mul_f32 v[14:15], v[50:51], v[14:15] op_sel:[1,0]
	v_pk_mul_f32 v[12:13], v[50:51], v[12:13] op_sel:[1,0]
	v_pk_fma_f32 v[10:11], v[92:93], v[14:15], v[10:11]
	v_pk_fma_f32 v[8:9], v[94:95], v[12:13], v[8:9]
	v_pk_fma_f32 v[10:11], v[66:67], s[78:79], v[10:11] op_sel_hi:[1,0,1]
	v_pk_fma_f32 v[8:9], v[64:65], s[78:79], v[8:9] op_sel_hi:[1,0,1]
	v_lshl_add_u64 v[12:13], v[158:159], 2, s[88:89]
	global_store_dwordx4 v[12:13], v[8:11], off
	v_add_u32_e32 v158, 0x58080, v148
	s_nop 0
	v_sub_f32_e32 v9, v37, v48
	v_sub_f32_e32 v8, v36, v48
	v_sub_f32_e32 v11, v39, v48
	v_sub_f32_e32 v10, v38, v48
	v_pk_mul_f32 v[10:11], v[48:49], v[10:11] op_sel:[1,0]
	v_pk_mul_f32 v[8:9], v[48:49], v[8:9] op_sel:[1,0]
	v_pk_fma_f32 v[6:7], v[96:97], v[10:11], v[6:7]
	v_pk_fma_f32 v[4:5], v[98:99], v[8:9], v[4:5]
	v_pk_fma_f32 v[6:7], v[70:71], s[78:79], v[6:7] op_sel_hi:[1,0,1]
	v_pk_fma_f32 v[4:5], v[68:69], s[78:79], v[4:5] op_sel_hi:[1,0,1]
	v_lshl_add_u64 v[8:9], v[158:159], 2, s[88:89]
	global_store_dwordx4 v[8:9], v[4:7], off
	v_add_u32_e32 v158, 0x58090, v148
	s_nop 0
	v_sub_f32_e32 v5, v33, v48
	v_sub_f32_e32 v4, v32, v48
	v_sub_f32_e32 v7, v35, v48
	v_sub_f32_e32 v6, v34, v48
	v_pk_mul_f32 v[6:7], v[48:49], v[6:7] op_sel:[1,0]
	v_pk_mul_f32 v[4:5], v[48:49], v[4:5] op_sel:[1,0]
	v_pk_fma_f32 v[2:3], v[92:93], v[6:7], v[2:3]
	v_pk_fma_f32 v[0:1], v[94:95], v[4:5], v[0:1]
	v_pk_fma_f32 v[2:3], v[66:67], s[78:79], v[2:3] op_sel_hi:[1,0,1]
	v_pk_fma_f32 v[0:1], v[64:65], s[78:79], v[0:1] op_sel_hi:[1,0,1]
	v_lshl_add_u64 v[4:5], v[158:159], 2, s[88:89]
	global_store_dwordx4 v[4:5], v[0:3], off
	s_and_b64 vcc, exec, s[6:7]
	s_mov_b32 s2, s37
	s_mov_b32 s3, s38
	s_mov_b64 s[18:19], s[10:11]
	s_mov_b64 s[16:17], s[8:9]
	v_readlane_b32 s33, v255, 39
	s_cbranch_vccz .LBB0_123
	s_waitcnt vmcnt(0)
	s_cmpk_gt_u32 s24, 0xff
	s_cbranch_scc1 .LBB0_138
	s_barrier

; #define PG8_STAGE(bufoff, gbase) do { _Pragma("unroll") for (int _i = 0; _i < 2; ++_i) \
;         __builtin_amdgcn_global_load_lds((const unsigned*)((const char*)(gbase) + voff[_i]), (LAS unsigned*)(lds + (bufoff) + ldsw + _i * 8192), 16, 0, 0); } while (0)
; #define PG8_LDA(dst, b, h) do { _Pragma("unroll") for (int m = 0; m < 4; ++m) _Pragma("unroll") for (int k = 0; k < 2; ++k) dst[m][k] = *(const LAS bf16x8*)(lds + PG8_SA(b, h) + aoff + m * 2048 + k * 1024); } while (0)
; #define PG8_LDB(dst, b, h) do { _Pragma("unroll") for (int n = 0; n < 2; ++n) _Pragma("unroll") for (int k = 0; k < 2; ++k) dst[n][k] = *(const LAS bf16x8*)(lds + PG8_SB(b, h) + boff + n * 2048 + k * 1024); } while (0)
; #define PG8_MMA(ai, bj, At, Bt) do { __builtin_amdgcn_s_setprio(1); _Pragma("unroll") for (int m = 0; m < 4; ++m) _Pragma("unroll") for (int n = 0; n < 2; ++n) _Pragma("unroll") for (int k = 0; k < 2; ++k) \
;         acc[ai][bj][m][n] = __builtin_amdgcn_mfma_f32_16x16x32_bf16(Bt[n][k], At[m][k], acc[ai][bj][m][n], 0, 0, 0); __builtin_amdgcn_s_setprio(0); } while (0)
; template <class Epi>
; DI void gemm_phase(LAS unsigned char* lds, const Gemm g, const StaticOrder& S, const Epi& E) {
;     ...
;         const bool has_next = S.next(ui + 1, nxt);
;         const char* nA = has_next ? (const char*)g.A + (size_t)nxt.pm * tstep : cA; const char* nB = has_next ? (const char*)g.Bt + (size_t)nxt.pn * tstep : cB;
;         for (int t = 0; t < nt; t += 2) {
;             const bool last = (t == nt - 2);
;             const char* a1 = cA + (size_t)(t + 1) * kstep;
;             const char* a2 = last ? nA : cA + (size_t)(t + 2) * kstep; const char* b2 = last ? nB : cB + (size_t)(t + 2) * kstep;
;             const char* a3 = a2 + kstep; const char* b3 = b2 + kstep;
;             PG8_LDB(B0, 0, 0); PG8_SCHED; PG8_LDA(At, 0, 0); PG8_STAGE(PG8_SA(1, 1), a1 + hstep);
;             PG8_WAIT_L(8); PG8_BAR; PG8_WAIT_L(0); PG8_MMA(0, 0, At, B0); PG8_BAR; PG8_SCHED;
;             PG8_LDB(B1, 0, 1); PG8_STAGE(PG8_SB(0, 0), b2);
;             PG8_BAR; PG8_WAIT_L(0); PG8_MMA(0, 1, At, B1); PG8_BAR;
;             PG8_LDA(At, 0, 1); PG8_STAGE(PG8_SA(0, 0), a2);
;             PG8_BAR; PG8_WAIT_L(0); PG8_MMA(1, 0, At, B0); PG8_BAR; PG8_SCHED;
;             PG8_STAGE(PG8_SB(0, 1), b2 + hstep);
;             PG8_WAIT_V(6); PG8_BAR; PG8_MMA(1, 1, At, B1); PG8_BAR;
.LBB0_202:
	s_add_u32 s18, s8, 0xfff80080
	s_addc_u32 s19, s9, -1
	s_add_i32 s37, 0, 0x10000
	s_waitcnt lgkmcnt(0)
	ds_read_b128 v[128:131], v187
	ds_read_b128 v[132:135], v187 offset:1024
	ds_read_b128 v[136:139], v187 offset:2048
	ds_read_b128 v[190:193], v187 offset:3072
	s_cmp_eq_u32 s36, 28
	s_cselect_b32 s21, s4, s19
	s_cselect_b32 s20, s5, s18
	s_cselect_b32 s19, s11, s35
	s_cselect_b32 s18, s13, s33
	s_add_i32 m0, s26, 0xc000
	ds_read_b128 v[194:197], v189
	ds_read_b128 v[198:201], v189 offset:1024
	ds_read_b128 v[202:205], v189 offset:2048
	ds_read_b128 v[206:209], v189 offset:3072
	ds_read_b128 v[210:213], v189 offset:4096
	ds_read_b128 v[214:217], v189 offset:5120
	ds_read_b128 v[226:229], v189 offset:6144
	ds_read_b128 v[230:233], v189 offset:7168
	global_load_lds_dwordx4 v150, s[8:9]
	s_add_i32 m0, s26, 0xe000
	s_nop 0
	global_load_lds_dwordx4 v152, s[8:9]
	s_waitcnt lgkmcnt(8)
	s_setprio 1
	s_barrier
	s_waitcnt lgkmcnt(0)
	v_mfma_f32_16x16x32_bf16 v[124:127], v[128:131], v[194:197], v[124:127]
	v_mfma_f32_16x16x32_bf16 v[120:123], v[136:139], v[194:197], v[120:123]
	v_mfma_f32_16x16x32_bf16 v[108:111], v[128:131], v[202:205], v[108:111]
	v_mfma_f32_16x16x32_bf16 v[104:107], v[136:139], v[202:205], v[104:107]
	v_mfma_f32_16x16x32_bf16 v[92:95], v[128:131], v[210:213], v[92:95]
	v_mfma_f32_16x16x32_bf16 v[88:91], v[136:139], v[210:213], v[88:91]
	v_mfma_f32_16x16x32_bf16 v[76:79], v[128:131], v[226:229], v[76:79]
	v_mfma_f32_16x16x32_bf16 v[72:75], v[136:139], v[226:229], v[72:75]
	v_mfma_f32_16x16x32_bf16 v[124:127], v[132:135], v[198:201], v[124:127]
	v_mfma_f32_16x16x32_bf16 v[120:123], v[190:193], v[198:201], v[120:123]
	v_mfma_f32_16x16x32_bf16 v[108:111], v[132:135], v[206:209], v[108:111]
	v_mfma_f32_16x16x32_bf16 v[104:107], v[190:193], v[206:209], v[104:107]
	v_mfma_f32_16x16x32_bf16 v[92:95], v[132:135], v[214:217], v[92:95]
	v_mfma_f32_16x16x32_bf16 v[88:91], v[190:193], v[214:217], v[88:91]
	v_mfma_f32_16x16x32_bf16 v[76:79], v[132:135], v[230:233], v[76:79]
	s_setprio 0
	v_mfma_f32_16x16x32_bf16 v[72:75], v[190:193], v[230:233], v[72:75]
	s_barrier
	ds_read_b128 v[234:237], v187 offset:16384
	ds_read_b128 v[238:241], v187 offset:17408
	ds_read_b128 v[242:245], v187 offset:18432
	ds_read_b128 v[246:249], v187 offset:19456
	s_add_i32 s40, 0, 0x14000
	s_add_i32 s37, s37, s25
	s_mov_b32 m0, s37
	s_nop 0
	global_load_lds_dwordx4 v144, s[18:19]
	s_add_i32 m0, s37, 0x2000
	s_nop 0
	global_load_lds_dwordx4 v142, s[18:19]
	s_waitcnt lgkmcnt(0)
	s_setprio 1
	s_barrier
	v_mfma_f32_16x16x32_bf16 v[116:119], v[234:237], v[194:197], v[116:119]
	v_mfma_f32_16x16x32_bf16 v[112:115], v[242:245], v[194:197], v[112:115]
	v_mfma_f32_16x16x32_bf16 v[100:103], v[234:237], v[202:205], v[100:103]
	v_mfma_f32_16x16x32_bf16 v[96:99], v[242:245], v[202:205], v[96:99]
	v_mfma_f32_16x16x32_bf16 v[84:87], v[234:237], v[210:213], v[84:87]
	v_mfma_f32_16x16x32_bf16 v[80:83], v[242:245], v[210:213], v[80:83]
	v_mfma_f32_16x16x32_bf16 v[68:71], v[234:237], v[226:229], v[68:71]
	v_mfma_f32_16x16x32_bf16 v[64:67], v[242:245], v[226:229], v[64:67]
	v_mfma_f32_16x16x32_bf16 v[116:119], v[238:241], v[198:201], v[116:119]
	v_mfma_f32_16x16x32_bf16 v[112:115], v[246:249], v[198:201], v[112:115]
	v_mfma_f32_16x16x32_bf16 v[100:103], v[238:241], v[206:209], v[100:103]
	v_mfma_f32_16x16x32_bf16 v[96:99], v[246:249], v[206:209], v[96:99]
	v_mfma_f32_16x16x32_bf16 v[84:87], v[238:241], v[214:217], v[84:87]
	v_mfma_f32_16x16x32_bf16 v[80:83], v[246:249], v[214:217], v[80:83]
	v_mfma_f32_16x16x32_bf16 v[68:71], v[238:241], v[230:233], v[68:71]
	s_setprio 0
	v_mfma_f32_16x16x32_bf16 v[64:67], v[246:249], v[230:233], v[64:67]
	s_barrier
	ds_read_b128 v[194:197], v189 offset:16384
	ds_read_b128 v[198:201], v189 offset:17408
	ds_read_b128 v[202:205], v189 offset:18432
	ds_read_b128 v[206:209], v189 offset:19456
	ds_read_b128 v[210:213], v189 offset:20480
	ds_read_b128 v[214:217], v189 offset:21504
	ds_read_b128 v[226:229], v189 offset:22528
	ds_read_b128 v[230:233], v189 offset:23552
	s_mov_b32 m0, s26
	s_nop 0
	global_load_lds_dwordx4 v144, s[20:21]
	s_mov_b32 m0, s27
	s_mov_b64 s[100:101], s[20:21]
	global_load_lds_dwordx4 v142, s[20:21]
	s_waitcnt lgkmcnt(0)
	s_setprio 1
	s_barrier
	v_mfma_f32_16x16x32_bf16 v[60:63], v[128:131], v[194:197], v[60:63]
	v_mfma_f32_16x16x32_bf16 v[56:59], v[136:139], v[194:197], v[56:59]
	v_mfma_f32_16x16x32_bf16 v[44:47], v[128:131], v[202:205], v[44:47]
	v_mfma_f32_16x16x32_bf16 v[40:43], v[136:139], v[202:205], v[40:43]
	v_mfma_f32_16x16x32_bf16 v[28:31], v[128:131], v[210:213], v[28:31]
	v_mfma_f32_16x16x32_bf16 v[24:27], v[136:139], v[210:213], v[24:27]
	v_mfma_f32_16x16x32_bf16 v[12:15], v[128:131], v[226:229], v[12:15]
	v_mfma_f32_16x16x32_bf16 v[8:11], v[136:139], v[226:229], v[8:11]
	v_mfma_f32_16x16x32_bf16 v[60:63], v[132:135], v[198:201], v[60:63]
	v_mfma_f32_16x16x32_bf16 v[56:59], v[190:193], v[198:201], v[56:59]
	v_mfma_f32_16x16x32_bf16 v[44:47], v[132:135], v[206:209], v[44:47]
	v_mfma_f32_16x16x32_bf16 v[40:43], v[190:193], v[206:209], v[40:43]
	v_mfma_f32_16x16x32_bf16 v[28:31], v[132:135], v[214:217], v[28:31]
	v_mfma_f32_16x16x32_bf16 v[24:27], v[190:193], v[214:217], v[24:27]
	v_mfma_f32_16x16x32_bf16 v[12:15], v[132:135], v[230:233], v[12:15]
	s_setprio 0
	v_mfma_f32_16x16x32_bf16 v[8:11], v[190:193], v[230:233], v[8:11]
	s_barrier
	s_add_u32 s38, s18, 0x80000
	s_addc_u32 s39, s19, 0
	s_add_i32 s37, s40, s25
	s_mov_b32 m0, s37
	s_nop 0
	global_load_lds_dwordx4 v144, s[38:39]
	s_add_i32 m0, s37, 0x2000
	s_nop 0
	global_load_lds_dwordx4 v142, s[38:39]
	s_waitcnt vmcnt(6)
	s_setprio 1
	s_barrier
; #define PG8_STAGE(bufoff, gbase) do { _Pragma("unroll") for (int _i = 0; _i < 2; ++_i) \
;         __builtin_amdgcn_global_load_lds((const unsigned*)((const char*)(gbase) + voff[_i]), (LAS unsigned*)(lds + (bufoff) + ldsw + _i * 8192), 16, 0, 0); } while (0)
; #define PG8_LDA(dst, b, h) do { _Pragma("unroll") for (int m = 0; m < 4; ++m) _Pragma("unroll") for (int k = 0; k < 2; ++k) dst[m][k] = *(const LAS bf16x8*)(lds + PG8_SA(b, h) + aoff + m * 2048 + k * 1024); } while (0)
; #define PG8_LDB(dst, b, h) do { _Pragma("unroll") for (int n = 0; n < 2; ++n) _Pragma("unroll") for (int k = 0; k < 2; ++k) dst[n][k] = *(const LAS bf16x8*)(lds + PG8_SB(b, h) + boff + n * 2048 + k * 1024); } while (0)
; #define PG8_MMA(ai, bj, At, Bt) do { __builtin_amdgcn_s_setprio(1); _Pragma("unroll") for (int m = 0; m < 4; ++m) _Pragma("unroll") for (int n = 0; n < 2; ++n) _Pragma("unroll") for (int k = 0; k < 2; ++k) \
;         acc[ai][bj][m][n] = __builtin_amdgcn_mfma_f32_16x16x32_bf16(Bt[n][k], At[m][k], acc[ai][bj][m][n], 0, 0, 0); __builtin_amdgcn_s_setprio(0); } while (0)
; #define PG8_WAIT_V(n) asm volatile("s_waitcnt vmcnt(" #n ")" ::: "memory")
; #define PG8_WAIT_L(n) asm volatile("s_waitcnt lgkmcnt(" #n ")" ::: "memory")
; #define PG8_BAR __builtin_amdgcn_s_barrier()
; #define PG8_SCHED __builtin_amdgcn_sched_barrier(0)
; template <class Epi>
; DI void gemm_phase(LAS unsigned char* lds, const Gemm g, const StaticOrder& S, const Epi& E) {
;     ...
;             PG8_WAIT_V(6); PG8_BAR; PG8_MMA(1, 1, At, B1); PG8_BAR;
;             PG8_LDB(B0, 1, 0); PG8_SCHED; PG8_LDA(At, 1, 0); PG8_STAGE(PG8_SA(0, 1), a2 + hstep);
;             PG8_WAIT_L(8); PG8_BAR; PG8_WAIT_L(0); PG8_MMA(0, 0, At, B0); PG8_BAR; PG8_SCHED;
;             PG8_LDB(B1, 1, 1); PG8_STAGE(PG8_SB(1, 0), b3);
;             PG8_BAR; PG8_WAIT_L(0); PG8_MMA(0, 1, At, B1); PG8_BAR;
;             PG8_LDA(At, 1, 1); PG8_STAGE(PG8_SA(1, 0), a3);
;             PG8_BAR; PG8_WAIT_L(0); PG8_MMA(1, 0, At, B0); PG8_BAR; PG8_SCHED;
	v_mfma_f32_16x16x32_bf16 v[52:55], v[234:237], v[194:197], v[52:55]
	v_mfma_f32_16x16x32_bf16 v[48:51], v[242:245], v[194:197], v[48:51]
	v_mfma_f32_16x16x32_bf16 v[36:39], v[234:237], v[202:205], v[36:39]
	v_mfma_f32_16x16x32_bf16 v[32:35], v[242:245], v[202:205], v[32:35]
	v_mfma_f32_16x16x32_bf16 v[20:23], v[234:237], v[210:213], v[20:23]
	v_mfma_f32_16x16x32_bf16 v[16:19], v[242:245], v[210:213], v[16:19]
	v_mfma_f32_16x16x32_bf16 v[4:7], v[234:237], v[226:229], v[4:7]
	v_mfma_f32_16x16x32_bf16 v[0:3], v[242:245], v[226:229], v[0:3]
	v_mfma_f32_16x16x32_bf16 v[52:55], v[238:241], v[198:201], v[52:55]
	v_mfma_f32_16x16x32_bf16 v[48:51], v[246:249], v[198:201], v[48:51]
	v_mfma_f32_16x16x32_bf16 v[36:39], v[238:241], v[206:209], v[36:39]
	v_mfma_f32_16x16x32_bf16 v[32:35], v[246:249], v[206:209], v[32:35]
	v_mfma_f32_16x16x32_bf16 v[20:23], v[238:241], v[214:217], v[20:23]
	v_mfma_f32_16x16x32_bf16 v[16:19], v[246:249], v[214:217], v[16:19]
	v_mfma_f32_16x16x32_bf16 v[4:7], v[238:241], v[230:233], v[4:7]
	s_setprio 0
	v_mfma_f32_16x16x32_bf16 v[0:3], v[246:249], v[230:233], v[0:3]
	s_barrier
	ds_read_b128 v[128:131], v187 offset:32768
	ds_read_b128 v[132:135], v187 offset:33792
	ds_read_b128 v[136:139], v187 offset:34816
	ds_read_b128 v[190:193], v187 offset:35840
	ds_read_b128 v[194:197], v189 offset:32768
	ds_read_b128 v[198:201], v189 offset:33792
	ds_read_b128 v[202:205], v189 offset:34816
	ds_read_b128 v[206:209], v189 offset:35840
	ds_read_b128 v[210:213], v189 offset:36864
	ds_read_b128 v[214:217], v189 offset:37888
	ds_read_b128 v[226:229], v189 offset:38912
	ds_read_b128 v[230:233], v189 offset:39936
	s_add_i32 s37, 0, 0x18000
	s_add_u32 s20, s20, 0x80000
	s_addc_u32 s21, s21, 0
	s_mov_b32 m0, s28
	s_nop 0
	global_load_lds_dwordx4 v144, s[20:21]
	s_mov_b32 m0, s29
	s_nop 0
	global_load_lds_dwordx4 v142, s[20:21]
	s_waitcnt lgkmcnt(8)
	s_setprio 1
	s_barrier
	s_waitcnt lgkmcnt(0)
	v_mfma_f32_16x16x32_bf16 v[124:127], v[128:131], v[194:197], v[124:127]
	v_mfma_f32_16x16x32_bf16 v[120:123], v[136:139], v[194:197], v[120:123]
	v_mfma_f32_16x16x32_bf16 v[108:111], v[128:131], v[202:205], v[108:111]
	v_mfma_f32_16x16x32_bf16 v[104:107], v[136:139], v[202:205], v[104:107]
	v_mfma_f32_16x16x32_bf16 v[92:95], v[128:131], v[210:213], v[92:95]
	v_mfma_f32_16x16x32_bf16 v[88:91], v[136:139], v[210:213], v[88:91]
	v_mfma_f32_16x16x32_bf16 v[76:79], v[128:131], v[226:229], v[76:79]
	v_mfma_f32_16x16x32_bf16 v[72:75], v[136:139], v[226:229], v[72:75]
	v_mfma_f32_16x16x32_bf16 v[124:127], v[132:135], v[198:201], v[124:127]
	v_mfma_f32_16x16x32_bf16 v[120:123], v[190:193], v[198:201], v[120:123]
	v_mfma_f32_16x16x32_bf16 v[108:111], v[132:135], v[206:209], v[108:111]
	v_mfma_f32_16x16x32_bf16 v[104:107], v[190:193], v[206:209], v[104:107]
	v_mfma_f32_16x16x32_bf16 v[92:95], v[132:135], v[214:217], v[92:95]
	v_mfma_f32_16x16x32_bf16 v[88:91], v[190:193], v[214:217], v[88:91]
	v_mfma_f32_16x16x32_bf16 v[76:79], v[132:135], v[230:233], v[76:79]
	s_setprio 0
	v_mfma_f32_16x16x32_bf16 v[72:75], v[190:193], v[230:233], v[72:75]
	s_barrier
	ds_read_b128 v[234:237], v187 offset:49152
	ds_read_b128 v[238:241], v187 offset:50176
	ds_read_b128 v[242:245], v187 offset:51200
	ds_read_b128 v[246:249], v187 offset:52224
	s_add_i32 s20, 0, 0x1c000
	s_add_i32 s21, s37, s25
	s_add_i32 m0, s21, 0xffffff80
	s_nop 0
	global_load_lds_dwordx4 v144, s[18:19] offset:128
	s_add_i32 m0, s21, 0x1f80
	s_nop 0
	global_load_lds_dwordx4 v142, s[18:19] offset:128
	s_waitcnt lgkmcnt(0)
	s_setprio 1
	s_barrier
	v_mfma_f32_16x16x32_bf16 v[116:119], v[234:237], v[194:197], v[116:119]
	v_mfma_f32_16x16x32_bf16 v[112:115], v[242:245], v[194:197], v[112:115]
	v_mfma_f32_16x16x32_bf16 v[100:103], v[234:237], v[202:205], v[100:103]
	v_mfma_f32_16x16x32_bf16 v[96:99], v[242:245], v[202:205], v[96:99]
	v_mfma_f32_16x16x32_bf16 v[84:87], v[234:237], v[210:213], v[84:87]
	v_mfma_f32_16x16x32_bf16 v[80:83], v[242:245], v[210:213], v[80:83]
	v_mfma_f32_16x16x32_bf16 v[68:71], v[234:237], v[226:229], v[68:71]
	v_mfma_f32_16x16x32_bf16 v[64:67], v[242:245], v[226:229], v[64:67]
	v_mfma_f32_16x16x32_bf16 v[116:119], v[238:241], v[198:201], v[116:119]
	v_mfma_f32_16x16x32_bf16 v[112:115], v[246:249], v[198:201], v[112:115]
	v_mfma_f32_16x16x32_bf16 v[100:103], v[238:241], v[206:209], v[100:103]
	v_mfma_f32_16x16x32_bf16 v[96:99], v[246:249], v[206:209], v[96:99]
	v_mfma_f32_16x16x32_bf16 v[84:87], v[238:241], v[214:217], v[84:87]
	v_mfma_f32_16x16x32_bf16 v[80:83], v[246:249], v[214:217], v[80:83]
	v_mfma_f32_16x16x32_bf16 v[68:71], v[238:241], v[230:233], v[68:71]
	s_setprio 0
	v_mfma_f32_16x16x32_bf16 v[64:67], v[246:249], v[230:233], v[64:67]
	s_barrier
; #define PG8_STAGE(bufoff, gbase) do { _Pragma("unroll") for (int _i = 0; _i < 2; ++_i) \
;         __builtin_amdgcn_global_load_lds((const unsigned*)((const char*)(gbase) + voff[_i]), (LAS unsigned*)(lds + (bufoff) + ldsw + _i * 8192), 16, 0, 0); } while (0)
; #define PG8_MMA(ai, bj, At, Bt) do { __builtin_amdgcn_s_setprio(1); _Pragma("unroll") for (int m = 0; m < 4; ++m) _Pragma("unroll") for (int n = 0; n < 2; ++n) _Pragma("unroll") for (int k = 0; k < 2; ++k) \
;         acc[ai][bj][m][n] = __builtin_amdgcn_mfma_f32_16x16x32_bf16(Bt[n][k], At[m][k], acc[ai][bj][m][n], 0, 0, 0); __builtin_amdgcn_s_setprio(0); } while (0)
; #define PG8_WAIT_V(n) asm volatile("s_waitcnt vmcnt(" #n ")" ::: "memory")
; #define PG8_WAIT_L(n) asm volatile("s_waitcnt lgkmcnt(" #n ")" ::: "memory")
; #define PG8_BAR __builtin_amdgcn_s_barrier()
; #define PG8_SCHED __builtin_amdgcn_sched_barrier(0)
; template <class Epi>
; DI void gemm_phase(LAS unsigned char* lds, const Gemm g, const StaticOrder& S, const Epi& E) {
;     ...
;             PG8_BAR; PG8_WAIT_L(0); PG8_MMA(1, 0, At, B0); PG8_BAR; PG8_SCHED;
;             PG8_STAGE(PG8_SB(1, 1), b3 + hstep);
;             PG8_WAIT_V(6); PG8_BAR; PG8_MMA(1, 1, At, B1); PG8_BAR;
;     DI void operator()(const f32x4 (&acc)[2][2][4][2], const Unit& u, int wr, int wc, int fr, int fq) const {
;         const int row0 = u.pm * BM + wr * 64 + fr, col0 = u.pn * BM + wc * 16 + 4 * fq;
;         const bool rot = u.pn < 18;
; #pragma unroll
;         for (int ai = 0; ai < 2; ++ai)
; #pragma unroll
;             for (int m = 0; m < 4; ++m) { const int row = row0 + ai * HALF + m * 16; u16* rowp = O + (size_t)row * NQKV_DIL + col0;
;                 f32x4 c4 = (f32x4){1.f, 1.f, 1.f, 1.f}, s4 = (f32x4){0.f, 0.f, 0.f, 0.f};
;                 if (rot) { const int pos = row & (SEQ - 1); c4 = *(const f32x4*)(cs + pos * 64 + wc * 16 + 4 * fq); s4 = *(const f32x4*)(sn + pos * 64 + wc * 16 + 4 * fq); }
	ds_read_b128 v[194:197], v189 offset:49152
	ds_read_b128 v[198:201], v189 offset:50176
	ds_read_b128 v[202:205], v189 offset:51200
	ds_read_b128 v[206:209], v189 offset:52224
	ds_read_b128 v[210:213], v189 offset:53248
	ds_read_b128 v[214:217], v189 offset:54272
	ds_read_b128 v[226:229], v189 offset:55296
	ds_read_b128 v[230:233], v189 offset:56320
	s_add_i32 m0, s30, 0xffffff80
	s_nop 0
	global_load_lds_dwordx4 v144, s[100:101] offset:128
	s_add_i32 m0, s31, 0xffffff80
	s_nop 0
	global_load_lds_dwordx4 v142, s[100:101] offset:128
	s_waitcnt lgkmcnt(0)
	s_setprio 1
	s_barrier
	v_mfma_f32_16x16x32_bf16 v[60:63], v[128:131], v[194:197], v[60:63]
	v_mfma_f32_16x16x32_bf16 v[56:59], v[136:139], v[194:197], v[56:59]
	v_mfma_f32_16x16x32_bf16 v[44:47], v[128:131], v[202:205], v[44:47]
	v_mfma_f32_16x16x32_bf16 v[40:43], v[136:139], v[202:205], v[40:43]
	v_mfma_f32_16x16x32_bf16 v[28:31], v[128:131], v[210:213], v[28:31]
	v_mfma_f32_16x16x32_bf16 v[24:27], v[136:139], v[210:213], v[24:27]
	v_mfma_f32_16x16x32_bf16 v[12:15], v[128:131], v[226:229], v[12:15]
	v_mfma_f32_16x16x32_bf16 v[8:11], v[136:139], v[226:229], v[8:11]
	v_mfma_f32_16x16x32_bf16 v[60:63], v[132:135], v[198:201], v[60:63]
	v_mfma_f32_16x16x32_bf16 v[56:59], v[190:193], v[198:201], v[56:59]
	v_mfma_f32_16x16x32_bf16 v[44:47], v[132:135], v[206:209], v[44:47]
	v_mfma_f32_16x16x32_bf16 v[40:43], v[190:193], v[206:209], v[40:43]
	v_mfma_f32_16x16x32_bf16 v[28:31], v[132:135], v[214:217], v[28:31]
	v_mfma_f32_16x16x32_bf16 v[24:27], v[190:193], v[214:217], v[24:27]
	v_mfma_f32_16x16x32_bf16 v[12:15], v[132:135], v[230:233], v[12:15]
	s_setprio 0
	v_mfma_f32_16x16x32_bf16 v[8:11], v[190:193], v[230:233], v[8:11]
	s_barrier
	s_add_u32 s18, s18, 0x80080
	s_addc_u32 s19, s19, 0
	s_add_i32 s20, s20, s25
	s_mov_b32 m0, s20
	s_nop 0
	global_load_lds_dwordx4 v144, s[18:19]
	s_add_i32 m0, s20, 0x2000
	s_nop 0
	global_load_lds_dwordx4 v142, s[18:19]
	s_waitcnt vmcnt(6)
	s_setprio 1
	s_barrier
	v_mfma_f32_16x16x32_bf16 v[52:55], v[234:237], v[194:197], v[52:55]
	v_mfma_f32_16x16x32_bf16 v[48:51], v[242:245], v[194:197], v[48:51]
	v_mfma_f32_16x16x32_bf16 v[36:39], v[234:237], v[202:205], v[36:39]
	v_mfma_f32_16x16x32_bf16 v[32:35], v[242:245], v[202:205], v[32:35]
	v_mfma_f32_16x16x32_bf16 v[20:23], v[234:237], v[210:213], v[20:23]
	v_mfma_f32_16x16x32_bf16 v[16:19], v[242:245], v[210:213], v[16:19]
	v_mfma_f32_16x16x32_bf16 v[4:7], v[234:237], v[226:229], v[4:7]
	v_mfma_f32_16x16x32_bf16 v[0:3], v[242:245], v[226:229], v[0:3]
	v_mfma_f32_16x16x32_bf16 v[52:55], v[238:241], v[198:201], v[52:55]
	s_add_i32 s36, s36, 2
	v_mfma_f32_16x16x32_bf16 v[48:51], v[246:249], v[198:201], v[48:51]
	s_add_u32 s8, s8, 0x100
	v_mfma_f32_16x16x32_bf16 v[36:39], v[238:241], v[206:209], v[36:39]
	s_addc_u32 s9, s9, 0
	v_mfma_f32_16x16x32_bf16 v[32:35], v[246:249], v[206:209], v[32:35]
	s_add_u32 s33, s33, 0x100
	v_mfma_f32_16x16x32_bf16 v[20:23], v[238:241], v[214:217], v[20:23]
	s_addc_u32 s35, s35, 0
	v_mfma_f32_16x16x32_bf16 v[16:19], v[246:249], v[214:217], v[16:19]
	s_cmp_gt_u32 s36, 29
	v_mfma_f32_16x16x32_bf16 v[4:7], v[238:241], v[230:233], v[4:7]
	s_setprio 0
	v_mfma_f32_16x16x32_bf16 v[0:3], v[246:249], v[230:233], v[0:3]
	s_barrier
	s_cbranch_scc0 .LBB0_202
	s_cmp_lt_i32 s2, 18
	v_lshl_add_u32 v190, s3, 8, v186
	v_mov_b32_e32 v128, 1.0
	v_mov_b32_e32 v132, 0
	s_cselect_b64 s[18:19], -1, 0
	s_cmp_gt_i32 s2, 17
	v_mov_b32_e32 v134, 0
	v_mov_b32_e32 v135, 0
	v_mov_b32_e32 v136, 0
	v_mov_b32_e32 v137, 0
	v_mov_b32_e32 v138, 1.0
	v_mov_b32_e32 v139, 1.0
	v_mov_b32_e32 v140, 1.0
	v_mov_b32_e32 v141, 1.0
	s_cbranch_scc1 .LBB0_205
	v_lshlrev_b32_e32 v129, 8, v190
	v_and_b32_e32 v158, 0xfcf00, v129
	v_lshl_add_u64 v[130:131], v[146:147], 0, v[158:159]
	v_lshl_add_u64 v[134:135], v[148:149], 0, v[158:159]
	global_load_dwordx4 v[138:141], v[130:131], off
	s_nop 0
	global_load_dwordx4 v[134:137], v[134:135], off

; #define PG8_STAGE(bufoff, gbase) do { _Pragma("unroll") for (int _i = 0; _i < 2; ++_i) \
;         __builtin_amdgcn_global_load_lds((const unsigned*)((const char*)(gbase) + voff[_i]), (LAS unsigned*)(lds + (bufoff) + ldsw + _i * 8192), 16, 0, 0); } while (0)
; #define PG8_LDA(dst, b, h) do { _Pragma("unroll") for (int m = 0; m < 4; ++m) _Pragma("unroll") for (int k = 0; k < 2; ++k) dst[m][k] = *(const LAS bf16x8*)(lds + PG8_SA(b, h) + aoff + m * 2048 + k * 1024); } while (0)
; #define PG8_LDB(dst, b, h) do { _Pragma("unroll") for (int n = 0; n < 2; ++n) _Pragma("unroll") for (int k = 0; k < 2; ++k) dst[n][k] = *(const LAS bf16x8*)(lds + PG8_SB(b, h) + boff + n * 2048 + k * 1024); } while (0)
; #define PG8_MMA(ai, bj, At, Bt) do { __builtin_amdgcn_s_setprio(1); _Pragma("unroll") for (int m = 0; m < 4; ++m) _Pragma("unroll") for (int n = 0; n < 2; ++n) _Pragma("unroll") for (int k = 0; k < 2; ++k) \
;         acc[ai][bj][m][n] = __builtin_amdgcn_mfma_f32_16x16x32_bf16(Bt[n][k], At[m][k], acc[ai][bj][m][n], 0, 0, 0); __builtin_amdgcn_s_setprio(0); } while (0)
; template <class Epi>
; DI void gemm_phase(LAS unsigned char* lds, const Gemm g, const StaticOrder& S, const Epi& E) {
;     ...
;         const bool has_next = S.next(ui + 1, nxt);
;         const char* nA = has_next ? (const char*)g.A + (size_t)nxt.pm * tstep : cA; const char* nB = has_next ? (const char*)g.Bt + (size_t)nxt.pn * tstep : cB;
;         for (int t = 0; t < nt; t += 2) {
;             const bool last = (t == nt - 2);
;             const char* a1 = cA + (size_t)(t + 1) * kstep;
;             const char* a2 = last ? nA : cA + (size_t)(t + 2) * kstep; const char* b2 = last ? nB : cB + (size_t)(t + 2) * kstep;
;             const char* a3 = a2 + kstep; const char* b3 = b2 + kstep;
;             PG8_LDB(B0, 0, 0); PG8_SCHED; PG8_LDA(At, 0, 0); PG8_STAGE(PG8_SA(1, 1), a1 + hstep);
;             PG8_WAIT_L(8); PG8_BAR; PG8_WAIT_L(0); PG8_MMA(0, 0, At, B0); PG8_BAR; PG8_SCHED;
;             PG8_LDB(B1, 0, 1); PG8_STAGE(PG8_SB(0, 0), b2);
;             PG8_BAR; PG8_WAIT_L(0); PG8_MMA(0, 1, At, B1); PG8_BAR;
;             PG8_LDA(At, 0, 1); PG8_STAGE(PG8_SA(0, 0), a2);
;             PG8_BAR; PG8_WAIT_L(0); PG8_MMA(1, 0, At, B0); PG8_BAR; PG8_SCHED;
;             PG8_STAGE(PG8_SB(0, 1), b2 + hstep);
;             PG8_WAIT_V(6); PG8_BAR; PG8_MMA(1, 1, At, B1); PG8_BAR;
.LBB0_231:
	ds_read_b128 v[138:141], v135
	ds_read_b128 v[142:145], v135 offset:1024
	ds_read_b128 v[146:149], v135 offset:2048
	ds_read_b128 v[150:153], v135 offset:3072
	ds_read_b128 v[186:189], v137
	ds_read_b128 v[190:193], v137 offset:1024
	ds_read_b128 v[194:197], v137 offset:2048
	ds_read_b128 v[198:201], v137 offset:3072
	ds_read_b128 v[202:205], v137 offset:4096
	ds_read_b128 v[206:209], v137 offset:5120
	ds_read_b128 v[210:213], v137 offset:6144
	ds_read_b128 v[214:217], v137 offset:7168
	s_add_u32 s18, s16, 0xfff80080
	s_addc_u32 s19, s17, -1
	s_add_i32 s37, 0, 0x10000
	s_cmp_eq_u32 s36, 28
	s_cselect_b32 s21, s4, s19
	s_cselect_b32 s20, s5, s18
	s_cselect_b32 s19, s9, s35
	s_cselect_b32 s18, s11, s34
	s_add_i32 m0, s24, 0xc000
	s_nop 0
	global_load_lds_dwordx4 v130, s[16:17]
	s_add_i32 m0, s24, 0xe000
	s_nop 0
	global_load_lds_dwordx4 v132, s[16:17]
	s_waitcnt lgkmcnt(8)
	s_setprio 1
	s_barrier
	s_waitcnt lgkmcnt(0)
	v_mfma_f32_16x16x32_bf16 v[124:127], v[138:141], v[186:189], v[124:127]
	v_mfma_f32_16x16x32_bf16 v[120:123], v[146:149], v[186:189], v[120:123]
	v_mfma_f32_16x16x32_bf16 v[116:119], v[138:141], v[194:197], v[116:119]
	v_mfma_f32_16x16x32_bf16 v[112:115], v[146:149], v[194:197], v[112:115]
	v_mfma_f32_16x16x32_bf16 v[100:103], v[138:141], v[202:205], v[100:103]
	v_mfma_f32_16x16x32_bf16 v[96:99], v[146:149], v[202:205], v[96:99]
	v_mfma_f32_16x16x32_bf16 v[84:87], v[138:141], v[210:213], v[84:87]
	v_mfma_f32_16x16x32_bf16 v[80:83], v[146:149], v[210:213], v[80:83]
	v_mfma_f32_16x16x32_bf16 v[124:127], v[142:145], v[190:193], v[124:127]
	v_mfma_f32_16x16x32_bf16 v[120:123], v[150:153], v[190:193], v[120:123]
	v_mfma_f32_16x16x32_bf16 v[116:119], v[142:145], v[198:201], v[116:119]
	v_mfma_f32_16x16x32_bf16 v[112:115], v[150:153], v[198:201], v[112:115]
	v_mfma_f32_16x16x32_bf16 v[100:103], v[142:145], v[206:209], v[100:103]
	v_mfma_f32_16x16x32_bf16 v[96:99], v[150:153], v[206:209], v[96:99]
	v_mfma_f32_16x16x32_bf16 v[84:87], v[142:145], v[214:217], v[84:87]
	s_setprio 0
	v_mfma_f32_16x16x32_bf16 v[80:83], v[150:153], v[214:217], v[80:83]
	s_barrier
	ds_read_b128 v[226:229], v135 offset:16384
	ds_read_b128 v[230:233], v135 offset:17408
	ds_read_b128 v[234:237], v135 offset:18432
	ds_read_b128 v[238:241], v135 offset:19456
	s_add_i32 s40, 0, 0x14000
	s_add_i32 s37, s37, s23
	s_mov_b32 m0, s37
	s_nop 0
	global_load_lds_dwordx4 v158, s[18:19]
	s_add_i32 m0, s37, 0x2000
	s_nop 0
	global_load_lds_dwordx4 v128, s[18:19]
	s_waitcnt lgkmcnt(0)
	s_setprio 1
	s_barrier
	v_mfma_f32_16x16x32_bf16 v[108:111], v[226:229], v[186:189], v[108:111]
	v_mfma_f32_16x16x32_bf16 v[104:107], v[234:237], v[186:189], v[104:107]
	v_mfma_f32_16x16x32_bf16 v[92:95], v[226:229], v[194:197], v[92:95]
	v_mfma_f32_16x16x32_bf16 v[88:91], v[234:237], v[194:197], v[88:91]
	v_mfma_f32_16x16x32_bf16 v[76:79], v[226:229], v[202:205], v[76:79]
	v_mfma_f32_16x16x32_bf16 v[72:75], v[234:237], v[202:205], v[72:75]
	v_mfma_f32_16x16x32_bf16 v[68:71], v[226:229], v[210:213], v[68:71]
	v_mfma_f32_16x16x32_bf16 v[64:67], v[234:237], v[210:213], v[64:67]
	v_mfma_f32_16x16x32_bf16 v[108:111], v[230:233], v[190:193], v[108:111]
	v_mfma_f32_16x16x32_bf16 v[104:107], v[238:241], v[190:193], v[104:107]
	v_mfma_f32_16x16x32_bf16 v[92:95], v[230:233], v[198:201], v[92:95]
	v_mfma_f32_16x16x32_bf16 v[88:91], v[238:241], v[198:201], v[88:91]
	v_mfma_f32_16x16x32_bf16 v[76:79], v[230:233], v[206:209], v[76:79]
	v_mfma_f32_16x16x32_bf16 v[72:75], v[238:241], v[206:209], v[72:75]
	v_mfma_f32_16x16x32_bf16 v[68:71], v[230:233], v[214:217], v[68:71]
	s_setprio 0
	v_mfma_f32_16x16x32_bf16 v[64:67], v[238:241], v[214:217], v[64:67]
	s_barrier
	ds_read_b128 v[186:189], v137 offset:16384
	ds_read_b128 v[190:193], v137 offset:17408
	ds_read_b128 v[194:197], v137 offset:18432
	ds_read_b128 v[198:201], v137 offset:19456
	ds_read_b128 v[202:205], v137 offset:20480
	ds_read_b128 v[206:209], v137 offset:21504
	ds_read_b128 v[210:213], v137 offset:22528
	ds_read_b128 v[214:217], v137 offset:23552
	s_mov_b32 m0, s24
	s_nop 0
	global_load_lds_dwordx4 v158, s[20:21]
	s_mov_b32 m0, s25
	s_mov_b64 s[100:101], s[20:21]
	global_load_lds_dwordx4 v128, s[20:21]
	s_waitcnt lgkmcnt(0)
	s_setprio 1
	s_barrier
	v_mfma_f32_16x16x32_bf16 v[60:63], v[138:141], v[186:189], v[60:63]
	v_mfma_f32_16x16x32_bf16 v[56:59], v[146:149], v[186:189], v[56:59]
	v_mfma_f32_16x16x32_bf16 v[52:55], v[138:141], v[194:197], v[52:55]
	v_mfma_f32_16x16x32_bf16 v[48:51], v[146:149], v[194:197], v[48:51]
	v_mfma_f32_16x16x32_bf16 v[36:39], v[138:141], v[202:205], v[36:39]
	v_mfma_f32_16x16x32_bf16 v[32:35], v[146:149], v[202:205], v[32:35]
	v_mfma_f32_16x16x32_bf16 v[20:23], v[138:141], v[210:213], v[20:23]
	v_mfma_f32_16x16x32_bf16 v[16:19], v[146:149], v[210:213], v[16:19]
	v_mfma_f32_16x16x32_bf16 v[60:63], v[142:145], v[190:193], v[60:63]
	v_mfma_f32_16x16x32_bf16 v[56:59], v[150:153], v[190:193], v[56:59]
	v_mfma_f32_16x16x32_bf16 v[52:55], v[142:145], v[198:201], v[52:55]
	v_mfma_f32_16x16x32_bf16 v[48:51], v[150:153], v[198:201], v[48:51]
	v_mfma_f32_16x16x32_bf16 v[36:39], v[142:145], v[206:209], v[36:39]
	v_mfma_f32_16x16x32_bf16 v[32:35], v[150:153], v[206:209], v[32:35]
	v_mfma_f32_16x16x32_bf16 v[20:23], v[142:145], v[214:217], v[20:23]
	s_setprio 0
	v_mfma_f32_16x16x32_bf16 v[16:19], v[150:153], v[214:217], v[16:19]
	s_barrier
	s_add_u32 s38, s18, 0x80000
	s_addc_u32 s39, s19, 0
	s_add_i32 s37, s40, s23
	s_mov_b32 m0, s37
	s_nop 0
	global_load_lds_dwordx4 v158, s[38:39]
	s_add_i32 m0, s37, 0x2000
	s_nop 0
	global_load_lds_dwordx4 v128, s[38:39]
	s_waitcnt vmcnt(6)
	s_setprio 1
	s_barrier
; #define PG8_STAGE(bufoff, gbase) do { _Pragma("unroll") for (int _i = 0; _i < 2; ++_i) \
;         __builtin_amdgcn_global_load_lds((const unsigned*)((const char*)(gbase) + voff[_i]), (LAS unsigned*)(lds + (bufoff) + ldsw + _i * 8192), 16, 0, 0); } while (0)
; #define PG8_LDA(dst, b, h) do { _Pragma("unroll") for (int m = 0; m < 4; ++m) _Pragma("unroll") for (int k = 0; k < 2; ++k) dst[m][k] = *(const LAS bf16x8*)(lds + PG8_SA(b, h) + aoff + m * 2048 + k * 1024); } while (0)
; #define PG8_LDB(dst, b, h) do { _Pragma("unroll") for (int n = 0; n < 2; ++n) _Pragma("unroll") for (int k = 0; k < 2; ++k) dst[n][k] = *(const LAS bf16x8*)(lds + PG8_SB(b, h) + boff + n * 2048 + k * 1024); } while (0)
; #define PG8_MMA(ai, bj, At, Bt) do { __builtin_amdgcn_s_setprio(1); _Pragma("unroll") for (int m = 0; m < 4; ++m) _Pragma("unroll") for (int n = 0; n < 2; ++n) _Pragma("unroll") for (int k = 0; k < 2; ++k) \
;         acc[ai][bj][m][n] = __builtin_amdgcn_mfma_f32_16x16x32_bf16(Bt[n][k], At[m][k], acc[ai][bj][m][n], 0, 0, 0); __builtin_amdgcn_s_setprio(0); } while (0)
; #define PG8_WAIT_V(n) asm volatile("s_waitcnt vmcnt(" #n ")" ::: "memory")
; #define PG8_WAIT_L(n) asm volatile("s_waitcnt lgkmcnt(" #n ")" ::: "memory")
; #define PG8_BAR __builtin_amdgcn_s_barrier()
; #define PG8_SCHED __builtin_amdgcn_sched_barrier(0)
; template <class Epi>
; DI void gemm_phase(LAS unsigned char* lds, const Gemm g, const StaticOrder& S, const Epi& E) {
;     ...
;             PG8_WAIT_V(6); PG8_BAR; PG8_MMA(1, 1, At, B1); PG8_BAR;
;             PG8_LDB(B0, 1, 0); PG8_SCHED; PG8_LDA(At, 1, 0); PG8_STAGE(PG8_SA(0, 1), a2 + hstep);
;             PG8_WAIT_L(8); PG8_BAR; PG8_WAIT_L(0); PG8_MMA(0, 0, At, B0); PG8_BAR; PG8_SCHED;
;             PG8_LDB(B1, 1, 1); PG8_STAGE(PG8_SB(1, 0), b3);
;             PG8_BAR; PG8_WAIT_L(0); PG8_MMA(0, 1, At, B1); PG8_BAR;
;             PG8_LDA(At, 1, 1); PG8_STAGE(PG8_SA(1, 0), a3);
;             PG8_BAR; PG8_WAIT_L(0); PG8_MMA(1, 0, At, B0); PG8_BAR; PG8_SCHED;
	v_mfma_f32_16x16x32_bf16 v[44:47], v[226:229], v[186:189], v[44:47]
	v_mfma_f32_16x16x32_bf16 v[40:43], v[234:237], v[186:189], v[40:43]
	v_mfma_f32_16x16x32_bf16 v[28:31], v[226:229], v[194:197], v[28:31]
	v_mfma_f32_16x16x32_bf16 v[24:27], v[234:237], v[194:197], v[24:27]
	v_mfma_f32_16x16x32_bf16 v[12:15], v[226:229], v[202:205], v[12:15]
	v_mfma_f32_16x16x32_bf16 v[8:11], v[234:237], v[202:205], v[8:11]
	v_mfma_f32_16x16x32_bf16 v[4:7], v[226:229], v[210:213], v[4:7]
	v_mfma_f32_16x16x32_bf16 v[0:3], v[234:237], v[210:213], v[0:3]
	v_mfma_f32_16x16x32_bf16 v[44:47], v[230:233], v[190:193], v[44:47]
	v_mfma_f32_16x16x32_bf16 v[40:43], v[238:241], v[190:193], v[40:43]
	v_mfma_f32_16x16x32_bf16 v[28:31], v[230:233], v[198:201], v[28:31]
	v_mfma_f32_16x16x32_bf16 v[24:27], v[238:241], v[198:201], v[24:27]
	v_mfma_f32_16x16x32_bf16 v[12:15], v[230:233], v[206:209], v[12:15]
	v_mfma_f32_16x16x32_bf16 v[8:11], v[238:241], v[206:209], v[8:11]
	v_mfma_f32_16x16x32_bf16 v[4:7], v[230:233], v[214:217], v[4:7]
	s_setprio 0
	v_mfma_f32_16x16x32_bf16 v[0:3], v[238:241], v[214:217], v[0:3]
	s_barrier
	ds_read_b128 v[138:141], v135 offset:32768
	ds_read_b128 v[142:145], v135 offset:33792
	ds_read_b128 v[146:149], v135 offset:34816
	ds_read_b128 v[150:153], v135 offset:35840
	ds_read_b128 v[186:189], v137 offset:32768
	ds_read_b128 v[190:193], v137 offset:33792
	ds_read_b128 v[194:197], v137 offset:34816
	ds_read_b128 v[198:201], v137 offset:35840
	ds_read_b128 v[202:205], v137 offset:36864
	ds_read_b128 v[206:209], v137 offset:37888
	ds_read_b128 v[210:213], v137 offset:38912
	ds_read_b128 v[214:217], v137 offset:39936
	s_add_i32 s37, 0, 0x18000
	s_add_u32 s20, s20, 0x80000
	s_addc_u32 s21, s21, 0
	s_mov_b32 m0, s26
	s_nop 0
	global_load_lds_dwordx4 v158, s[20:21]
	s_mov_b32 m0, s27
	s_nop 0
	global_load_lds_dwordx4 v128, s[20:21]
	s_waitcnt lgkmcnt(8)
	s_setprio 1
	s_barrier
	s_waitcnt lgkmcnt(0)
	v_mfma_f32_16x16x32_bf16 v[124:127], v[138:141], v[186:189], v[124:127]
	v_mfma_f32_16x16x32_bf16 v[120:123], v[146:149], v[186:189], v[120:123]
	v_mfma_f32_16x16x32_bf16 v[116:119], v[138:141], v[194:197], v[116:119]
	v_mfma_f32_16x16x32_bf16 v[112:115], v[146:149], v[194:197], v[112:115]
	v_mfma_f32_16x16x32_bf16 v[100:103], v[138:141], v[202:205], v[100:103]
	v_mfma_f32_16x16x32_bf16 v[96:99], v[146:149], v[202:205], v[96:99]
	v_mfma_f32_16x16x32_bf16 v[84:87], v[138:141], v[210:213], v[84:87]
	v_mfma_f32_16x16x32_bf16 v[80:83], v[146:149], v[210:213], v[80:83]
	v_mfma_f32_16x16x32_bf16 v[124:127], v[142:145], v[190:193], v[124:127]
	v_mfma_f32_16x16x32_bf16 v[120:123], v[150:153], v[190:193], v[120:123]
	v_mfma_f32_16x16x32_bf16 v[116:119], v[142:145], v[198:201], v[116:119]
	v_mfma_f32_16x16x32_bf16 v[112:115], v[150:153], v[198:201], v[112:115]
	v_mfma_f32_16x16x32_bf16 v[100:103], v[142:145], v[206:209], v[100:103]
	v_mfma_f32_16x16x32_bf16 v[96:99], v[150:153], v[206:209], v[96:99]
	v_mfma_f32_16x16x32_bf16 v[84:87], v[142:145], v[214:217], v[84:87]
	s_setprio 0
	v_mfma_f32_16x16x32_bf16 v[80:83], v[150:153], v[214:217], v[80:83]
	s_barrier
	ds_read_b128 v[226:229], v135 offset:49152
	ds_read_b128 v[230:233], v135 offset:50176
	ds_read_b128 v[234:237], v135 offset:51200
	ds_read_b128 v[238:241], v135 offset:52224
	s_add_i32 s20, 0, 0x1c000
	s_add_i32 s21, s37, s23
	s_add_i32 m0, s21, 0xffffff80
	s_nop 0
	global_load_lds_dwordx4 v158, s[18:19] offset:128
	s_add_i32 m0, s21, 0x1f80
	s_nop 0
	global_load_lds_dwordx4 v128, s[18:19] offset:128
	s_waitcnt lgkmcnt(0)
	s_setprio 1
	s_barrier
	v_mfma_f32_16x16x32_bf16 v[108:111], v[226:229], v[186:189], v[108:111]
	v_mfma_f32_16x16x32_bf16 v[104:107], v[234:237], v[186:189], v[104:107]
	v_mfma_f32_16x16x32_bf16 v[92:95], v[226:229], v[194:197], v[92:95]
	v_mfma_f32_16x16x32_bf16 v[88:91], v[234:237], v[194:197], v[88:91]
	v_mfma_f32_16x16x32_bf16 v[76:79], v[226:229], v[202:205], v[76:79]
	v_mfma_f32_16x16x32_bf16 v[72:75], v[234:237], v[202:205], v[72:75]
	v_mfma_f32_16x16x32_bf16 v[68:71], v[226:229], v[210:213], v[68:71]
	v_mfma_f32_16x16x32_bf16 v[64:67], v[234:237], v[210:213], v[64:67]
	v_mfma_f32_16x16x32_bf16 v[108:111], v[230:233], v[190:193], v[108:111]
	v_mfma_f32_16x16x32_bf16 v[104:107], v[238:241], v[190:193], v[104:107]
	v_mfma_f32_16x16x32_bf16 v[92:95], v[230:233], v[198:201], v[92:95]
	v_mfma_f32_16x16x32_bf16 v[88:91], v[238:241], v[198:201], v[88:91]
	v_mfma_f32_16x16x32_bf16 v[76:79], v[230:233], v[206:209], v[76:79]
	v_mfma_f32_16x16x32_bf16 v[72:75], v[238:241], v[206:209], v[72:75]
	v_mfma_f32_16x16x32_bf16 v[68:71], v[230:233], v[214:217], v[68:71]
	s_setprio 0
	v_mfma_f32_16x16x32_bf16 v[64:67], v[238:241], v[214:217], v[64:67]
	s_barrier
	ds_read_b128 v[186:189], v137 offset:49152
	ds_read_b128 v[190:193], v137 offset:50176
	ds_read_b128 v[194:197], v137 offset:51200
	ds_read_b128 v[198:201], v137 offset:52224
	ds_read_b128 v[202:205], v137 offset:53248
	ds_read_b128 v[206:209], v137 offset:54272
	ds_read_b128 v[210:213], v137 offset:55296
	ds_read_b128 v[214:217], v137 offset:56320
	s_add_i32 m0, s28, 0xffffff80
	s_nop 0
	global_load_lds_dwordx4 v158, s[100:101] offset:128
	s_add_i32 m0, s29, 0xffffff80
	s_nop 0
	global_load_lds_dwordx4 v128, s[100:101] offset:128
	s_waitcnt lgkmcnt(0)
	s_setprio 1
	s_barrier
; #define PG8_STAGE(bufoff, gbase) do { _Pragma("unroll") for (int _i = 0; _i < 2; ++_i) \
;         __builtin_amdgcn_global_load_lds((const unsigned*)((const char*)(gbase) + voff[_i]), (LAS unsigned*)(lds + (bufoff) + ldsw + _i * 8192), 16, 0, 0); } while (0)
; #define PG8_MMA(ai, bj, At, Bt) do { __builtin_amdgcn_s_setprio(1); _Pragma("unroll") for (int m = 0; m < 4; ++m) _Pragma("unroll") for (int n = 0; n < 2; ++n) _Pragma("unroll") for (int k = 0; k < 2; ++k) \
;         acc[ai][bj][m][n] = __builtin_amdgcn_mfma_f32_16x16x32_bf16(Bt[n][k], At[m][k], acc[ai][bj][m][n], 0, 0, 0); __builtin_amdgcn_s_setprio(0); } while (0)
; #define PG8_WAIT_V(n) asm volatile("s_waitcnt vmcnt(" #n ")" ::: "memory")
; #define PG8_WAIT_L(n) asm volatile("s_waitcnt lgkmcnt(" #n ")" ::: "memory")
; #define PG8_BAR __builtin_amdgcn_s_barrier()
; #define PG8_SCHED __builtin_amdgcn_sched_barrier(0)
; template <class Epi>
; DI void gemm_phase(LAS unsigned char* lds, const Gemm g, const StaticOrder& S, const Epi& E) {
;     ...
;             PG8_BAR; PG8_WAIT_L(0); PG8_MMA(1, 0, At, B0); PG8_BAR; PG8_SCHED;
;             PG8_STAGE(PG8_SB(1, 1), b3 + hstep);
;             PG8_WAIT_V(6); PG8_BAR; PG8_MMA(1, 1, At, B1); PG8_BAR;
;         }
	v_mfma_f32_16x16x32_bf16 v[60:63], v[138:141], v[186:189], v[60:63]
	v_mfma_f32_16x16x32_bf16 v[56:59], v[146:149], v[186:189], v[56:59]
	v_mfma_f32_16x16x32_bf16 v[52:55], v[138:141], v[194:197], v[52:55]
	v_mfma_f32_16x16x32_bf16 v[48:51], v[146:149], v[194:197], v[48:51]
	v_mfma_f32_16x16x32_bf16 v[36:39], v[138:141], v[202:205], v[36:39]
	v_mfma_f32_16x16x32_bf16 v[32:35], v[146:149], v[202:205], v[32:35]
	v_mfma_f32_16x16x32_bf16 v[20:23], v[138:141], v[210:213], v[20:23]
	v_mfma_f32_16x16x32_bf16 v[16:19], v[146:149], v[210:213], v[16:19]
	v_mfma_f32_16x16x32_bf16 v[60:63], v[142:145], v[190:193], v[60:63]
	v_mfma_f32_16x16x32_bf16 v[56:59], v[150:153], v[190:193], v[56:59]
	v_mfma_f32_16x16x32_bf16 v[52:55], v[142:145], v[198:201], v[52:55]
	v_mfma_f32_16x16x32_bf16 v[48:51], v[150:153], v[198:201], v[48:51]
	v_mfma_f32_16x16x32_bf16 v[36:39], v[142:145], v[206:209], v[36:39]
	v_mfma_f32_16x16x32_bf16 v[32:35], v[150:153], v[206:209], v[32:35]
	v_mfma_f32_16x16x32_bf16 v[20:23], v[142:145], v[214:217], v[20:23]
	s_setprio 0
	v_mfma_f32_16x16x32_bf16 v[16:19], v[150:153], v[214:217], v[16:19]
	s_barrier
	s_add_u32 s18, s18, 0x80080
	s_addc_u32 s19, s19, 0
	s_add_i32 s20, s20, s23
	s_mov_b32 m0, s20
	s_nop 0
	global_load_lds_dwordx4 v158, s[18:19]
	s_add_i32 m0, s20, 0x2000
	s_nop 0
	global_load_lds_dwordx4 v128, s[18:19]
	s_waitcnt vmcnt(6)
	s_setprio 1
	s_barrier
	v_mfma_f32_16x16x32_bf16 v[44:47], v[226:229], v[186:189], v[44:47]
	v_mfma_f32_16x16x32_bf16 v[40:43], v[234:237], v[186:189], v[40:43]
	v_mfma_f32_16x16x32_bf16 v[28:31], v[226:229], v[194:197], v[28:31]
	v_mfma_f32_16x16x32_bf16 v[24:27], v[234:237], v[194:197], v[24:27]
	v_mfma_f32_16x16x32_bf16 v[12:15], v[226:229], v[202:205], v[12:15]
	v_mfma_f32_16x16x32_bf16 v[8:11], v[234:237], v[202:205], v[8:11]
	v_mfma_f32_16x16x32_bf16 v[4:7], v[226:229], v[210:213], v[4:7]
	v_mfma_f32_16x16x32_bf16 v[0:3], v[234:237], v[210:213], v[0:3]
	v_mfma_f32_16x16x32_bf16 v[44:47], v[230:233], v[190:193], v[44:47]
	s_add_i32 s36, s36, 2
	v_mfma_f32_16x16x32_bf16 v[40:43], v[238:241], v[190:193], v[40:43]
	s_add_u32 s16, s16, 0x100
	v_mfma_f32_16x16x32_bf16 v[28:31], v[230:233], v[198:201], v[28:31]
	s_addc_u32 s17, s17, 0
	v_mfma_f32_16x16x32_bf16 v[24:27], v[238:241], v[198:201], v[24:27]
	s_add_u32 s34, s34, 0x100
	v_mfma_f32_16x16x32_bf16 v[12:15], v[230:233], v[206:209], v[12:15]
	s_addc_u32 s35, s35, 0
	v_mfma_f32_16x16x32_bf16 v[8:11], v[238:241], v[206:209], v[8:11]
	s_cmp_gt_u32 s36, 29
	v_mfma_f32_16x16x32_bf16 v[4:7], v[230:233], v[214:217], v[4:7]
	s_setprio 0
	v_mfma_f32_16x16x32_bf16 v[0:3], v[238:241], v[214:217], v[0:3]
	s_barrier
	s_cbranch_scc0 .LBB0_231
; #define PG8_WAIT_V(n) asm volatile("s_waitcnt vmcnt(" #n ")" ::: "memory")
; #define PG8_BAR __builtin_amdgcn_s_barrier()
; template <class Epi>
; DI void gemm_phase(LAS unsigned char* lds, const Gemm g, const StaticOrder& S, const Epi& E) {
;     ...
;         E(acc, cur, wr, wc, fr, fq);
;         if (!has_next) break;
; #pragma unroll
;         for (int a = 0; a < 2; ++a)
; #pragma unroll
;             for (int b = 0; b < 2; ++b)
; #pragma unroll
;                 for (int m = 0; m < 4; ++m)
; #pragma unroll
;                     for (int n = 0; n < 2; ++n) acc[a][b][m][n] = (f32x4){0.f, 0.f, 0.f, 0.f};
;         cur = nxt; cA = nA; cB = nB; ++ui;
;     }
;     PG8_WAIT_V(0);
;     if (wr == 0) PG8_BAR;
;     PG8_BAR;
;     DI void operator()(const f32x4 (&acc)[2][2][4][2], const Unit& u, int wr, int wc, int fr, int fq) const {
;         const int row0 = u.pm * BM + wr * 64 + fr, col0 = u.pn * BM + wc * 32 + 8 * fq;
; #pragma unroll
;         for (int ai = 0; ai < 2; ++ai)
; #pragma unroll
;             for (int m = 0; m < 4; ++m) { u16* rowp = O + (size_t)(row0 + ai * HALF + m * 16) * ldc + col0;
; #pragma unroll
;                 for (int bj = 0; bj < 2; ++bj) { const f32x4 v0 = acc[ai][bj][m][0], v1 = acc[ai][bj][m][1];
;                     *(u32x4*)(rowp + bj * HALF) = (u32x4){pk(v0[0], v0[1]), pk(v0[2], v0[3]), pk(v1[0], v1[1]), pk(v1[2], v1[3])}; } }
	v_lshl_add_u32 v144, s33, 8, v134
	v_lshl_or_b32 v138, s31, 8, v136
	v_ashrrev_i32_e32 v139, 31, v138
	v_mov_b64_e32 v[140:141], s[50:51]
	s_movk_i32 s9, 0x3000
	v_cvt_pk_bf16_f32 v68, v68, v69
	v_cvt_pk_bf16_f32 v69, v70, v71
	v_cvt_pk_bf16_f32 v70, v64, v65
	v_add_u32_e32 v64, 0x80, v144
	v_mad_i64_i32 v[142:143], s[4:5], v144, s9, v[140:141]
	v_lshlrev_b64 v[138:139], 1, v[138:139]
	v_cvt_pk_bf16_f32 v108, v108, v109
	v_cvt_pk_bf16_f32 v109, v110, v111
	v_cvt_pk_bf16_f32 v110, v104, v105
	v_or_b32_e32 v104, 16, v144
	v_mad_i64_i32 v[64:65], s[4:5], v64, s9, v[140:141]
	v_cvt_pk_bf16_f32 v44, v44, v45
	v_cvt_pk_bf16_f32 v45, v46, v47
	v_cvt_pk_bf16_f32 v46, v40, v41
	v_add_u32_e32 v40, 0x90, v144
	v_lshl_add_u64 v[142:143], v[142:143], 0, v[138:139]
	v_cvt_pk_bf16_f32 v111, v106, v107
	v_mad_i64_i32 v[104:105], s[4:5], v104, s9, v[140:141]
	v_cvt_pk_bf16_f32 v92, v92, v93
	v_cvt_pk_bf16_f32 v93, v94, v95
	v_cvt_pk_bf16_f32 v94, v88, v89
	v_or_b32_e32 v88, 32, v144
	v_lshl_add_u64 v[64:65], v[64:65], 0, v[138:139]
	v_cvt_pk_bf16_f32 v47, v42, v43
	v_mad_i64_i32 v[40:41], s[4:5], v40, s9, v[140:141]
	v_cvt_pk_bf16_f32 v28, v28, v29
	v_cvt_pk_bf16_f32 v29, v30, v31
	v_cvt_pk_bf16_f32 v30, v24, v25
	v_add_u32_e32 v24, 0xa0, v144
	global_store_dwordx4 v[142:143], v[108:111], off offset:256
	v_cvt_pk_bf16_f32 v95, v90, v91
	v_mad_i64_i32 v[88:89], s[4:5], v88, s9, v[140:141]
	v_lshl_add_u64 v[108:109], v[104:105], 0, v[138:139]
	v_cvt_pk_bf16_f32 v76, v76, v77
	v_cvt_pk_bf16_f32 v77, v78, v79
	v_cvt_pk_bf16_f32 v78, v72, v73
	v_or_b32_e32 v72, 48, v144
	global_store_dwordx4 v[64:65], v[44:47], off offset:256
	v_cvt_pk_bf16_f32 v31, v26, v27
	v_mad_i64_i32 v[24:25], s[4:5], v24, s9, v[140:141]
	v_lshl_add_u64 v[44:45], v[40:41], 0, v[138:139]
	v_cvt_pk_bf16_f32 v12, v12, v13
	v_cvt_pk_bf16_f32 v13, v14, v15
	v_cvt_pk_bf16_f32 v14, v8, v9
	v_add_u32_e32 v8, 0xb0, v144
	global_store_dwordx4 v[108:109], v[92:95], off offset:256
	v_cvt_pk_bf16_f32 v79, v74, v75
	v_mad_i64_i32 v[72:73], s[4:5], v72, s9, v[140:141]
	v_lshl_add_u64 v[92:93], v[88:89], 0, v[138:139]
	global_store_dwordx4 v[44:45], v[28:31], off offset:256
	v_cvt_pk_bf16_f32 v15, v10, v11
	v_mad_i64_i32 v[8:9], s[4:5], v8, s9, v[140:141]
	v_lshl_add_u64 v[28:29], v[24:25], 0, v[138:139]
	v_cvt_pk_bf16_f32 v124, v124, v125
	v_cvt_pk_bf16_f32 v125, v126, v127
	v_cvt_pk_bf16_f32 v126, v120, v121
	v_cvt_pk_bf16_f32 v127, v122, v123
	v_cvt_pk_bf16_f32 v104, v116, v117
	v_cvt_pk_bf16_f32 v105, v118, v119
	v_cvt_pk_bf16_f32 v106, v112, v113
	v_cvt_pk_bf16_f32 v107, v114, v115
	v_cvt_pk_bf16_f32 v88, v100, v101
	v_cvt_pk_bf16_f32 v89, v102, v103
	v_cvt_pk_bf16_f32 v90, v96, v97
	v_cvt_pk_bf16_f32 v91, v98, v99
	global_store_dwordx4 v[92:93], v[76:79], off offset:256
	v_cvt_pk_bf16_f32 v74, v80, v81
	v_cvt_pk_bf16_f32 v75, v82, v83
	v_lshl_add_u64 v[76:77], v[72:73], 0, v[138:139]
	v_cvt_pk_bf16_f32 v72, v84, v85
	v_cvt_pk_bf16_f32 v73, v86, v87
	v_cvt_pk_bf16_f32 v71, v66, v67
	v_cvt_pk_bf16_f32 v60, v60, v61
	v_cvt_pk_bf16_f32 v61, v62, v63
	v_cvt_pk_bf16_f32 v62, v56, v57
	v_cvt_pk_bf16_f32 v63, v58, v59
	v_cvt_pk_bf16_f32 v40, v52, v53
	v_cvt_pk_bf16_f32 v41, v54, v55
	v_cvt_pk_bf16_f32 v42, v48, v49
	v_cvt_pk_bf16_f32 v43, v50, v51
	v_cvt_pk_bf16_f32 v24, v36, v37
	v_cvt_pk_bf16_f32 v25, v38, v39
	v_cvt_pk_bf16_f32 v26, v32, v33
	v_cvt_pk_bf16_f32 v27, v34, v35
	global_store_dwordx4 v[28:29], v[12:15], off offset:256
	v_cvt_pk_bf16_f32 v10, v16, v17
	v_cvt_pk_bf16_f32 v11, v18, v19
	v_lshl_add_u64 v[12:13], v[8:9], 0, v[138:139]
	v_cvt_pk_bf16_f32 v8, v20, v21
	v_cvt_pk_bf16_f32 v9, v22, v23
	v_cvt_pk_bf16_f32 v4, v4, v5
	v_cvt_pk_bf16_f32 v5, v6, v7
	v_cvt_pk_bf16_f32 v6, v0, v1
	v_cvt_pk_bf16_f32 v7, v2, v3
	s_and_b64 vcc, exec, s[6:7]
	s_mov_b32 s31, s8
	s_mov_b32 s33, s10
	s_mov_b64 s[18:19], s[14:15]
	s_mov_b64 s[16:17], s[12:13]
	global_store_dwordx4 v[142:143], v[124:127], off
	global_store_dwordx4 v[108:109], v[104:107], off
	global_store_dwordx4 v[92:93], v[88:91], off
	global_store_dwordx4 v[76:77], v[72:75], off
	global_store_dwordx4 v[76:77], v[68:71], off offset:256
	global_store_dwordx4 v[64:65], v[60:63], off
	global_store_dwordx4 v[44:45], v[40:43], off
	global_store_dwordx4 v[28:29], v[24:27], off
	global_store_dwordx4 v[12:13], v[8:11], off
	global_store_dwordx4 v[12:13], v[4:7], off offset:256
	s_cbranch_vccz .LBB0_228
	s_waitcnt vmcnt(0)
	s_cmpk_gt_u32 s2, 0xff
	s_cbranch_scc1 .LBB0_235
	s_barrier

; #define PG8_STAGE(bufoff, gbase) do { _Pragma("unroll") for (int _i = 0; _i < 2; ++_i) \
;         __builtin_amdgcn_global_load_lds((const unsigned*)((const char*)(gbase) + voff[_i]), (LAS unsigned*)(lds + (bufoff) + ldsw + _i * 8192), 16, 0, 0); } while (0)
; #define PG8_LDA(dst, b, h) do { _Pragma("unroll") for (int m = 0; m < 4; ++m) _Pragma("unroll") for (int k = 0; k < 2; ++k) dst[m][k] = *(const LAS bf16x8*)(lds + PG8_SA(b, h) + aoff + m * 2048 + k * 1024); } while (0)
; #define PG8_LDB(dst, b, h) do { _Pragma("unroll") for (int n = 0; n < 2; ++n) _Pragma("unroll") for (int k = 0; k < 2; ++k) dst[n][k] = *(const LAS bf16x8*)(lds + PG8_SB(b, h) + boff + n * 2048 + k * 1024); } while (0)
; #define PG8_MMA(ai, bj, At, Bt) do { __builtin_amdgcn_s_setprio(1); _Pragma("unroll") for (int m = 0; m < 4; ++m) _Pragma("unroll") for (int n = 0; n < 2; ++n) _Pragma("unroll") for (int k = 0; k < 2; ++k) \
;         acc[ai][bj][m][n] = __builtin_amdgcn_mfma_f32_16x16x32_bf16(Bt[n][k], At[m][k], acc[ai][bj][m][n], 0, 0, 0); __builtin_amdgcn_s_setprio(0); } while (0)
; template <class Epi>
; DI void gemm_phase(LAS unsigned char* lds, const Gemm g, const StaticOrder& S, const Epi& E) {
;     ...
;         const bool has_next = S.next(ui + 1, nxt);
;         const char* nA = has_next ? (const char*)g.A + (size_t)nxt.pm * tstep : cA; const char* nB = has_next ? (const char*)g.Bt + (size_t)nxt.pn * tstep : cB;
;         for (int t = 0; t < nt; t += 2) {
;             const bool last = (t == nt - 2);
;             const char* a1 = cA + (size_t)(t + 1) * kstep;
;             const char* a2 = last ? nA : cA + (size_t)(t + 2) * kstep; const char* b2 = last ? nB : cB + (size_t)(t + 2) * kstep;
;             const char* a3 = a2 + kstep; const char* b3 = b2 + kstep;
;             PG8_LDB(B0, 0, 0); PG8_SCHED; PG8_LDA(At, 0, 0); PG8_STAGE(PG8_SA(1, 1), a1 + hstep);
;             PG8_WAIT_L(8); PG8_BAR; PG8_WAIT_L(0); PG8_MMA(0, 0, At, B0); PG8_BAR; PG8_SCHED;
;             PG8_LDB(B1, 0, 1); PG8_STAGE(PG8_SB(0, 0), b2);
;             PG8_BAR; PG8_WAIT_L(0); PG8_MMA(0, 1, At, B1); PG8_BAR;
;             PG8_LDA(At, 0, 1); PG8_STAGE(PG8_SA(0, 0), a2);
;             PG8_BAR; PG8_WAIT_L(0); PG8_MMA(1, 0, At, B0); PG8_BAR; PG8_SCHED;
;             PG8_STAGE(PG8_SB(0, 1), b2 + hstep);
;             PG8_WAIT_V(6); PG8_BAR; PG8_MMA(1, 1, At, B1); PG8_BAR;
.LBB0_320:
	s_add_u32 s26, s24, 0x100
	s_addc_u32 s27, s25, 0
	s_add_i32 s47, 0, 0x10000
	ds_read_b128 v[128:131], v226
	ds_read_b128 v[132:135], v226 offset:1024
	ds_read_b128 v[136:139], v226 offset:2048
	ds_read_b128 v[140:143], v226 offset:3072
	s_cmp_eq_u32 s46, 28
	s_cselect_b32 s31, s4, s27
	s_cselect_b32 s30, s5, s26
	s_cselect_b32 s29, s9, s45
	s_cselect_b32 s28, s11, s33
	v_lshl_add_u64 v[214:215], s[24:25], 0, v[190:191]
	s_add_i32 m0, s38, 0xc000
	ds_read_b128 v[144:147], v228
	ds_read_b128 v[148:151], v228 offset:1024
	ds_read_b128 v[152:155], v228 offset:2048
	ds_read_b128 v[194:197], v228 offset:3072
	ds_read_b128 v[198:201], v228 offset:4096
	ds_read_b128 v[202:205], v228 offset:5120
	ds_read_b128 v[206:209], v228 offset:6144
	ds_read_b128 v[210:213], v228 offset:7168
	global_load_lds_dwordx4 v[214:215], off
	v_lshl_add_u64 v[214:215], s[24:25], 0, v[192:193]
	s_add_i32 m0, s38, 0xe000
	s_nop 0
	global_load_lds_dwordx4 v[214:215], off
	s_waitcnt lgkmcnt(8)
	s_setprio 1
	s_barrier
	s_waitcnt lgkmcnt(0)
	v_mfma_f32_16x16x32_bf16 v[124:127], v[128:131], v[144:147], v[124:127]
	v_mfma_f32_16x16x32_bf16 v[120:123], v[136:139], v[144:147], v[120:123]
	v_mfma_f32_16x16x32_bf16 v[116:119], v[128:131], v[152:155], v[116:119]
	v_mfma_f32_16x16x32_bf16 v[112:115], v[136:139], v[152:155], v[112:115]
	v_mfma_f32_16x16x32_bf16 v[108:111], v[128:131], v[198:201], v[108:111]
	v_mfma_f32_16x16x32_bf16 v[104:107], v[136:139], v[198:201], v[104:107]
	v_mfma_f32_16x16x32_bf16 v[100:103], v[128:131], v[206:209], v[100:103]
	v_mfma_f32_16x16x32_bf16 v[96:99], v[136:139], v[206:209], v[96:99]
	v_mfma_f32_16x16x32_bf16 v[124:127], v[132:135], v[148:151], v[124:127]
	v_mfma_f32_16x16x32_bf16 v[120:123], v[140:143], v[148:151], v[120:123]
	v_mfma_f32_16x16x32_bf16 v[116:119], v[132:135], v[194:197], v[116:119]
	v_mfma_f32_16x16x32_bf16 v[112:115], v[140:143], v[194:197], v[112:115]
	v_mfma_f32_16x16x32_bf16 v[108:111], v[132:135], v[202:205], v[108:111]
	v_mfma_f32_16x16x32_bf16 v[104:107], v[140:143], v[202:205], v[104:107]
	v_mfma_f32_16x16x32_bf16 v[100:103], v[132:135], v[210:213], v[100:103]
	s_setprio 0
	v_mfma_f32_16x16x32_bf16 v[96:99], v[140:143], v[210:213], v[96:99]
	s_barrier
	ds_read_b128 v[214:217], v226 offset:16384
	ds_read_b128 v[230:233], v226 offset:17408
	ds_read_b128 v[234:237], v226 offset:18432
	ds_read_b128 v[238:241], v226 offset:19456
	s_add_i32 s48, 0, 0x14000
	s_add_i32 s24, s47, s37
	s_mov_b32 m0, s24
	s_nop 0
	global_load_lds_dwordx4 v188, s[28:29]
	s_add_i32 m0, s24, 0x2000
	s_nop 0
	global_load_lds_dwordx4 v186, s[28:29]
	s_waitcnt lgkmcnt(0)
	s_setprio 1
	s_barrier
	v_mfma_f32_16x16x32_bf16 v[60:63], v[214:217], v[144:147], v[60:63]
	v_mfma_f32_16x16x32_bf16 v[56:59], v[234:237], v[144:147], v[56:59]
	v_mfma_f32_16x16x32_bf16 v[52:55], v[214:217], v[152:155], v[52:55]
	v_mfma_f32_16x16x32_bf16 v[48:51], v[234:237], v[152:155], v[48:51]
	v_mfma_f32_16x16x32_bf16 v[44:47], v[214:217], v[198:201], v[44:47]
	v_mfma_f32_16x16x32_bf16 v[40:43], v[234:237], v[198:201], v[40:43]
	v_mfma_f32_16x16x32_bf16 v[36:39], v[214:217], v[206:209], v[36:39]
	v_mfma_f32_16x16x32_bf16 v[32:35], v[234:237], v[206:209], v[32:35]
	v_mfma_f32_16x16x32_bf16 v[60:63], v[230:233], v[148:151], v[60:63]
	v_mfma_f32_16x16x32_bf16 v[56:59], v[238:241], v[148:151], v[56:59]
	v_mfma_f32_16x16x32_bf16 v[52:55], v[230:233], v[194:197], v[52:55]
	v_mfma_f32_16x16x32_bf16 v[48:51], v[238:241], v[194:197], v[48:51]
	v_mfma_f32_16x16x32_bf16 v[44:47], v[230:233], v[202:205], v[44:47]
	v_mfma_f32_16x16x32_bf16 v[40:43], v[238:241], v[202:205], v[40:43]
	v_mfma_f32_16x16x32_bf16 v[36:39], v[230:233], v[210:213], v[36:39]
	s_setprio 0
	v_mfma_f32_16x16x32_bf16 v[32:35], v[238:241], v[210:213], v[32:35]
	s_barrier
	ds_read_b128 v[144:147], v228 offset:16384
	ds_read_b128 v[148:151], v228 offset:17408
	ds_read_b128 v[152:155], v228 offset:18432
	ds_read_b128 v[194:197], v228 offset:19456
	ds_read_b128 v[198:201], v228 offset:20480
	ds_read_b128 v[202:205], v228 offset:21504
	ds_read_b128 v[206:209], v228 offset:22528
	ds_read_b128 v[210:213], v228 offset:23552
	s_mov_b32 m0, s38
	s_nop 0
	global_load_lds_dwordx4 v188, s[30:31]
	s_mov_b32 m0, s39
	s_mov_b64 s[100:101], s[30:31]
	global_load_lds_dwordx4 v186, s[30:31]
	s_waitcnt lgkmcnt(0)
	s_setprio 1
	s_barrier
	v_mfma_f32_16x16x32_bf16 v[92:95], v[128:131], v[144:147], v[92:95]
	v_mfma_f32_16x16x32_bf16 v[88:91], v[136:139], v[144:147], v[88:91]
	v_mfma_f32_16x16x32_bf16 v[84:87], v[128:131], v[152:155], v[84:87]
	v_mfma_f32_16x16x32_bf16 v[80:83], v[136:139], v[152:155], v[80:83]
	v_mfma_f32_16x16x32_bf16 v[76:79], v[128:131], v[198:201], v[76:79]
	v_mfma_f32_16x16x32_bf16 v[72:75], v[136:139], v[198:201], v[72:75]
	v_mfma_f32_16x16x32_bf16 v[68:71], v[128:131], v[206:209], v[68:71]
	v_mfma_f32_16x16x32_bf16 v[64:67], v[136:139], v[206:209], v[64:67]
	v_mfma_f32_16x16x32_bf16 v[92:95], v[132:135], v[148:151], v[92:95]
	v_mfma_f32_16x16x32_bf16 v[88:91], v[140:143], v[148:151], v[88:91]
	v_mfma_f32_16x16x32_bf16 v[84:87], v[132:135], v[194:197], v[84:87]
	v_mfma_f32_16x16x32_bf16 v[80:83], v[140:143], v[194:197], v[80:83]
	v_mfma_f32_16x16x32_bf16 v[76:79], v[132:135], v[202:205], v[76:79]
	v_mfma_f32_16x16x32_bf16 v[72:75], v[140:143], v[202:205], v[72:75]
	v_mfma_f32_16x16x32_bf16 v[68:71], v[132:135], v[210:213], v[68:71]
	s_setprio 0
	v_mfma_f32_16x16x32_bf16 v[64:67], v[140:143], v[210:213], v[64:67]
	s_barrier
	s_add_u32 s24, s28, 0x80000
	s_addc_u32 s25, s29, 0
	s_add_i32 s47, s48, s37
	s_mov_b32 m0, s47
	s_nop 0
	global_load_lds_dwordx4 v188, s[24:25]
	s_add_i32 m0, s47, 0x2000
	s_nop 0
	global_load_lds_dwordx4 v186, s[24:25]
	s_waitcnt vmcnt(6)
	s_setprio 1
	s_barrier
; #define PG8_STAGE(bufoff, gbase) do { _Pragma("unroll") for (int _i = 0; _i < 2; ++_i) \
;         __builtin_amdgcn_global_load_lds((const unsigned*)((const char*)(gbase) + voff[_i]), (LAS unsigned*)(lds + (bufoff) + ldsw + _i * 8192), 16, 0, 0); } while (0)
; #define PG8_LDA(dst, b, h) do { _Pragma("unroll") for (int m = 0; m < 4; ++m) _Pragma("unroll") for (int k = 0; k < 2; ++k) dst[m][k] = *(const LAS bf16x8*)(lds + PG8_SA(b, h) + aoff + m * 2048 + k * 1024); } while (0)
; #define PG8_LDB(dst, b, h) do { _Pragma("unroll") for (int n = 0; n < 2; ++n) _Pragma("unroll") for (int k = 0; k < 2; ++k) dst[n][k] = *(const LAS bf16x8*)(lds + PG8_SB(b, h) + boff + n * 2048 + k * 1024); } while (0)
; #define PG8_MMA(ai, bj, At, Bt) do { __builtin_amdgcn_s_setprio(1); _Pragma("unroll") for (int m = 0; m < 4; ++m) _Pragma("unroll") for (int n = 0; n < 2; ++n) _Pragma("unroll") for (int k = 0; k < 2; ++k) \
;         acc[ai][bj][m][n] = __builtin_amdgcn_mfma_f32_16x16x32_bf16(Bt[n][k], At[m][k], acc[ai][bj][m][n], 0, 0, 0); __builtin_amdgcn_s_setprio(0); } while (0)
; #define PG8_WAIT_V(n) asm volatile("s_waitcnt vmcnt(" #n ")" ::: "memory")
; #define PG8_WAIT_L(n) asm volatile("s_waitcnt lgkmcnt(" #n ")" ::: "memory")
; #define PG8_BAR __builtin_amdgcn_s_barrier()
; #define PG8_SCHED __builtin_amdgcn_sched_barrier(0)
; template <class Epi>
; DI void gemm_phase(LAS unsigned char* lds, const Gemm g, const StaticOrder& S, const Epi& E) {
;     ...
;             PG8_WAIT_V(6); PG8_BAR; PG8_MMA(1, 1, At, B1); PG8_BAR;
;             PG8_LDB(B0, 1, 0); PG8_SCHED; PG8_LDA(At, 1, 0); PG8_STAGE(PG8_SA(0, 1), a2 + hstep);
;             PG8_WAIT_L(8); PG8_BAR; PG8_WAIT_L(0); PG8_MMA(0, 0, At, B0); PG8_BAR; PG8_SCHED;
;             PG8_LDB(B1, 1, 1); PG8_STAGE(PG8_SB(1, 0), b3);
;             PG8_BAR; PG8_WAIT_L(0); PG8_MMA(0, 1, At, B1); PG8_BAR;
;             PG8_LDA(At, 1, 1); PG8_STAGE(PG8_SA(1, 0), a3);
;             PG8_BAR; PG8_WAIT_L(0); PG8_MMA(1, 0, At, B0); PG8_BAR; PG8_SCHED;
	v_mfma_f32_16x16x32_bf16 v[28:31], v[214:217], v[144:147], v[28:31]
	v_mfma_f32_16x16x32_bf16 v[24:27], v[234:237], v[144:147], v[24:27]
	v_mfma_f32_16x16x32_bf16 v[20:23], v[214:217], v[152:155], v[20:23]
	v_mfma_f32_16x16x32_bf16 v[16:19], v[234:237], v[152:155], v[16:19]
	v_mfma_f32_16x16x32_bf16 v[12:15], v[214:217], v[198:201], v[12:15]
	v_mfma_f32_16x16x32_bf16 v[8:11], v[234:237], v[198:201], v[8:11]
	v_mfma_f32_16x16x32_bf16 v[4:7], v[214:217], v[206:209], v[4:7]
	v_mfma_f32_16x16x32_bf16 v[0:3], v[234:237], v[206:209], v[0:3]
	v_mfma_f32_16x16x32_bf16 v[28:31], v[230:233], v[148:151], v[28:31]
	v_mfma_f32_16x16x32_bf16 v[24:27], v[238:241], v[148:151], v[24:27]
	v_mfma_f32_16x16x32_bf16 v[20:23], v[230:233], v[194:197], v[20:23]
	v_mfma_f32_16x16x32_bf16 v[16:19], v[238:241], v[194:197], v[16:19]
	v_mfma_f32_16x16x32_bf16 v[12:15], v[230:233], v[202:205], v[12:15]
	v_mfma_f32_16x16x32_bf16 v[8:11], v[238:241], v[202:205], v[8:11]
	v_mfma_f32_16x16x32_bf16 v[4:7], v[230:233], v[210:213], v[4:7]
	s_setprio 0
	v_mfma_f32_16x16x32_bf16 v[0:3], v[238:241], v[210:213], v[0:3]
	s_barrier
	ds_read_b128 v[128:131], v226 offset:32768
	ds_read_b128 v[132:135], v226 offset:33792
	ds_read_b128 v[136:139], v226 offset:34816
	ds_read_b128 v[140:143], v226 offset:35840
	ds_read_b128 v[144:147], v228 offset:32768
	ds_read_b128 v[148:151], v228 offset:33792
	ds_read_b128 v[152:155], v228 offset:34816
	ds_read_b128 v[194:197], v228 offset:35840
	ds_read_b128 v[198:201], v228 offset:36864
	ds_read_b128 v[202:205], v228 offset:37888
	ds_read_b128 v[206:209], v228 offset:38912
	ds_read_b128 v[210:213], v228 offset:39936
	s_add_i32 s47, 0, 0x18000
	s_add_u32 s24, s30, 0x80000
	s_addc_u32 s25, s31, 0
	s_mov_b32 m0, s40
	s_nop 0
	global_load_lds_dwordx4 v188, s[24:25]
	s_mov_b32 m0, s41
	s_nop 0
	global_load_lds_dwordx4 v186, s[24:25]
	s_waitcnt lgkmcnt(8)
	s_setprio 1
	s_barrier
	s_waitcnt lgkmcnt(0)
	v_mfma_f32_16x16x32_bf16 v[124:127], v[128:131], v[144:147], v[124:127]
	v_mfma_f32_16x16x32_bf16 v[120:123], v[136:139], v[144:147], v[120:123]
	v_mfma_f32_16x16x32_bf16 v[116:119], v[128:131], v[152:155], v[116:119]
	v_mfma_f32_16x16x32_bf16 v[112:115], v[136:139], v[152:155], v[112:115]
	v_mfma_f32_16x16x32_bf16 v[108:111], v[128:131], v[198:201], v[108:111]
	v_mfma_f32_16x16x32_bf16 v[104:107], v[136:139], v[198:201], v[104:107]
	v_mfma_f32_16x16x32_bf16 v[100:103], v[128:131], v[206:209], v[100:103]
	v_mfma_f32_16x16x32_bf16 v[96:99], v[136:139], v[206:209], v[96:99]
	v_mfma_f32_16x16x32_bf16 v[124:127], v[132:135], v[148:151], v[124:127]
	v_mfma_f32_16x16x32_bf16 v[120:123], v[140:143], v[148:151], v[120:123]
	v_mfma_f32_16x16x32_bf16 v[116:119], v[132:135], v[194:197], v[116:119]
	v_mfma_f32_16x16x32_bf16 v[112:115], v[140:143], v[194:197], v[112:115]
	v_mfma_f32_16x16x32_bf16 v[108:111], v[132:135], v[202:205], v[108:111]
	v_mfma_f32_16x16x32_bf16 v[104:107], v[140:143], v[202:205], v[104:107]
	v_mfma_f32_16x16x32_bf16 v[100:103], v[132:135], v[210:213], v[100:103]
	s_setprio 0
	v_mfma_f32_16x16x32_bf16 v[96:99], v[140:143], v[210:213], v[96:99]
	s_barrier
	ds_read_b128 v[214:217], v226 offset:49152
	ds_read_b128 v[230:233], v226 offset:50176
	ds_read_b128 v[234:237], v226 offset:51200
	ds_read_b128 v[238:241], v226 offset:52224
	s_add_i32 s30, 0, 0x1c000
	s_add_i32 s24, s47, s37
	s_add_i32 m0, s24, 0xffffff80
	s_nop 0
	global_load_lds_dwordx4 v188, s[28:29] offset:128
	s_add_i32 m0, s24, 0x1f80
	s_nop 0
	global_load_lds_dwordx4 v186, s[28:29] offset:128
	s_waitcnt lgkmcnt(0)
	s_setprio 1
	s_barrier
	v_mfma_f32_16x16x32_bf16 v[60:63], v[214:217], v[144:147], v[60:63]
	v_mfma_f32_16x16x32_bf16 v[56:59], v[234:237], v[144:147], v[56:59]
	v_mfma_f32_16x16x32_bf16 v[52:55], v[214:217], v[152:155], v[52:55]
	v_mfma_f32_16x16x32_bf16 v[48:51], v[234:237], v[152:155], v[48:51]
	v_mfma_f32_16x16x32_bf16 v[44:47], v[214:217], v[198:201], v[44:47]
	v_mfma_f32_16x16x32_bf16 v[40:43], v[234:237], v[198:201], v[40:43]
	v_mfma_f32_16x16x32_bf16 v[36:39], v[214:217], v[206:209], v[36:39]
	v_mfma_f32_16x16x32_bf16 v[32:35], v[234:237], v[206:209], v[32:35]
	v_mfma_f32_16x16x32_bf16 v[60:63], v[230:233], v[148:151], v[60:63]
	v_mfma_f32_16x16x32_bf16 v[56:59], v[238:241], v[148:151], v[56:59]
	v_mfma_f32_16x16x32_bf16 v[52:55], v[230:233], v[194:197], v[52:55]
	v_mfma_f32_16x16x32_bf16 v[48:51], v[238:241], v[194:197], v[48:51]
	v_mfma_f32_16x16x32_bf16 v[44:47], v[230:233], v[202:205], v[44:47]
	v_mfma_f32_16x16x32_bf16 v[40:43], v[238:241], v[202:205], v[40:43]
	v_mfma_f32_16x16x32_bf16 v[36:39], v[230:233], v[210:213], v[36:39]
	s_setprio 0
	v_mfma_f32_16x16x32_bf16 v[32:35], v[238:241], v[210:213], v[32:35]
	s_barrier
	ds_read_b128 v[144:147], v228 offset:49152
	ds_read_b128 v[148:151], v228 offset:50176
	ds_read_b128 v[152:155], v228 offset:51200
	ds_read_b128 v[194:197], v228 offset:52224
	ds_read_b128 v[198:201], v228 offset:53248
	ds_read_b128 v[202:205], v228 offset:54272
	ds_read_b128 v[206:209], v228 offset:55296
	ds_read_b128 v[210:213], v228 offset:56320
	s_add_i32 m0, s42, 0xffffff80
	s_nop 0
	global_load_lds_dwordx4 v188, s[100:101] offset:128
	s_add_i32 m0, s43, 0xffffff80
	s_nop 0
	global_load_lds_dwordx4 v186, s[100:101] offset:128
	s_waitcnt lgkmcnt(0)
	s_setprio 1
	s_barrier
; #define PG8_BAR __builtin_amdgcn_s_barrier()
; template <class Epi>
; DI void gemm_phase(LAS unsigned char* lds, const Gemm g, const StaticOrder& S, const Epi& E) {
;     ...
;             PG8_BAR; PG8_WAIT_L(0); PG8_MMA(1, 0, At, B0); PG8_BAR; PG8_SCHED;
;             PG8_STAGE(PG8_SB(1, 1), b3 + hstep);
;             PG8_WAIT_V(6); PG8_BAR; PG8_MMA(1, 1, At, B1); PG8_BAR;
;         }
;         E(acc, cur, wr, wc, fr, fq);
;     template <bool LN, int BJ, int LO, int HI> DI void batch(const f32x4 (&acc)[2][2][4][2], unsigned row0, unsigned col0, const f32x4 (&gv)[2], const f32x4 (&bv)[2]) const {
;         f32x4 r[HI - LO]; float mean[(HI - LO) / 2], rstd[(HI - LO) / 2];
; #pragma unroll
;         for (int i = LO; i < HI; ++i) { const int ai = i >> 3, m = (i >> 1) & 3, n = i & 1; const unsigned row = row0 + ai * HALF + m * 16;
;             if (n == 0) { mean[(i - LO) >> 1] = 0.f; rstd[(i - LO) >> 1] = 1.f;
;                 if (LN) { const float2 st = *(const float2*)(stats + row * 2u); mean[(i - LO) >> 1] = st.x; rstd[(i - LO) >> 1] = st.y; } }
;             r[i - LO] = *(const f32x4*)(src + (row * (unsigned)DM + col0 + BJ * HALF + n * 16)); }
; #pragma unroll
;         for (int i = LO; i < HI; ++i) { const int ai = i >> 3, m = (i >> 1) & 3, n = i & 1; const unsigned row = row0 + ai * HALF + m * 16;
;             *(f32x4*)(Y + (row * (unsigned)DM + col0 + BJ * HALF + n * 16)) = acc[ai][BJ][m][n] + ((r[i - LO] - mean[(i - LO) >> 1]) * rstd[(i - LO) >> 1]) * gv[n] + bv[n]; }
;         __builtin_amdgcn_sched_barrier(0);
;     }
;     template <bool LN, int BJ> DI void load_gb(unsigned col0, f32x4 (&gv)[2], f32x4 (&bv)[2]) const {
; #pragma unroll
;         for (int n = 0; n < 2; ++n) {
;             if (LN) { gv[n] = *(const f32x4*)(gam + col0 + BJ * HALF + n * 16) * ALPHA; bv[n] = *(const f32x4*)(bet + col0 + BJ * HALF + n * 16) * ALPHA; }
;             else { gv[n] = (f32x4){ALPHA, ALPHA, ALPHA, ALPHA}; bv[n] = (f32x4){0.f, 0.f, 0.f, 0.f}; }
;         }
;     }
;     template <bool LN> DI void run(const f32x4 (&acc)[2][2][4][2], const Unit& u, int wr, int wc, int fr, int fq) const {
;         const unsigned row0 = u.pm * BM + wr * 64 + fr, col0 = u.pn * BM + wc * 32 + 4 * fq;
;         f32x4 gv[2], bv[2];
;         load_gb<LN, 0>(col0, gv, bv);
;         batch<LN, 0, 0, 4>(acc, row0, col0, gv, bv);
;         batch<LN, 0, 4, 8>(acc, row0, col0, gv, bv);
	v_mfma_f32_16x16x32_bf16 v[92:95], v[128:131], v[144:147], v[92:95]
	v_mfma_f32_16x16x32_bf16 v[88:91], v[136:139], v[144:147], v[88:91]
	v_mfma_f32_16x16x32_bf16 v[84:87], v[128:131], v[152:155], v[84:87]
	v_mfma_f32_16x16x32_bf16 v[80:83], v[136:139], v[152:155], v[80:83]
	v_mfma_f32_16x16x32_bf16 v[76:79], v[128:131], v[198:201], v[76:79]
	v_mfma_f32_16x16x32_bf16 v[72:75], v[136:139], v[198:201], v[72:75]
	v_mfma_f32_16x16x32_bf16 v[68:71], v[128:131], v[206:209], v[68:71]
	v_mfma_f32_16x16x32_bf16 v[64:67], v[136:139], v[206:209], v[64:67]
	v_mfma_f32_16x16x32_bf16 v[92:95], v[132:135], v[148:151], v[92:95]
	v_mfma_f32_16x16x32_bf16 v[88:91], v[140:143], v[148:151], v[88:91]
	v_mfma_f32_16x16x32_bf16 v[84:87], v[132:135], v[194:197], v[84:87]
	v_mfma_f32_16x16x32_bf16 v[80:83], v[140:143], v[194:197], v[80:83]
	v_mfma_f32_16x16x32_bf16 v[76:79], v[132:135], v[202:205], v[76:79]
	v_mfma_f32_16x16x32_bf16 v[72:75], v[140:143], v[202:205], v[72:75]
	v_mfma_f32_16x16x32_bf16 v[68:71], v[132:135], v[210:213], v[68:71]
	s_setprio 0
	v_mfma_f32_16x16x32_bf16 v[64:67], v[140:143], v[210:213], v[64:67]
	s_barrier
	s_add_u32 s24, s28, 0x80080
	s_addc_u32 s25, s29, 0
	s_add_i32 s28, s30, s37
	s_mov_b32 m0, s28
	s_nop 0
	global_load_lds_dwordx4 v188, s[24:25]
	s_add_i32 m0, s28, 0x2000
	s_nop 0
	global_load_lds_dwordx4 v186, s[24:25]
	s_waitcnt vmcnt(6)
	s_setprio 1
	s_barrier
	v_mfma_f32_16x16x32_bf16 v[28:31], v[214:217], v[144:147], v[28:31]
	v_mfma_f32_16x16x32_bf16 v[24:27], v[234:237], v[144:147], v[24:27]
	v_mfma_f32_16x16x32_bf16 v[20:23], v[214:217], v[152:155], v[20:23]
	v_mfma_f32_16x16x32_bf16 v[16:19], v[234:237], v[152:155], v[16:19]
	v_mfma_f32_16x16x32_bf16 v[12:15], v[214:217], v[198:201], v[12:15]
	v_mfma_f32_16x16x32_bf16 v[8:11], v[234:237], v[198:201], v[8:11]
	v_mfma_f32_16x16x32_bf16 v[4:7], v[214:217], v[206:209], v[4:7]
	v_mfma_f32_16x16x32_bf16 v[0:3], v[234:237], v[206:209], v[0:3]
	v_mfma_f32_16x16x32_bf16 v[28:31], v[230:233], v[148:151], v[28:31]
	s_add_i32 s46, s46, 2
	v_mfma_f32_16x16x32_bf16 v[24:27], v[238:241], v[148:151], v[24:27]
	s_add_u32 s33, s33, 0x100
	v_mfma_f32_16x16x32_bf16 v[20:23], v[230:233], v[194:197], v[20:23]
	s_addc_u32 s45, s45, 0
	v_mfma_f32_16x16x32_bf16 v[16:19], v[238:241], v[194:197], v[16:19]
	s_cmp_gt_u32 s46, 29
	v_mfma_f32_16x16x32_bf16 v[12:15], v[230:233], v[202:205], v[12:15]
	s_mov_b64 s[24:25], s[26:27]
	v_mfma_f32_16x16x32_bf16 v[8:11], v[238:241], v[202:205], v[8:11]
	v_mfma_f32_16x16x32_bf16 v[4:7], v[230:233], v[210:213], v[4:7]
	s_setprio 0
	v_mfma_f32_16x16x32_bf16 v[0:3], v[238:241], v[210:213], v[0:3]
	s_barrier
	s_cbranch_scc0 .LBB0_320
	v_lshl_add_u32 v206, s3, 8, v225
	v_lshl_or_b32 v158, s2, 8, v227
	v_lshlrev_b32_e32 v232, 11, v206
	s_andn2_b64 vcc, exec, s[14:15]
	v_or_b32_e32 v231, 16, v158
	v_add_u32_e32 v194, v232, v158
	v_or_b32_e32 v230, 0x80, v158
	v_or_b32_e32 v229, 0x90, v158
	s_cbranch_vccnz .LBB0_323
	v_lshlrev_b64 v[132:133], 2, v[158:159]
	v_lshl_add_u64 v[140:141], s[16:17], 0, v[132:133]
	global_load_dwordx4 v[128:131], v[140:141], off
	v_lshl_add_u64 v[142:143], s[18:19], 0, v[132:133]
	v_readlane_b32 s2, v253, 8
	v_mov_b32_e32 v195, v159
	v_lshlrev_b32_e32 v136, 1, v206
	v_mov_b32_e32 v137, v159
	v_readlane_b32 s3, v253, 9
	v_lshlrev_b64 v[212:213], 2, v[194:195]
	v_add_u32_e32 v146, v232, v231
	v_lshl_add_u64 v[144:145], v[136:137], 2, s[2:3]
	v_lshl_add_u64 v[136:137], s[88:89], 0, v[212:213]
	v_mov_b32_e32 v147, v159
	v_lshl_add_u64 v[146:147], v[146:147], 2, s[88:89]
	v_or_b32_e32 v195, 16, v206
	v_mov_b32_e32 v201, v159
	v_mov_b32_e32 v209, v159
	v_lshl_add_u64 v[212:213], s[90:91], 0, v[212:213]
	s_waitcnt vmcnt(0)
	v_pk_mul_f32 v[152:153], v[130:131], s[78:79] op_sel_hi:[1,0]
	v_pk_mul_f32 v[154:155], v[128:129], s[78:79] op_sel_hi:[1,0]
	global_load_dwordx4 v[132:135], v[142:143], off
	global_load_dwordx4 v[128:131], v[140:141], off offset:64
	global_load_dwordx2 v[204:205], v[144:145], off
	global_load_dwordx4 v[196:199], v[146:147], off
	v_lshlrev_b32_e32 v146, 1, v195
	global_load_dwordx4 v[136:139], v[136:137], off
	v_lshlrev_b32_e32 v195, 11, v195
	v_mov_b32_e32 v147, v159
	v_add_u32_e32 v200, v195, v158
	v_lshl_add_u64 v[146:147], v[146:147], 2, s[2:3]
	v_lshl_add_u64 v[200:201], v[200:201], 2, s[88:89]
	global_load_dwordx2 v[214:215], v[146:147], off
	v_add_u32_e32 v208, v195, v231
	global_load_dwordx4 v[200:203], v[200:201], off
	v_lshl_add_u64 v[208:209], v[208:209], 2, s[88:89]
	global_load_dwordx4 v[208:211], v[208:209], off
	s_waitcnt vmcnt(0)
	v_pk_mul_f32 v[148:149], v[130:131], s[78:79] op_sel_hi:[1,0]
	v_pk_mul_f32 v[150:151], v[128:129], s[78:79] op_sel_hi:[1,0]
	global_load_dwordx4 v[128:131], v[142:143], off offset:64
	v_sub_f32_e32 v137, v137, v204
	v_sub_f32_e32 v136, v136, v204
	v_sub_f32_e32 v139, v139, v204
	v_sub_f32_e32 v138, v138, v204
	v_pk_mul_f32 v[138:139], v[204:205], v[138:139] op_sel:[1,0]
	v_pk_mul_f32 v[136:137], v[204:205], v[136:137] op_sel:[1,0]
	v_pk_fma_f32 v[138:139], v[152:153], v[138:139], v[126:127]
	v_pk_fma_f32 v[136:137], v[154:155], v[136:137], v[124:125]
	v_pk_fma_f32 v[138:139], v[134:135], s[78:79], v[138:139] op_sel_hi:[1,0,1]
	v_pk_fma_f32 v[136:137], v[132:133], s[78:79], v[136:137] op_sel_hi:[1,0,1]
	global_store_dwordx4 v[212:213], v[136:139], off
	s_nop 1
	v_sub_f32_e32 v137, v197, v204
	v_sub_f32_e32 v136, v196, v204
	v_sub_f32_e32 v139, v199, v204
	v_sub_f32_e32 v138, v198, v204
	v_pk_mul_f32 v[138:139], v[204:205], v[138:139] op_sel:[1,0]
	v_pk_mul_f32 v[136:137], v[204:205], v[136:137] op_sel:[1,0]
	v_pk_fma_f32 v[138:139], v[148:149], v[138:139], v[122:123]
	v_pk_fma_f32 v[136:137], v[150:151], v[136:137], v[120:121]
	v_or_b32_e32 v196, 16, v194
	v_mov_b32_e32 v197, v159
	v_lshl_add_u64 v[196:197], v[196:197], 2, s[90:91]
	s_waitcnt vmcnt(0)
;     template <bool LN, int BJ, int LO, int HI> DI void batch(const f32x4 (&acc)[2][2][4][2], unsigned row0, unsigned col0, const f32x4 (&gv)[2], const f32x4 (&bv)[2]) const {
;         f32x4 r[HI - LO]; float mean[(HI - LO) / 2], rstd[(HI - LO) / 2];
; #pragma unroll
;         for (int i = LO; i < HI; ++i) { const int ai = i >> 3, m = (i >> 1) & 3, n = i & 1; const unsigned row = row0 + ai * HALF + m * 16;
;             if (n == 0) { mean[(i - LO) >> 1] = 0.f; rstd[(i - LO) >> 1] = 1.f;
;                 if (LN) { const float2 st = *(const float2*)(stats + row * 2u); mean[(i - LO) >> 1] = st.x; rstd[(i - LO) >> 1] = st.y; } }
;             r[i - LO] = *(const f32x4*)(src + (row * (unsigned)DM + col0 + BJ * HALF + n * 16)); }
; #pragma unroll
;         for (int i = LO; i < HI; ++i) { const int ai = i >> 3, m = (i >> 1) & 3, n = i & 1; const unsigned row = row0 + ai * HALF + m * 16;
;             *(f32x4*)(Y + (row * (unsigned)DM + col0 + BJ * HALF + n * 16)) = acc[ai][BJ][m][n] + ((r[i - LO] - mean[(i - LO) >> 1]) * rstd[(i - LO) >> 1]) * gv[n] + bv[n]; }
	v_pk_fma_f32 v[138:139], v[130:131], s[78:79], v[138:139] op_sel_hi:[1,0,1]
	v_pk_fma_f32 v[136:137], v[128:129], s[78:79], v[136:137] op_sel_hi:[1,0,1]
	global_store_dwordx4 v[196:197], v[136:139], off
	v_add_u32_e32 v196, 0x8000, v194
	v_mov_b32_e32 v197, v159
	v_sub_f32_e32 v137, v201, v214
	v_sub_f32_e32 v136, v200, v214
	v_sub_f32_e32 v139, v203, v214
	v_sub_f32_e32 v138, v202, v214
	v_pk_mul_f32 v[138:139], v[214:215], v[138:139] op_sel:[1,0]
	v_pk_mul_f32 v[136:137], v[214:215], v[136:137] op_sel:[1,0]
	v_pk_fma_f32 v[138:139], v[152:153], v[138:139], v[118:119]
	v_pk_fma_f32 v[136:137], v[154:155], v[136:137], v[116:117]
	v_pk_fma_f32 v[138:139], v[134:135], s[78:79], v[138:139] op_sel_hi:[1,0,1]
	v_pk_fma_f32 v[136:137], v[132:133], s[78:79], v[136:137] op_sel_hi:[1,0,1]
	v_lshl_add_u64 v[196:197], v[196:197], 2, s[90:91]
	global_store_dwordx4 v[196:197], v[136:139], off
	v_add_u32_e32 v196, 0x8010, v194
	v_mov_b32_e32 v197, v159
	v_sub_f32_e32 v137, v209, v214
	v_sub_f32_e32 v136, v208, v214
	v_sub_f32_e32 v139, v211, v214
	v_sub_f32_e32 v138, v210, v214
	v_pk_mul_f32 v[138:139], v[214:215], v[138:139] op_sel:[1,0]
	v_pk_mul_f32 v[136:137], v[214:215], v[136:137] op_sel:[1,0]
	v_pk_fma_f32 v[138:139], v[148:149], v[138:139], v[114:115]
	v_pk_fma_f32 v[136:137], v[150:151], v[136:137], v[112:113]
	v_pk_fma_f32 v[138:139], v[130:131], s[78:79], v[138:139] op_sel_hi:[1,0,1]
	v_pk_fma_f32 v[136:137], v[128:129], s[78:79], v[136:137] op_sel_hi:[1,0,1]
	v_lshl_add_u64 v[196:197], v[196:197], 2, s[90:91]
	global_store_dwordx4 v[196:197], v[136:139], off
	s_nop 1
	v_or_b32_e32 v138, 32, v206
	v_lshlrev_b32_e32 v136, 1, v138
	v_mov_b32_e32 v137, v159
	v_lshlrev_b32_e32 v236, 11, v138
	v_lshl_add_u64 v[200:201], v[136:137], 2, s[2:3]
	v_add_u32_e32 v136, v236, v158
	v_lshl_add_u64 v[136:137], v[136:137], 2, s[88:89]
	global_load_dwordx2 v[204:205], v[200:201], off
	v_add_u32_e32 v196, v236, v231
	global_load_dwordx4 v[136:139], v[136:137], off
	v_mov_b32_e32 v197, v159
	v_lshl_add_u64 v[196:197], v[196:197], 2, s[88:89]
	global_load_dwordx4 v[196:199], v[196:197], off
	v_or_b32_e32 v207, 48, v206
	v_lshlrev_b32_e32 v235, 11, v207
	v_lshlrev_b32_e32 v202, 1, v207
	v_mov_b32_e32 v203, v159
	v_add_u32_e32 v208, v235, v158
	v_mov_b32_e32 v209, v159
	v_lshl_add_u64 v[202:203], v[202:203], 2, s[2:3]
	v_lshl_add_u64 v[208:209], v[208:209], 2, s[88:89]
	global_load_dwordx2 v[216:217], v[202:203], off
	v_add_u32_e32 v212, v235, v231
	global_load_dwordx4 v[208:211], v[208:209], off
	v_mov_b32_e32 v213, v159
	v_lshl_add_u64 v[212:213], v[212:213], 2, s[88:89]
	global_load_dwordx4 v[212:215], v[212:213], off
	v_add_u32_e32 v218, 0x10000, v194
	v_mov_b32_e32 v219, v159
	v_lshl_add_u64 v[218:219], v[218:219], 2, s[90:91]
	s_waitcnt vmcnt(0)
	v_sub_f32_e32 v137, v137, v204
	v_sub_f32_e32 v136, v136, v204
	v_sub_f32_e32 v139, v139, v204
	v_sub_f32_e32 v138, v138, v204
	v_pk_mul_f32 v[138:139], v[204:205], v[138:139] op_sel:[1,0]
	v_pk_mul_f32 v[136:137], v[204:205], v[136:137] op_sel:[1,0]
	v_pk_fma_f32 v[138:139], v[152:153], v[138:139], v[110:111]
	v_pk_fma_f32 v[136:137], v[154:155], v[136:137], v[108:109]
	v_pk_fma_f32 v[138:139], v[134:135], s[78:79], v[138:139] op_sel_hi:[1,0,1]
	v_pk_fma_f32 v[136:137], v[132:133], s[78:79], v[136:137] op_sel_hi:[1,0,1]
	global_store_dwordx4 v[218:219], v[136:139], off
	s_nop 1
	v_sub_f32_e32 v137, v197, v204
	v_sub_f32_e32 v136, v196, v204
	v_sub_f32_e32 v139, v199, v204
	v_sub_f32_e32 v138, v198, v204
	v_pk_mul_f32 v[138:139], v[204:205], v[138:139] op_sel:[1,0]
	v_pk_mul_f32 v[136:137], v[204:205], v[136:137] op_sel:[1,0]
	v_pk_fma_f32 v[138:139], v[148:149], v[138:139], v[106:107]
	v_pk_fma_f32 v[136:137], v[150:151], v[136:137], v[104:105]
	v_add_u32_e32 v196, 0x10010, v194
	v_mov_b32_e32 v197, v159
	v_pk_fma_f32 v[138:139], v[130:131], s[78:79], v[138:139] op_sel_hi:[1,0,1]
	v_pk_fma_f32 v[136:137], v[128:129], s[78:79], v[136:137] op_sel_hi:[1,0,1]
	v_lshl_add_u64 v[196:197], v[196:197], 2, s[90:91]
	global_store_dwordx4 v[196:197], v[136:139], off
	v_add_u32_e32 v196, 0x18000, v194
	v_mov_b32_e32 v197, v159
	v_sub_f32_e32 v137, v209, v216
	v_sub_f32_e32 v136, v208, v216
	v_sub_f32_e32 v139, v211, v216
	v_sub_f32_e32 v138, v210, v216
	v_pk_mul_f32 v[138:139], v[216:217], v[138:139] op_sel:[1,0]
	v_pk_mul_f32 v[136:137], v[216:217], v[136:137] op_sel:[1,0]
	v_pk_fma_f32 v[138:139], v[152:153], v[138:139], v[102:103]
	v_pk_fma_f32 v[136:137], v[154:155], v[136:137], v[100:101]
	v_pk_fma_f32 v[138:139], v[134:135], s[78:79], v[138:139] op_sel_hi:[1,0,1]
	v_pk_fma_f32 v[136:137], v[132:133], s[78:79], v[136:137] op_sel_hi:[1,0,1]
	v_lshl_add_u64 v[196:197], v[196:197], 2, s[90:91]
	global_store_dwordx4 v[196:197], v[136:139], off
	v_add_u32_e32 v196, 0x18010, v194
	v_mov_b32_e32 v197, v159
	v_sub_f32_e32 v137, v213, v216
	v_sub_f32_e32 v136, v212, v216
	v_sub_f32_e32 v139, v215, v216
	v_sub_f32_e32 v138, v214, v216
	v_pk_mul_f32 v[138:139], v[216:217], v[138:139] op_sel:[1,0]
	v_pk_mul_f32 v[136:137], v[216:217], v[136:137] op_sel:[1,0]
	v_pk_fma_f32 v[138:139], v[148:149], v[138:139], v[98:99]
	v_pk_fma_f32 v[136:137], v[150:151], v[136:137], v[96:97]
	v_pk_fma_f32 v[138:139], v[130:131], s[78:79], v[138:139] op_sel_hi:[1,0,1]
	v_pk_fma_f32 v[136:137], v[128:129], s[78:79], v[136:137] op_sel_hi:[1,0,1]
	v_lshl_add_u64 v[196:197], v[196:197], 2, s[90:91]
	global_store_dwordx4 v[196:197], v[136:139], off
	s_nop 1
	v_add_u32_e32 v138, 0x80, v206
	v_lshlrev_b32_e32 v136, 1, v138
	v_mov_b32_e32 v137, v159
	v_lshlrev_b32_e32 v233, 11, v138
	v_lshl_add_u64 v[196:197], v[136:137], 2, s[2:3]
	v_add_u32_e32 v136, v233, v158
	v_lshl_add_u64 v[136:137], v[136:137], 2, s[88:89]
	global_load_dwordx2 v[204:205], v[196:197], off
	v_add_u32_e32 v198, v233, v231
	global_load_dwordx4 v[136:139], v[136:137], off
	v_mov_b32_e32 v199, v159
	v_add_u32_e32 v207, 0x90, v206
	v_lshl_add_u64 v[198:199], v[198:199], 2, s[88:89]
	v_lshlrev_b32_e32 v234, 11, v207
	global_load_dwordx4 v[208:211], v[198:199], off
	v_add_u32_e32 v212, v234, v158
	v_mov_b32_e32 v213, v159
	v_lshl_add_u64 v[212:213], v[212:213], 2, s[88:89]
	global_load_dwordx4 v[212:215], v[212:213], off
	v_lshlrev_b32_e32 v198, 1, v207
	v_mov_b32_e32 v199, v159
	v_lshl_add_u64 v[198:199], v[198:199], 2, s[2:3]
	global_load_dwordx2 v[238:239], v[198:199], off
	v_add_u32_e32 v216, v234, v231
	v_mov_b32_e32 v217, v159
	v_lshl_add_u64 v[216:217], v[216:217], 2, s[88:89]
	global_load_dwordx4 v[216:219], v[216:217], off
	v_add_u32_e32 v240, 0x40000, v194
	v_mov_b32_e32 v241, v159
	v_lshl_add_u64 v[240:241], v[240:241], 2, s[90:91]
	s_waitcnt vmcnt(0)
;     template <bool LN, int BJ, int LO, int HI> DI void batch(const f32x4 (&acc)[2][2][4][2], unsigned row0, unsigned col0, const f32x4 (&gv)[2], const f32x4 (&bv)[2]) const {
;         f32x4 r[HI - LO]; float mean[(HI - LO) / 2], rstd[(HI - LO) / 2];
; #pragma unroll
;         for (int i = LO; i < HI; ++i) { const int ai = i >> 3, m = (i >> 1) & 3, n = i & 1; const unsigned row = row0 + ai * HALF + m * 16;
;             if (n == 0) { mean[(i - LO) >> 1] = 0.f; rstd[(i - LO) >> 1] = 1.f;
;                 if (LN) { const float2 st = *(const float2*)(stats + row * 2u); mean[(i - LO) >> 1] = st.x; rstd[(i - LO) >> 1] = st.y; } }
;             r[i - LO] = *(const f32x4*)(src + (row * (unsigned)DM + col0 + BJ * HALF + n * 16)); }
; #pragma unroll
;         for (int i = LO; i < HI; ++i) { const int ai = i >> 3, m = (i >> 1) & 3, n = i & 1; const unsigned row = row0 + ai * HALF + m * 16;
;             *(f32x4*)(Y + (row * (unsigned)DM + col0 + BJ * HALF + n * 16)) = acc[ai][BJ][m][n] + ((r[i - LO] - mean[(i - LO) >> 1]) * rstd[(i - LO) >> 1]) * gv[n] + bv[n]; }
;     template <bool LN> DI void run(const f32x4 (&acc)[2][2][4][2], const Unit& u, int wr, int wc, int fr, int fq) const {
;     ...
;         load_gb<LN, 1>(col0, gv, bv);
	v_sub_f32_e32 v137, v137, v204
	v_sub_f32_e32 v136, v136, v204
	v_sub_f32_e32 v139, v139, v204
	v_sub_f32_e32 v138, v138, v204
	v_pk_mul_f32 v[138:139], v[204:205], v[138:139] op_sel:[1,0]
	v_pk_mul_f32 v[136:137], v[204:205], v[136:137] op_sel:[1,0]
	v_pk_fma_f32 v[138:139], v[152:153], v[138:139], v[94:95]
	v_pk_fma_f32 v[136:137], v[154:155], v[136:137], v[92:93]
	v_pk_fma_f32 v[138:139], v[134:135], s[78:79], v[138:139] op_sel_hi:[1,0,1]
	v_pk_fma_f32 v[136:137], v[132:133], s[78:79], v[136:137] op_sel_hi:[1,0,1]
	global_store_dwordx4 v[240:241], v[136:139], off
	s_nop 1
	v_sub_f32_e32 v137, v209, v204
	v_sub_f32_e32 v136, v208, v204
	v_sub_f32_e32 v139, v211, v204
	v_sub_f32_e32 v138, v210, v204
	v_pk_mul_f32 v[138:139], v[204:205], v[138:139] op_sel:[1,0]
	v_pk_mul_f32 v[136:137], v[204:205], v[136:137] op_sel:[1,0]
	v_pk_fma_f32 v[138:139], v[148:149], v[138:139], v[90:91]
	v_pk_fma_f32 v[136:137], v[150:151], v[136:137], v[88:89]
	v_add_u32_e32 v204, 0x40010, v194
	v_mov_b32_e32 v205, v159
	v_pk_fma_f32 v[138:139], v[130:131], s[78:79], v[138:139] op_sel_hi:[1,0,1]
	v_pk_fma_f32 v[136:137], v[128:129], s[78:79], v[136:137] op_sel_hi:[1,0,1]
	v_lshl_add_u64 v[204:205], v[204:205], 2, s[90:91]
	global_store_dwordx4 v[204:205], v[136:139], off
	v_add_u32_e32 v204, 0x48000, v194
	v_mov_b32_e32 v205, v159
	v_sub_f32_e32 v137, v213, v238
	v_sub_f32_e32 v136, v212, v238
	v_sub_f32_e32 v139, v215, v238
	v_sub_f32_e32 v138, v214, v238
	v_pk_mul_f32 v[138:139], v[238:239], v[138:139] op_sel:[1,0]
	v_pk_mul_f32 v[136:137], v[238:239], v[136:137] op_sel:[1,0]
	v_pk_fma_f32 v[138:139], v[152:153], v[138:139], v[86:87]
	v_pk_fma_f32 v[136:137], v[154:155], v[136:137], v[84:85]
	v_pk_fma_f32 v[138:139], v[134:135], s[78:79], v[138:139] op_sel_hi:[1,0,1]
	v_pk_fma_f32 v[136:137], v[132:133], s[78:79], v[136:137] op_sel_hi:[1,0,1]
	v_lshl_add_u64 v[204:205], v[204:205], 2, s[90:91]
	global_store_dwordx4 v[204:205], v[136:139], off
	v_add_u32_e32 v204, 0x48010, v194
	v_mov_b32_e32 v205, v159
	v_sub_f32_e32 v137, v217, v238
	v_sub_f32_e32 v136, v216, v238
	v_sub_f32_e32 v139, v219, v238
	v_sub_f32_e32 v138, v218, v238
	v_pk_mul_f32 v[138:139], v[238:239], v[138:139] op_sel:[1,0]
	v_pk_mul_f32 v[136:137], v[238:239], v[136:137] op_sel:[1,0]
	v_pk_fma_f32 v[138:139], v[148:149], v[138:139], v[82:83]
	v_pk_fma_f32 v[136:137], v[150:151], v[136:137], v[80:81]
	v_pk_fma_f32 v[138:139], v[130:131], s[78:79], v[138:139] op_sel_hi:[1,0,1]
	v_pk_fma_f32 v[136:137], v[128:129], s[78:79], v[136:137] op_sel_hi:[1,0,1]
	v_lshl_add_u64 v[204:205], v[204:205], 2, s[90:91]
	global_store_dwordx4 v[204:205], v[136:139], off
	s_nop 1
	v_add_u32_e32 v138, 0xa0, v206
	v_lshlrev_b32_e32 v136, 1, v138
	v_mov_b32_e32 v137, v159
	v_lshlrev_b32_e32 v237, 11, v138
	v_lshl_add_u64 v[204:205], v[136:137], 2, s[2:3]
	v_add_u32_e32 v136, v237, v158
	v_lshl_add_u64 v[136:137], v[136:137], 2, s[88:89]
	global_load_dwordx2 v[240:241], v[204:205], off
	v_add_u32_e32 v208, v237, v231
	global_load_dwordx4 v[136:139], v[136:137], off
	v_mov_b32_e32 v209, v159
	v_lshl_add_u64 v[208:209], v[208:209], 2, s[88:89]
	global_load_dwordx4 v[212:215], v[208:209], off
	v_add_u32_e32 v208, 0xb0, v206
	v_lshlrev_b32_e32 v206, 1, v208
	v_mov_b32_e32 v207, v159
	v_lshlrev_b32_e32 v238, 11, v208
	v_lshl_add_u64 v[210:211], v[206:207], 2, s[2:3]
	v_add_u32_e32 v206, v238, v158
	v_lshl_add_u64 v[206:207], v[206:207], 2, s[88:89]
	global_load_dwordx2 v[242:243], v[210:211], off
	v_add_u32_e32 v216, v238, v231
	global_load_dwordx4 v[206:209], v[206:207], off
	v_mov_b32_e32 v217, v159
	v_lshl_add_u64 v[216:217], v[216:217], 2, s[88:89]
	global_load_dwordx4 v[216:219], v[216:217], off
	v_add_u32_e32 v244, 0x50000, v194
	v_mov_b32_e32 v245, v159
	v_lshl_add_u64 v[244:245], v[244:245], 2, s[90:91]
	s_waitcnt vmcnt(0)
	v_sub_f32_e32 v137, v137, v240
	v_sub_f32_e32 v136, v136, v240
	v_sub_f32_e32 v139, v139, v240
	v_sub_f32_e32 v138, v138, v240
	v_pk_mul_f32 v[138:139], v[240:241], v[138:139] op_sel:[1,0]
	v_pk_mul_f32 v[136:137], v[240:241], v[136:137] op_sel:[1,0]
	v_pk_fma_f32 v[138:139], v[152:153], v[138:139], v[78:79]
	v_pk_fma_f32 v[136:137], v[154:155], v[136:137], v[76:77]
	v_pk_fma_f32 v[138:139], v[134:135], s[78:79], v[138:139] op_sel_hi:[1,0,1]
	v_pk_fma_f32 v[136:137], v[132:133], s[78:79], v[136:137] op_sel_hi:[1,0,1]
	global_store_dwordx4 v[244:245], v[136:139], off
	s_nop 1
	v_sub_f32_e32 v137, v213, v240
	v_sub_f32_e32 v136, v212, v240
	v_sub_f32_e32 v139, v215, v240
	v_sub_f32_e32 v138, v214, v240
	v_pk_mul_f32 v[138:139], v[240:241], v[138:139] op_sel:[1,0]
	v_pk_mul_f32 v[136:137], v[240:241], v[136:137] op_sel:[1,0]
	v_pk_fma_f32 v[138:139], v[148:149], v[138:139], v[74:75]
	v_pk_fma_f32 v[136:137], v[150:151], v[136:137], v[72:73]
	v_add_u32_e32 v212, 0x50010, v194
	v_mov_b32_e32 v213, v159
	v_pk_fma_f32 v[138:139], v[130:131], s[78:79], v[138:139] op_sel_hi:[1,0,1]
	v_pk_fma_f32 v[136:137], v[128:129], s[78:79], v[136:137] op_sel_hi:[1,0,1]
	v_lshl_add_u64 v[212:213], v[212:213], 2, s[90:91]
	global_store_dwordx4 v[212:213], v[136:139], off
	s_nop 1
	v_sub_f32_e32 v137, v207, v242
	v_sub_f32_e32 v136, v206, v242
	v_sub_f32_e32 v139, v209, v242
	v_sub_f32_e32 v138, v208, v242
	v_pk_mul_f32 v[136:137], v[242:243], v[136:137] op_sel:[1,0]
	v_pk_mul_f32 v[138:139], v[242:243], v[138:139] op_sel:[1,0]
	v_pk_fma_f32 v[136:137], v[154:155], v[136:137], v[68:69]
	v_pk_fma_f32 v[138:139], v[152:153], v[138:139], v[70:71]
	v_pk_fma_f32 v[132:133], v[132:133], s[78:79], v[136:137] op_sel_hi:[1,0,1]
	v_add_u32_e32 v136, 0x58000, v194
	v_mov_b32_e32 v137, v159
	v_pk_fma_f32 v[134:135], v[134:135], s[78:79], v[138:139] op_sel_hi:[1,0,1]
	v_lshl_add_u64 v[136:137], v[136:137], 2, s[90:91]
	global_store_dwordx4 v[136:137], v[132:135], off
	s_nop 1
	v_sub_f32_e32 v133, v217, v242
	v_sub_f32_e32 v132, v216, v242
	v_sub_f32_e32 v135, v219, v242
	v_sub_f32_e32 v134, v218, v242
	v_pk_mul_f32 v[132:133], v[242:243], v[132:133] op_sel:[1,0]
	v_pk_mul_f32 v[134:135], v[242:243], v[134:135] op_sel:[1,0]
	v_pk_fma_f32 v[132:133], v[150:151], v[132:133], v[64:65]
	v_pk_fma_f32 v[134:135], v[148:149], v[134:135], v[66:67]
	v_pk_fma_f32 v[128:129], v[128:129], s[78:79], v[132:133] op_sel_hi:[1,0,1]
	v_add_u32_e32 v132, 0x58010, v194
	v_mov_b32_e32 v133, v159
	v_pk_fma_f32 v[130:131], v[130:131], s[78:79], v[134:135] op_sel_hi:[1,0,1]
	v_lshl_add_u64 v[132:133], v[132:133], 2, s[90:91]
	global_store_dwordx4 v[132:133], v[128:131], off
	global_load_dwordx4 v[128:131], v[140:141], off offset:512
	v_add_u32_e32 v136, v232, v230
	v_mov_b32_e32 v137, v159
	v_lshl_add_u64 v[136:137], v[136:137], 2, s[88:89]
	s_waitcnt vmcnt(0)
;     template <bool LN, int BJ, int LO, int HI> DI void batch(const f32x4 (&acc)[2][2][4][2], unsigned row0, unsigned col0, const f32x4 (&gv)[2], const f32x4 (&bv)[2]) const {
;         f32x4 r[HI - LO]; float mean[(HI - LO) / 2], rstd[(HI - LO) / 2];
; #pragma unroll
;         for (int i = LO; i < HI; ++i) { const int ai = i >> 3, m = (i >> 1) & 3, n = i & 1; const unsigned row = row0 + ai * HALF + m * 16;
;             if (n == 0) { mean[(i - LO) >> 1] = 0.f; rstd[(i - LO) >> 1] = 1.f;
;                 if (LN) { const float2 st = *(const float2*)(stats + row * 2u); mean[(i - LO) >> 1] = st.x; rstd[(i - LO) >> 1] = st.y; } }
;             r[i - LO] = *(const f32x4*)(src + (row * (unsigned)DM + col0 + BJ * HALF + n * 16)); }
; #pragma unroll
;         for (int i = LO; i < HI; ++i) { const int ai = i >> 3, m = (i >> 1) & 3, n = i & 1; const unsigned row = row0 + ai * HALF + m * 16;
;             *(f32x4*)(Y + (row * (unsigned)DM + col0 + BJ * HALF + n * 16)) = acc[ai][BJ][m][n] + ((r[i - LO] - mean[(i - LO) >> 1]) * rstd[(i - LO) >> 1]) * gv[n] + bv[n]; }
;         __builtin_amdgcn_sched_barrier(0);
;     }
;     template <bool LN, int BJ> DI void load_gb(unsigned col0, f32x4 (&gv)[2], f32x4 (&bv)[2]) const {
; #pragma unroll
;         for (int n = 0; n < 2; ++n) {
;             if (LN) { gv[n] = *(const f32x4*)(gam + col0 + BJ * HALF + n * 16) * ALPHA; bv[n] = *(const f32x4*)(bet + col0 + BJ * HALF + n * 16) * ALPHA; }
;             else { gv[n] = (f32x4){ALPHA, ALPHA, ALPHA, ALPHA}; bv[n] = (f32x4){0.f, 0.f, 0.f, 0.f}; }
;         }
;     }
	v_pk_mul_f32 v[212:213], v[130:131], s[78:79] op_sel_hi:[1,0]
	v_pk_mul_f32 v[214:215], v[128:129], s[78:79] op_sel_hi:[1,0]
	global_load_dwordx4 v[132:135], v[142:143], off offset:512
	global_load_dwordx4 v[128:131], v[140:141], off offset:576
	s_waitcnt vmcnt(0)
	v_pk_mul_f32 v[206:207], v[130:131], s[78:79] op_sel_hi:[1,0]
	v_pk_mul_f32 v[208:209], v[128:129], s[78:79] op_sel_hi:[1,0]
	global_load_dwordx4 v[128:131], v[142:143], off offset:576
	global_load_dwordx2 v[220:221], v[144:145], off
	global_load_dwordx4 v[240:243], v[136:137], off
	v_add_u32_e32 v136, v232, v229
	v_mov_b32_e32 v137, v159
	v_lshl_add_u64 v[136:137], v[136:137], 2, s[88:89]
	global_load_dwordx4 v[244:247], v[136:137], off
	global_load_dwordx2 v[218:219], v[146:147], off
	v_add_u32_e32 v136, v195, v230
	v_mov_b32_e32 v137, v159
	v_lshl_add_u64 v[136:137], v[136:137], 2, s[88:89]
	global_load_dwordx4 v[248:251], v[136:137], off
	v_add_u32_e32 v136, v195, v229
	v_mov_b32_e32 v137, v159
	v_lshl_add_u64 v[136:137], v[136:137], 2, s[88:89]
	global_load_dwordx4 v[152:155], v[136:137], off
	global_load_dwordx2 v[216:217], v[200:201], off
	v_add_u32_e32 v136, v236, v230
	v_mov_b32_e32 v137, v159
	v_lshl_add_u64 v[136:137], v[136:137], 2, s[88:89]
	global_load_dwordx4 v[148:151], v[136:137], off
	v_add_u32_e32 v136, v236, v229
	v_mov_b32_e32 v137, v159
	v_lshl_add_u64 v[136:137], v[136:137], 2, s[88:89]
	global_load_dwordx4 v[144:147], v[136:137], off
	global_load_dwordx2 v[200:201], v[202:203], off
	v_add_u32_e32 v136, v235, v230
	v_mov_b32_e32 v137, v159
	v_lshl_add_u64 v[136:137], v[136:137], 2, s[88:89]
	global_load_dwordx4 v[140:143], v[136:137], off
	v_add_u32_e32 v136, v235, v229
	v_mov_b32_e32 v137, v159
	v_lshl_add_u64 v[136:137], v[136:137], 2, s[88:89]
	global_load_dwordx4 v[136:139], v[136:137], off
	v_add_u32_e32 v202, 0x80, v194
	v_mov_b32_e32 v203, v159
	v_lshl_add_u64 v[202:203], v[202:203], 2, s[90:91]
	s_waitcnt vmcnt(0)
	v_sub_f32_e32 v241, v241, v220
	v_sub_f32_e32 v240, v240, v220
	v_sub_f32_e32 v243, v243, v220
	v_sub_f32_e32 v242, v242, v220
	v_pk_mul_f32 v[242:243], v[220:221], v[242:243] op_sel:[1,0]
	v_pk_mul_f32 v[240:241], v[220:221], v[240:241] op_sel:[1,0]
	v_pk_fma_f32 v[242:243], v[212:213], v[242:243], v[62:63]
	v_pk_fma_f32 v[240:241], v[214:215], v[240:241], v[60:61]
	v_pk_fma_f32 v[242:243], v[134:135], s[78:79], v[242:243] op_sel_hi:[1,0,1]
	v_pk_fma_f32 v[240:241], v[132:133], s[78:79], v[240:241] op_sel_hi:[1,0,1]
	global_store_dwordx4 v[202:203], v[240:243], off
	v_sub_f32_e32 v203, v245, v220
	v_sub_f32_e32 v202, v244, v220
	v_sub_f32_e32 v241, v247, v220
	v_sub_f32_e32 v240, v246, v220
	v_pk_mul_f32 v[202:203], v[220:221], v[202:203] op_sel:[1,0]
	v_pk_mul_f32 v[240:241], v[220:221], v[240:241] op_sel:[1,0]
	v_pk_fma_f32 v[202:203], v[208:209], v[202:203], v[56:57]
	v_pk_fma_f32 v[220:221], v[206:207], v[240:241], v[58:59]
	v_pk_fma_f32 v[240:241], v[128:129], s[78:79], v[202:203] op_sel_hi:[1,0,1]
	v_add_u32_e32 v202, 0x90, v194
	v_mov_b32_e32 v203, v159
	v_pk_fma_f32 v[242:243], v[130:131], s[78:79], v[220:221] op_sel_hi:[1,0,1]
	v_lshl_add_u64 v[202:203], v[202:203], 2, s[90:91]
	global_store_dwordx4 v[202:203], v[240:243], off
	v_sub_f32_e32 v203, v249, v218
	v_sub_f32_e32 v202, v248, v218
	v_sub_f32_e32 v221, v251, v218
	v_sub_f32_e32 v220, v250, v218
	v_pk_mul_f32 v[202:203], v[218:219], v[202:203] op_sel:[1,0]
	v_pk_mul_f32 v[220:221], v[218:219], v[220:221] op_sel:[1,0]
	v_pk_fma_f32 v[202:203], v[214:215], v[202:203], v[52:53]
	v_pk_fma_f32 v[220:221], v[212:213], v[220:221], v[54:55]
	v_pk_fma_f32 v[240:241], v[132:133], s[78:79], v[202:203] op_sel_hi:[1,0,1]
	v_add_u32_e32 v202, 0x8080, v194
	v_mov_b32_e32 v203, v159
	v_sub_f32_e32 v153, v153, v218
	v_sub_f32_e32 v152, v152, v218
	v_sub_f32_e32 v155, v155, v218
	v_sub_f32_e32 v154, v154, v218
	v_pk_fma_f32 v[242:243], v[134:135], s[78:79], v[220:221] op_sel_hi:[1,0,1]
	v_lshl_add_u64 v[202:203], v[202:203], 2, s[90:91]
	v_pk_mul_f32 v[154:155], v[218:219], v[154:155] op_sel:[1,0]
	v_pk_mul_f32 v[152:153], v[218:219], v[152:153] op_sel:[1,0]
	global_store_dwordx4 v[202:203], v[240:243], off
	v_pk_fma_f32 v[152:153], v[208:209], v[152:153], v[48:49]
	v_pk_fma_f32 v[154:155], v[206:207], v[154:155], v[50:51]
	v_add_u32_e32 v202, 0x8090, v194
	v_mov_b32_e32 v203, v159
	v_sub_f32_e32 v149, v149, v216
	v_sub_f32_e32 v148, v148, v216
	v_sub_f32_e32 v151, v151, v216
	v_sub_f32_e32 v150, v150, v216
	v_pk_fma_f32 v[154:155], v[130:131], s[78:79], v[154:155] op_sel_hi:[1,0,1]
	v_pk_fma_f32 v[152:153], v[128:129], s[78:79], v[152:153] op_sel_hi:[1,0,1]
	v_lshl_add_u64 v[202:203], v[202:203], 2, s[90:91]
	v_pk_mul_f32 v[150:151], v[216:217], v[150:151] op_sel:[1,0]
	v_pk_mul_f32 v[148:149], v[216:217], v[148:149] op_sel:[1,0]
	global_store_dwordx4 v[202:203], v[152:155], off
	v_pk_fma_f32 v[148:149], v[214:215], v[148:149], v[44:45]
	v_pk_fma_f32 v[150:151], v[212:213], v[150:151], v[46:47]
	v_add_u32_e32 v152, 0x10080, v194
	v_mov_b32_e32 v153, v159
	v_sub_f32_e32 v145, v145, v216
	v_sub_f32_e32 v144, v144, v216
	v_sub_f32_e32 v147, v147, v216
	v_sub_f32_e32 v146, v146, v216
	v_pk_fma_f32 v[150:151], v[134:135], s[78:79], v[150:151] op_sel_hi:[1,0,1]
	v_pk_fma_f32 v[148:149], v[132:133], s[78:79], v[148:149] op_sel_hi:[1,0,1]
	v_lshl_add_u64 v[152:153], v[152:153], 2, s[90:91]
	v_pk_mul_f32 v[146:147], v[216:217], v[146:147] op_sel:[1,0]
	v_pk_mul_f32 v[144:145], v[216:217], v[144:145] op_sel:[1,0]
	global_store_dwordx4 v[152:153], v[148:151], off
	v_pk_fma_f32 v[144:145], v[208:209], v[144:145], v[40:41]
	v_pk_fma_f32 v[146:147], v[206:207], v[146:147], v[42:43]
;     template <bool LN, int BJ, int LO, int HI> DI void batch(const f32x4 (&acc)[2][2][4][2], unsigned row0, unsigned col0, const f32x4 (&gv)[2], const f32x4 (&bv)[2]) const {
;         f32x4 r[HI - LO]; float mean[(HI - LO) / 2], rstd[(HI - LO) / 2];
; #pragma unroll
;         for (int i = LO; i < HI; ++i) { const int ai = i >> 3, m = (i >> 1) & 3, n = i & 1; const unsigned row = row0 + ai * HALF + m * 16;
;             if (n == 0) { mean[(i - LO) >> 1] = 0.f; rstd[(i - LO) >> 1] = 1.f;
;                 if (LN) { const float2 st = *(const float2*)(stats + row * 2u); mean[(i - LO) >> 1] = st.x; rstd[(i - LO) >> 1] = st.y; } }
;             r[i - LO] = *(const f32x4*)(src + (row * (unsigned)DM + col0 + BJ * HALF + n * 16)); }
; #pragma unroll
;         for (int i = LO; i < HI; ++i) { const int ai = i >> 3, m = (i >> 1) & 3, n = i & 1; const unsigned row = row0 + ai * HALF + m * 16;
;             *(f32x4*)(Y + (row * (unsigned)DM + col0 + BJ * HALF + n * 16)) = acc[ai][BJ][m][n] + ((r[i - LO] - mean[(i - LO) >> 1]) * rstd[(i - LO) >> 1]) * gv[n] + bv[n]; }
	v_add_u32_e32 v148, 0x10090, v194
	v_mov_b32_e32 v149, v159
	v_sub_f32_e32 v141, v141, v200
	v_sub_f32_e32 v140, v140, v200
	v_sub_f32_e32 v143, v143, v200
	v_sub_f32_e32 v142, v142, v200
	v_pk_fma_f32 v[146:147], v[130:131], s[78:79], v[146:147] op_sel_hi:[1,0,1]
	v_pk_fma_f32 v[144:145], v[128:129], s[78:79], v[144:145] op_sel_hi:[1,0,1]
	v_lshl_add_u64 v[148:149], v[148:149], 2, s[90:91]
	v_pk_mul_f32 v[142:143], v[200:201], v[142:143] op_sel:[1,0]
	v_pk_mul_f32 v[140:141], v[200:201], v[140:141] op_sel:[1,0]
	global_store_dwordx4 v[148:149], v[144:147], off
	v_pk_fma_f32 v[140:141], v[214:215], v[140:141], v[36:37]
	v_pk_fma_f32 v[142:143], v[212:213], v[142:143], v[38:39]
	v_add_u32_e32 v144, 0x18080, v194
	v_mov_b32_e32 v145, v159
	v_sub_f32_e32 v137, v137, v200
	v_sub_f32_e32 v136, v136, v200
	v_sub_f32_e32 v139, v139, v200
	v_sub_f32_e32 v138, v138, v200
	v_pk_fma_f32 v[142:143], v[134:135], s[78:79], v[142:143] op_sel_hi:[1,0,1]
	v_pk_fma_f32 v[140:141], v[132:133], s[78:79], v[140:141] op_sel_hi:[1,0,1]
	v_lshl_add_u64 v[144:145], v[144:145], 2, s[90:91]
	v_pk_mul_f32 v[138:139], v[200:201], v[138:139] op_sel:[1,0]
	v_pk_mul_f32 v[136:137], v[200:201], v[136:137] op_sel:[1,0]
	global_store_dwordx4 v[144:145], v[140:143], off
	v_pk_fma_f32 v[136:137], v[208:209], v[136:137], v[32:33]
	v_pk_fma_f32 v[138:139], v[206:207], v[138:139], v[34:35]
	v_add_u32_e32 v140, 0x18090, v194
	v_mov_b32_e32 v141, v159
	v_pk_fma_f32 v[138:139], v[130:131], s[78:79], v[138:139] op_sel_hi:[1,0,1]
	v_pk_fma_f32 v[136:137], v[128:129], s[78:79], v[136:137] op_sel_hi:[1,0,1]
	v_lshl_add_u64 v[140:141], v[140:141], 2, s[90:91]
	global_store_dwordx4 v[140:141], v[136:139], off
	s_nop 1
	v_add_u32_e32 v136, v233, v230
	v_mov_b32_e32 v137, v159
	v_lshl_add_u64 v[136:137], v[136:137], 2, s[88:89]
	global_load_dwordx2 v[220:221], v[196:197], off
	global_load_dwordx4 v[216:219], v[136:137], off
	v_add_u32_e32 v136, v233, v229
	v_mov_b32_e32 v137, v159
	v_lshl_add_u64 v[136:137], v[136:137], 2, s[88:89]
	global_load_dwordx4 v[240:243], v[136:137], off
	global_load_dwordx2 v[200:201], v[198:199], off
	v_add_u32_e32 v136, v234, v230
	v_mov_b32_e32 v137, v159
	v_lshl_add_u64 v[136:137], v[136:137], 2, s[88:89]
	global_load_dwordx4 v[244:247], v[136:137], off
	v_add_u32_e32 v136, v234, v229
	v_mov_b32_e32 v137, v159
	v_lshl_add_u64 v[136:137], v[136:137], 2, s[88:89]
	global_load_dwordx4 v[152:155], v[136:137], off
	global_load_dwordx2 v[198:199], v[204:205], off
	v_add_u32_e32 v136, v237, v230
	v_mov_b32_e32 v137, v159
	v_lshl_add_u64 v[136:137], v[136:137], 2, s[88:89]
	global_load_dwordx4 v[148:151], v[136:137], off
	v_add_u32_e32 v136, v237, v229
	v_mov_b32_e32 v137, v159
	v_lshl_add_u64 v[136:137], v[136:137], 2, s[88:89]
	global_load_dwordx4 v[144:147], v[136:137], off
	global_load_dwordx2 v[196:197], v[210:211], off
	v_add_u32_e32 v136, v238, v230
	v_mov_b32_e32 v137, v159
	v_lshl_add_u64 v[136:137], v[136:137], 2, s[88:89]
	global_load_dwordx4 v[140:143], v[136:137], off
	v_add_u32_e32 v136, v238, v229
	v_mov_b32_e32 v137, v159
	v_lshl_add_u64 v[136:137], v[136:137], 2, s[88:89]
	global_load_dwordx4 v[136:139], v[136:137], off
	v_add_u32_e32 v210, 0x40080, v194
	v_mov_b32_e32 v211, v159
	v_lshl_add_u64 v[210:211], v[210:211], 2, s[90:91]
	s_waitcnt vmcnt(0)
;     template <bool LN, int BJ, int LO, int HI> DI void batch(const f32x4 (&acc)[2][2][4][2], unsigned row0, unsigned col0, const f32x4 (&gv)[2], const f32x4 (&bv)[2]) const {
;     ...
;         for (int i = LO; i < HI; ++i) { const int ai = i >> 3, m = (i >> 1) & 3, n = i & 1; const unsigned row = row0 + ai * HALF + m * 16;
;             if (n == 0) { mean[(i - LO) >> 1] = 0.f; rstd[(i - LO) >> 1] = 1.f;
;                 if (LN) { const float2 st = *(const float2*)(stats + row * 2u); mean[(i - LO) >> 1] = st.x; rstd[(i - LO) >> 1] = st.y; } }
;             r[i - LO] = *(const f32x4*)(src + (row * (unsigned)DM + col0 + BJ * HALF + n * 16)); }
; #pragma unroll
;         for (int i = LO; i < HI; ++i) { const int ai = i >> 3, m = (i >> 1) & 3, n = i & 1; const unsigned row = row0 + ai * HALF + m * 16;
;             *(f32x4*)(Y + (row * (unsigned)DM + col0 + BJ * HALF + n * 16)) = acc[ai][BJ][m][n] + ((r[i - LO] - mean[(i - LO) >> 1]) * rstd[(i - LO) >> 1]) * gv[n] + bv[n]; }
;     template <bool LN> DI void run(const f32x4 (&acc)[2][2][4][2], const Unit& u, int wr, int wc, int fr, int fq) const {
;     ...
;         batch<LN, 1, 8, 16>(acc, row0, col0, gv, bv);
	v_sub_f32_e32 v203, v217, v220
	v_sub_f32_e32 v202, v216, v220
	v_sub_f32_e32 v205, v219, v220
	v_sub_f32_e32 v204, v218, v220
	v_pk_mul_f32 v[204:205], v[220:221], v[204:205] op_sel:[1,0]
	v_pk_mul_f32 v[202:203], v[220:221], v[202:203] op_sel:[1,0]
	v_pk_fma_f32 v[204:205], v[212:213], v[204:205], v[30:31]
	v_pk_fma_f32 v[202:203], v[214:215], v[202:203], v[28:29]
	v_pk_fma_f32 v[204:205], v[134:135], s[78:79], v[204:205] op_sel_hi:[1,0,1]
	v_pk_fma_f32 v[202:203], v[132:133], s[78:79], v[202:203] op_sel_hi:[1,0,1]
	global_store_dwordx4 v[210:211], v[202:205], off
	v_add_u32_e32 v210, 0x40090, v194
	v_mov_b32_e32 v211, v159
	v_sub_f32_e32 v203, v241, v220
	v_sub_f32_e32 v202, v240, v220
	v_sub_f32_e32 v205, v243, v220
	v_sub_f32_e32 v204, v242, v220
	v_pk_mul_f32 v[204:205], v[220:221], v[204:205] op_sel:[1,0]
	v_pk_mul_f32 v[202:203], v[220:221], v[202:203] op_sel:[1,0]
	v_pk_fma_f32 v[204:205], v[206:207], v[204:205], v[26:27]
	v_pk_fma_f32 v[202:203], v[208:209], v[202:203], v[24:25]
	v_pk_fma_f32 v[204:205], v[130:131], s[78:79], v[204:205] op_sel_hi:[1,0,1]
	v_pk_fma_f32 v[202:203], v[128:129], s[78:79], v[202:203] op_sel_hi:[1,0,1]
	v_lshl_add_u64 v[210:211], v[210:211], 2, s[90:91]
	global_store_dwordx4 v[210:211], v[202:205], off
	v_sub_f32_e32 v149, v149, v198
	v_sub_f32_e32 v148, v148, v198
	v_sub_f32_e32 v203, v245, v200
	v_sub_f32_e32 v202, v244, v200
	v_sub_f32_e32 v141, v141, v196
	v_sub_f32_e32 v140, v140, v196
	v_sub_f32_e32 v205, v247, v200
	v_sub_f32_e32 v204, v246, v200
	v_pk_mul_f32 v[202:203], v[200:201], v[202:203] op_sel:[1,0]
	v_sub_f32_e32 v151, v151, v198
	v_sub_f32_e32 v150, v150, v198
	v_pk_mul_f32 v[148:149], v[198:199], v[148:149] op_sel:[1,0]
	v_sub_f32_e32 v143, v143, v196
	v_sub_f32_e32 v142, v142, v196
	v_pk_mul_f32 v[140:141], v[196:197], v[140:141] op_sel:[1,0]
	v_pk_mul_f32 v[204:205], v[200:201], v[204:205] op_sel:[1,0]
	v_pk_fma_f32 v[202:203], v[214:215], v[202:203], v[20:21]
	v_sub_f32_e32 v153, v153, v200
	v_sub_f32_e32 v152, v152, v200
	v_sub_f32_e32 v155, v155, v200
	v_sub_f32_e32 v154, v154, v200
	v_pk_mul_f32 v[150:151], v[198:199], v[150:151] op_sel:[1,0]
	v_pk_fma_f32 v[148:149], v[214:215], v[148:149], v[12:13]
	v_pk_mul_f32 v[142:143], v[196:197], v[142:143] op_sel:[1,0]
	v_pk_fma_f32 v[140:141], v[214:215], v[140:141], v[4:5]
	v_pk_fma_f32 v[204:205], v[212:213], v[204:205], v[22:23]
	v_pk_fma_f32 v[202:203], v[132:133], s[78:79], v[202:203] op_sel_hi:[1,0,1]
	v_pk_mul_f32 v[154:155], v[200:201], v[154:155] op_sel:[1,0]
	v_pk_mul_f32 v[152:153], v[200:201], v[152:153] op_sel:[1,0]
	v_pk_fma_f32 v[150:151], v[212:213], v[150:151], v[14:15]
	v_pk_fma_f32 v[148:149], v[132:133], s[78:79], v[148:149] op_sel_hi:[1,0,1]
	v_pk_fma_f32 v[142:143], v[212:213], v[142:143], v[6:7]
	v_pk_fma_f32 v[132:133], v[132:133], s[78:79], v[140:141] op_sel_hi:[1,0,1]
	v_add_u32_e32 v140, 0x58080, v194
	v_mov_b32_e32 v141, v159
	v_pk_fma_f32 v[204:205], v[134:135], s[78:79], v[204:205] op_sel_hi:[1,0,1]
	v_pk_fma_f32 v[152:153], v[208:209], v[152:153], v[16:17]
	v_pk_fma_f32 v[154:155], v[206:207], v[154:155], v[18:19]
	v_add_u32_e32 v200, 0x48090, v194
	v_mov_b32_e32 v201, v159
	v_pk_fma_f32 v[150:151], v[134:135], s[78:79], v[150:151] op_sel_hi:[1,0,1]
	v_pk_fma_f32 v[134:135], v[134:135], s[78:79], v[142:143] op_sel_hi:[1,0,1]
	v_lshl_add_u64 v[140:141], v[140:141], 2, s[90:91]
	v_pk_fma_f32 v[154:155], v[130:131], s[78:79], v[154:155] op_sel_hi:[1,0,1]
	v_pk_fma_f32 v[152:153], v[128:129], s[78:79], v[152:153] op_sel_hi:[1,0,1]
	v_lshl_add_u64 v[200:201], v[200:201], 2, s[90:91]
	v_sub_f32_e32 v145, v145, v198
	v_sub_f32_e32 v144, v144, v198
	global_store_dwordx4 v[140:141], v[132:135], off
	global_store_dwordx4 v[200:201], v[152:155], off
	v_sub_f32_e32 v147, v147, v198
	v_sub_f32_e32 v133, v137, v196
	v_sub_f32_e32 v132, v136, v196
	v_add_u32_e32 v152, 0x50080, v194
	v_mov_b32_e32 v153, v159
	v_sub_f32_e32 v146, v146, v198
	v_pk_mul_f32 v[144:145], v[198:199], v[144:145] op_sel:[1,0]
	v_sub_f32_e32 v135, v139, v196
	v_sub_f32_e32 v134, v138, v196
	v_pk_mul_f32 v[132:133], v[196:197], v[132:133] op_sel:[1,0]
	v_lshl_add_u64 v[152:153], v[152:153], 2, s[90:91]
	v_pk_mul_f32 v[146:147], v[198:199], v[146:147] op_sel:[1,0]
	v_pk_fma_f32 v[144:145], v[208:209], v[144:145], v[8:9]
	v_pk_mul_f32 v[134:135], v[196:197], v[134:135] op_sel:[1,0]
	v_pk_fma_f32 v[132:133], v[208:209], v[132:133], v[0:1]
	v_add_u32_e32 v210, 0x48080, v194
	v_mov_b32_e32 v211, v159
	global_store_dwordx4 v[152:153], v[148:151], off
	v_pk_fma_f32 v[146:147], v[206:207], v[146:147], v[10:11]
	v_pk_fma_f32 v[144:145], v[128:129], s[78:79], v[144:145] op_sel_hi:[1,0,1]
	v_add_u32_e32 v148, 0x50090, v194
	v_mov_b32_e32 v149, v159
	v_pk_fma_f32 v[134:135], v[206:207], v[134:135], v[2:3]
	v_pk_fma_f32 v[128:129], v[128:129], s[78:79], v[132:133] op_sel_hi:[1,0,1]
	v_add_u32_e32 v132, 0x58090, v194
	v_mov_b32_e32 v133, v159
	v_lshl_add_u64 v[210:211], v[210:211], 2, s[90:91]
	v_pk_fma_f32 v[146:147], v[130:131], s[78:79], v[146:147] op_sel_hi:[1,0,1]
	v_lshl_add_u64 v[148:149], v[148:149], 2, s[90:91]
	v_pk_fma_f32 v[130:131], v[130:131], s[78:79], v[134:135] op_sel_hi:[1,0,1]
	v_lshl_add_u64 v[132:133], v[132:133], 2, s[90:91]
	global_store_dwordx4 v[210:211], v[202:205], off
	global_store_dwordx4 v[148:149], v[144:147], off
	global_store_dwordx4 v[132:133], v[128:131], off
	s_mov_b64 s[24:25], 0
	s_branch .LBB0_324
